# v32 with every per-cluster s_setprio flip deleted from the K-loops and one static s_setprio 1 for waves 4-7 per tile (strategy lever 4)
# baseline (speedup 1.0000x reference)
;     __host__ __device__ bool next(int i, Unit& u) const { const bool ok = StaticOrder::next(i, u); u.lm = 0; u.ln = 0; return ok; }
; #define PG8_STAGE(bufoff, gbase, voff) do { _Pragma("unroll") for (int _i = 0; _i < 2; ++_i) \
;         __builtin_amdgcn_global_load_lds((const unsigned*)((const char*)(gbase) + (voff)[_i]), (PG8_LAS unsigned*)(lds + (bufoff) + ldsw + _i * 8192), 16, 0, 0); } while (0)
; #define PG8_BAR __builtin_amdgcn_s_barrier()
; template <class Epi, class Sched, bool ALIGN_EPI = false, bool SP2 = false>
; __device__ __forceinline__ void gemm_phase(PG8_LAS unsigned char* lds, const Gemm g, const Sched& S, const Epi& E, const int wave_id) {
;     ...
;         const bool has_next = S.next(ui + 1, nxt);
;         const char* nA = has_next ? (const char*)g.A + (size_t)nxt.lm * tstep : cA; const char* nB = has_next ? (const char*)g.Bt + (size_t)nxt.ln * tstep : cB;
; #pragma unroll 1
;         for (int t = 0; t < nt; t += 2) {
;             const bool last = (t == nt - 2);
;             const char* a1 = cA + (size_t)(t + 1) * kstep;
;             const char* a2 = last ? nA : cA + (size_t)(t + 2) * kstep; const char* b2 = last ? nB : cB + (size_t)(t + 2) * kstep;
;             const char* a3 = a2 + kstep; const char* b3 = b2 + kstep;
;             if (last && has_next) S.a_ready(nxt);
;             if constexpr (SP2) {
;             PG8_LDB(B0, 0, 0); PG8_LDB(B1, 0, 1); PG8_SCHED; PG8_LDA(At, 0, 0); PG8_STAGE(PG8_SA(1, 1), a1 + hstep, voffA);
;             PG8_WAIT_V(8); PG8_WAIT_L(0); PG8_BAR; PG8_MMA(0, 0, At, B0); PG8_MMA(0, 1, At, B1); PG8_BAR; PG8_SCHED;
;             PG8_LDA(At, 0, 1); PG8_STAGE(PG8_SB(0, 0), b2, voffB); PG8_STAGE(PG8_SB(0, 1), b2 + hstep, voffB); PG8_STAGE(PG8_SA(0, 0), a2, voffA);
;             PG8_WAIT_V(8); PG8_WAIT_L(0); PG8_BAR; PG8_MMA(1, 0, At, B0); PG8_MMA(1, 1, At, B1); PG8_BAR; PG8_SCHED;
;             PG8_LDB(B0, 1, 0); PG8_LDB(B1, 1, 1); PG8_SCHED; PG8_LDA(At, 1, 0); PG8_STAGE(PG8_SA(0, 1), a2 + hstep, voffA);
;             PG8_WAIT_V(8); PG8_WAIT_L(0); PG8_BAR; PG8_MMA(0, 0, At, B0); PG8_MMA(0, 1, At, B1); PG8_BAR; PG8_SCHED;
;             PG8_LDA(At, 1, 1); PG8_STAGE(PG8_SB(1, 0), b3, voffB); PG8_STAGE(PG8_SB(1, 1), b3 + hstep, voffB); PG8_STAGE(PG8_SA(1, 0), a3, voffA);
;             PG8_WAIT_V(8); PG8_WAIT_L(0); PG8_BAR; PG8_MMA(1, 0, At, B0); PG8_MMA(1, 1, At, B1); PG8_BAR; PG8_SCHED;
.LBB0_173:
	s_ashr_i32 s15, s14, 31
	s_lshl_b64 s[16:17], s[14:15], 20
	s_add_u32 s16, s49, s16
	s_addc_u32 s17, s52, s17
	s_and_b64 s[18:19], s[38:39], exec
	s_cselect_b32 s15, s17, s21
	s_cselect_b32 s41, s16, s20
	s_ashr_i32 s13, s12, 31
	s_lshl_b64 s[18:19], s[12:13], 20
	s_add_u32 s18, s47, s18
	s_addc_u32 s19, s48, s19
	s_and_b64 s[44:45], s[38:39], exec
	s_cselect_b32 s13, s19, s43
	s_cselect_b32 s72, s18, s42
	s_add_u32 s20, s20, 0x80080
	s_addc_u32 s21, s21, 0
	s_add_u32 s73, s42, 0x100
	s_addc_u32 s74, s43, 0
	s_mov_b32 s75, -2
	v_add_u32_e32 v230, 0x10000, v171
	s_cmp_eq_u64 s[10:11], 0
	s_cbranch_scc0 .Lprio_g1
	s_setprio 1
.Lprio_g1:
	s_add_u32 s42, s20, 0xfff80080
	s_addc_u32 s43, s21, -1
	s_add_i32 s76, 0, 0x10000
	s_cmp_eq_u32 s75, 28
	s_cselect_b32 s45, s15, s43
	s_cselect_b32 s44, s41, s42
	s_cselect_b32 s43, s13, s74
	s_cselect_b32 s42, s72, s73
	s_add_i32 s79, 0, 0x14000
	s_add_i32 m0, s56, 0xc000
	s_nop 0
	global_load_lds_dwordx4 v138, s[20:21]
	ds_read_b128 v[142:145], v230
	ds_read_b128 v[146:149], v230 offset:1024
	ds_read_b128 v[150:153], v230 offset:2048
	ds_read_b128 v[154:157], v230 offset:3072
	ds_read_b128 v[158:161], v230 offset:16384
	ds_read_b128 v[162:165], v230 offset:17408
	ds_read_b128 v[166:169], v230 offset:18432
	ds_read_b128 v[178:181], v230 offset:19456
	s_add_i32 m0, s56, 0xe000
	s_nop 0
	global_load_lds_dwordx4 v140, s[20:21]
	ds_read_b128 v[182:185], v175
	ds_read_b128 v[186:189], v175 offset:1024
	ds_read_b128 v[190:193], v175 offset:2048
	ds_read_b128 v[206:209], v175 offset:3072
	ds_read_b128 v[210:213], v175 offset:4096
	ds_read_b128 v[214:217], v175 offset:5120
	ds_read_b128 v[226:229], v175 offset:6144
	ds_read_b128 v[234:237], v175 offset:7168
	s_waitcnt lgkmcnt(0)
	v_mfma_f32_16x16x32_bf16 v[126:129], v[142:145], v[182:185], 0
	v_mfma_f32_16x16x32_bf16 v[118:121], v[150:153], v[182:185], 0
	v_mfma_f32_16x16x32_bf16 v[110:113], v[142:145], v[190:193], 0
	v_mfma_f32_16x16x32_bf16 v[102:105], v[150:153], v[190:193], 0
	s_waitcnt vmcnt(8)
	s_barrier
	v_mfma_f32_16x16x32_bf16 v[94:97], v[142:145], v[210:213], 0
	v_mfma_f32_16x16x32_bf16 v[86:89], v[150:153], v[210:213], 0
	v_mfma_f32_16x16x32_bf16 v[78:81], v[142:145], v[226:229], 0
	v_mfma_f32_16x16x32_bf16 v[70:73], v[150:153], v[226:229], 0
	v_mfma_f32_16x16x32_bf16 v[126:129], v[146:149], v[186:189], v[126:129]
	v_mfma_f32_16x16x32_bf16 v[118:121], v[154:157], v[186:189], v[118:121]
	v_mfma_f32_16x16x32_bf16 v[110:113], v[146:149], v[206:209], v[110:113]
	v_mfma_f32_16x16x32_bf16 v[102:105], v[154:157], v[206:209], v[102:105]
	v_mfma_f32_16x16x32_bf16 v[94:97], v[146:149], v[214:217], v[94:97]
	v_mfma_f32_16x16x32_bf16 v[86:89], v[154:157], v[214:217], v[86:89]
	v_mfma_f32_16x16x32_bf16 v[78:81], v[146:149], v[234:237], v[78:81]
	v_mfma_f32_16x16x32_bf16 v[70:73], v[154:157], v[234:237], v[70:73]
	v_mfma_f32_16x16x32_bf16 v[122:125], v[158:161], v[182:185], 0
	v_mfma_f32_16x16x32_bf16 v[114:117], v[166:169], v[182:185], 0
	v_mfma_f32_16x16x32_bf16 v[106:109], v[158:161], v[190:193], 0
	v_mfma_f32_16x16x32_bf16 v[98:101], v[166:169], v[190:193], 0
	v_mfma_f32_16x16x32_bf16 v[90:93], v[158:161], v[210:213], 0
	v_mfma_f32_16x16x32_bf16 v[82:85], v[166:169], v[210:213], 0
	v_mfma_f32_16x16x32_bf16 v[74:77], v[158:161], v[226:229], 0
	v_mfma_f32_16x16x32_bf16 v[66:69], v[166:169], v[226:229], 0
	v_mfma_f32_16x16x32_bf16 v[122:125], v[162:165], v[186:189], v[122:125]
	v_mfma_f32_16x16x32_bf16 v[114:117], v[178:181], v[186:189], v[114:117]
	v_mfma_f32_16x16x32_bf16 v[106:109], v[162:165], v[206:209], v[106:109]
	v_mfma_f32_16x16x32_bf16 v[98:101], v[178:181], v[206:209], v[98:101]
	v_mfma_f32_16x16x32_bf16 v[90:93], v[162:165], v[214:217], v[90:93]
	v_mfma_f32_16x16x32_bf16 v[82:85], v[178:181], v[214:217], v[82:85]
	v_mfma_f32_16x16x32_bf16 v[74:77], v[162:165], v[234:237], v[74:77]
	v_mfma_f32_16x16x32_bf16 v[66:69], v[178:181], v[234:237], v[66:69]
	s_barrier
	s_add_i32 s76, s76, s53
	s_mov_b32 m0, s76
	s_nop 0
	global_load_lds_dwordx4 v132, s[42:43]
	ds_read_b128 v[182:185], v175 offset:16384
	ds_read_b128 v[186:189], v175 offset:17408
	s_add_i32 m0, s76, 0x2000
	s_add_u32 s76, s42, 0x80000
	s_addc_u32 s77, s43, 0
	s_add_i32 s79, s79, s53
	global_load_lds_dwordx4 v136, s[42:43]
	ds_read_b128 v[190:193], v175 offset:18432
	ds_read_b128 v[206:209], v175 offset:19456
	s_mov_b32 m0, s79
	s_nop 0
	global_load_lds_dwordx4 v132, s[76:77]
	ds_read_b128 v[210:213], v175 offset:20480
	ds_read_b128 v[214:217], v175 offset:21504
	s_add_i32 m0, s79, 0x2000
	s_nop 0
	global_load_lds_dwordx4 v136, s[76:77]
	ds_read_b128 v[226:229], v175 offset:22528
	ds_read_b128 v[234:237], v175 offset:23552
	s_mov_b32 m0, s56
	s_nop 0
	global_load_lds_dwordx4 v130, s[44:45]
	s_mov_b32 m0, s57
	s_nop 0
	global_load_lds_dwordx4 v134, s[44:45]
	s_waitcnt lgkmcnt(0)
	v_mfma_f32_16x16x32_bf16 v[62:65], v[142:145], v[182:185], 0
	v_mfma_f32_16x16x32_bf16 v[54:57], v[150:153], v[182:185], 0
	v_mfma_f32_16x16x32_bf16 v[46:49], v[142:145], v[190:193], 0
	v_mfma_f32_16x16x32_bf16 v[38:41], v[150:153], v[190:193], 0
	s_waitcnt vmcnt(8)
	s_barrier
; #define PG8_STAGE(bufoff, gbase, voff) do { _Pragma("unroll") for (int _i = 0; _i < 2; ++_i) \
;         __builtin_amdgcn_global_load_lds((const unsigned*)((const char*)(gbase) + (voff)[_i]), (PG8_LAS unsigned*)(lds + (bufoff) + ldsw + _i * 8192), 16, 0, 0); } while (0)
; #define PG8_LDA(dst, b, h) do { _Pragma("unroll") for (int m = 0; m < 4; ++m) _Pragma("unroll") for (int k = 0; k < 2; ++k) dst[m][k] = *(const PG8_LAS bf16x8*)(lds + PG8_SA(b, h) + aoff + m * 2048 + k * 1024); } while (0)
; #define PG8_LDB(dst, b, h) do { _Pragma("unroll") for (int n = 0; n < 2; ++n) _Pragma("unroll") for (int k = 0; k < 2; ++k) dst[n][k] = *(const PG8_LAS bf16x8*)(lds + PG8_SB(b, h) + boff + n * 2048 + k * 1024); } while (0)
; #define PG8_MMA(ai, bj, At, Bt) do { __builtin_amdgcn_s_setprio(1); _Pragma("unroll") for (int m = 0; m < 4; ++m) _Pragma("unroll") for (int n = 0; n < 2; ++n) _Pragma("unroll") for (int k = 0; k < 2; ++k) \
;         acc[ai][bj][m][n] = __builtin_amdgcn_mfma_f32_16x16x32_bf16(Bt[n][k], At[m][k], acc[ai][bj][m][n], 0, 0, 0); __builtin_amdgcn_s_setprio(0); } while (0)
; #define PG8_BAR __builtin_amdgcn_s_barrier()
; template <class Epi, class Sched, bool ALIGN_EPI = false, bool SP2 = false>
; __device__ __forceinline__ void gemm_phase(PG8_LAS unsigned char* lds, const Gemm g, const Sched& S, const Epi& E, const int wave_id) {
;     ...
;             PG8_LDB(B0, 0, 0); PG8_LDB(B1, 0, 1); PG8_SCHED; PG8_LDA(At, 0, 0); PG8_STAGE(PG8_SA(1, 1), a1 + hstep, voffA);
;             PG8_WAIT_V(8); PG8_WAIT_L(0); PG8_BAR; PG8_MMA(0, 0, At, B0); PG8_MMA(0, 1, At, B1); PG8_BAR; PG8_SCHED;
;             PG8_LDA(At, 0, 1); PG8_STAGE(PG8_SB(0, 0), b2, voffB); PG8_STAGE(PG8_SB(0, 1), b2 + hstep, voffB); PG8_STAGE(PG8_SA(0, 0), a2, voffA);
;             PG8_WAIT_V(8); PG8_WAIT_L(0); PG8_BAR; PG8_MMA(1, 0, At, B0); PG8_MMA(1, 1, At, B1); PG8_BAR; PG8_SCHED;
;             PG8_LDB(B0, 1, 0); PG8_LDB(B1, 1, 1); PG8_SCHED; PG8_LDA(At, 1, 0); PG8_STAGE(PG8_SA(0, 1), a2 + hstep, voffA);
;             PG8_WAIT_V(8); PG8_WAIT_L(0); PG8_BAR; PG8_MMA(0, 0, At, B0); PG8_MMA(0, 1, At, B1); PG8_BAR; PG8_SCHED;
;             PG8_LDA(At, 1, 1); PG8_STAGE(PG8_SB(1, 0), b3, voffB); PG8_STAGE(PG8_SB(1, 1), b3 + hstep, voffB); PG8_STAGE(PG8_SA(1, 0), a3, voffA);
;             PG8_WAIT_V(8); PG8_WAIT_L(0); PG8_BAR; PG8_MMA(1, 0, At, B0); PG8_MMA(1, 1, At, B1); PG8_BAR; PG8_SCHED;
	v_mfma_f32_16x16x32_bf16 v[30:33], v[142:145], v[210:213], 0
	v_mfma_f32_16x16x32_bf16 v[22:25], v[150:153], v[210:213], 0
	v_mfma_f32_16x16x32_bf16 v[14:17], v[142:145], v[226:229], 0
	v_mfma_f32_16x16x32_bf16 v[6:9], v[150:153], v[226:229], 0
	v_mfma_f32_16x16x32_bf16 v[62:65], v[146:149], v[186:189], v[62:65]
	v_mfma_f32_16x16x32_bf16 v[54:57], v[154:157], v[186:189], v[54:57]
	v_mfma_f32_16x16x32_bf16 v[46:49], v[146:149], v[206:209], v[46:49]
	v_mfma_f32_16x16x32_bf16 v[38:41], v[154:157], v[206:209], v[38:41]
	v_mfma_f32_16x16x32_bf16 v[30:33], v[146:149], v[214:217], v[30:33]
	v_mfma_f32_16x16x32_bf16 v[22:25], v[154:157], v[214:217], v[22:25]
	v_mfma_f32_16x16x32_bf16 v[14:17], v[146:149], v[234:237], v[14:17]
	v_mfma_f32_16x16x32_bf16 v[6:9], v[154:157], v[234:237], v[6:9]
	v_mfma_f32_16x16x32_bf16 v[58:61], v[158:161], v[182:185], 0
	v_mfma_f32_16x16x32_bf16 v[50:53], v[166:169], v[182:185], 0
	v_mfma_f32_16x16x32_bf16 v[42:45], v[158:161], v[190:193], 0
	v_mfma_f32_16x16x32_bf16 v[34:37], v[166:169], v[190:193], 0
	v_mfma_f32_16x16x32_bf16 v[26:29], v[158:161], v[210:213], 0
	v_mfma_f32_16x16x32_bf16 v[18:21], v[166:169], v[210:213], 0
	v_mfma_f32_16x16x32_bf16 v[10:13], v[158:161], v[226:229], 0
	v_mfma_f32_16x16x32_bf16 v[2:5], v[166:169], v[226:229], 0
	v_mfma_f32_16x16x32_bf16 v[58:61], v[162:165], v[186:189], v[58:61]
	v_mfma_f32_16x16x32_bf16 v[50:53], v[178:181], v[186:189], v[50:53]
	v_mfma_f32_16x16x32_bf16 v[42:45], v[162:165], v[206:209], v[42:45]
	v_mfma_f32_16x16x32_bf16 v[34:37], v[178:181], v[206:209], v[34:37]
	v_mfma_f32_16x16x32_bf16 v[26:29], v[162:165], v[214:217], v[26:29]
	v_mfma_f32_16x16x32_bf16 v[18:21], v[178:181], v[214:217], v[18:21]
	v_mfma_f32_16x16x32_bf16 v[10:13], v[162:165], v[234:237], v[10:13]
	v_mfma_f32_16x16x32_bf16 v[2:5], v[178:181], v[234:237], v[2:5]
	s_barrier
	s_add_i32 s76, 0, 0x18000
	s_add_i32 s77, 0, 0x1c000
	s_add_u32 s44, s44, 0x80000
	s_addc_u32 s45, s45, 0
	s_mov_b32 m0, s64
	s_nop 0
	global_load_lds_dwordx4 v130, s[44:45]
	ds_read_b128 v[142:145], v230 offset:32768
	ds_read_b128 v[146:149], v230 offset:33792
	ds_read_b128 v[150:153], v230 offset:34816
	ds_read_b128 v[154:157], v230 offset:35840
	ds_read_b128 v[158:161], v230 offset:49152
	ds_read_b128 v[162:165], v230 offset:50176
	ds_read_b128 v[166:169], v230 offset:51200
	ds_read_b128 v[178:181], v230 offset:52224
	s_mov_b32 m0, s65
	s_nop 0
	global_load_lds_dwordx4 v134, s[44:45]
	ds_read_b128 v[182:185], v175 offset:32768
	ds_read_b128 v[186:189], v175 offset:33792
	ds_read_b128 v[190:193], v175 offset:34816
	ds_read_b128 v[206:209], v175 offset:35840
	ds_read_b128 v[210:213], v175 offset:36864
	ds_read_b128 v[214:217], v175 offset:37888
	ds_read_b128 v[226:229], v175 offset:38912
	ds_read_b128 v[234:237], v175 offset:39936
	s_waitcnt lgkmcnt(0)
	v_mfma_f32_16x16x32_bf16 v[126:129], v[142:145], v[182:185], v[126:129]
	v_mfma_f32_16x16x32_bf16 v[118:121], v[150:153], v[182:185], v[118:121]
	v_mfma_f32_16x16x32_bf16 v[110:113], v[142:145], v[190:193], v[110:113]
	v_mfma_f32_16x16x32_bf16 v[102:105], v[150:153], v[190:193], v[102:105]
	s_waitcnt vmcnt(8)
	s_barrier
	v_mfma_f32_16x16x32_bf16 v[94:97], v[142:145], v[210:213], v[94:97]
	v_mfma_f32_16x16x32_bf16 v[86:89], v[150:153], v[210:213], v[86:89]
	v_mfma_f32_16x16x32_bf16 v[78:81], v[142:145], v[226:229], v[78:81]
	v_mfma_f32_16x16x32_bf16 v[70:73], v[150:153], v[226:229], v[70:73]
	v_mfma_f32_16x16x32_bf16 v[126:129], v[146:149], v[186:189], v[126:129]
	v_mfma_f32_16x16x32_bf16 v[118:121], v[154:157], v[186:189], v[118:121]
	v_mfma_f32_16x16x32_bf16 v[110:113], v[146:149], v[206:209], v[110:113]
	v_mfma_f32_16x16x32_bf16 v[102:105], v[154:157], v[206:209], v[102:105]
	v_mfma_f32_16x16x32_bf16 v[94:97], v[146:149], v[214:217], v[94:97]
	v_mfma_f32_16x16x32_bf16 v[86:89], v[154:157], v[214:217], v[86:89]
	v_mfma_f32_16x16x32_bf16 v[78:81], v[146:149], v[234:237], v[78:81]
	v_mfma_f32_16x16x32_bf16 v[70:73], v[154:157], v[234:237], v[70:73]
	v_mfma_f32_16x16x32_bf16 v[122:125], v[158:161], v[182:185], v[122:125]
	v_mfma_f32_16x16x32_bf16 v[114:117], v[166:169], v[182:185], v[114:117]
	v_mfma_f32_16x16x32_bf16 v[106:109], v[158:161], v[190:193], v[106:109]
	v_mfma_f32_16x16x32_bf16 v[98:101], v[166:169], v[190:193], v[98:101]
	v_mfma_f32_16x16x32_bf16 v[90:93], v[158:161], v[210:213], v[90:93]
	v_mfma_f32_16x16x32_bf16 v[82:85], v[166:169], v[210:213], v[82:85]
	v_mfma_f32_16x16x32_bf16 v[74:77], v[158:161], v[226:229], v[74:77]
	v_mfma_f32_16x16x32_bf16 v[66:69], v[166:169], v[226:229], v[66:69]
	v_mfma_f32_16x16x32_bf16 v[122:125], v[162:165], v[186:189], v[122:125]
	v_mfma_f32_16x16x32_bf16 v[114:117], v[178:181], v[186:189], v[114:117]
	v_mfma_f32_16x16x32_bf16 v[106:109], v[162:165], v[206:209], v[106:109]
	v_mfma_f32_16x16x32_bf16 v[98:101], v[178:181], v[206:209], v[98:101]
	v_mfma_f32_16x16x32_bf16 v[90:93], v[162:165], v[214:217], v[90:93]
	v_mfma_f32_16x16x32_bf16 v[82:85], v[178:181], v[214:217], v[82:85]
	v_mfma_f32_16x16x32_bf16 v[74:77], v[162:165], v[234:237], v[74:77]
	v_mfma_f32_16x16x32_bf16 v[66:69], v[178:181], v[234:237], v[66:69]
	s_barrier
; #define PG8_STAGE(bufoff, gbase, voff) do { _Pragma("unroll") for (int _i = 0; _i < 2; ++_i) \
;         __builtin_amdgcn_global_load_lds((const unsigned*)((const char*)(gbase) + (voff)[_i]), (PG8_LAS unsigned*)(lds + (bufoff) + ldsw + _i * 8192), 16, 0, 0); } while (0)
; #define PG8_LDA(dst, b, h) do { _Pragma("unroll") for (int m = 0; m < 4; ++m) _Pragma("unroll") for (int k = 0; k < 2; ++k) dst[m][k] = *(const PG8_LAS bf16x8*)(lds + PG8_SA(b, h) + aoff + m * 2048 + k * 1024); } while (0)
; #define PG8_WAIT_V(n) asm volatile("s_waitcnt vmcnt(" #n ")" ::: "memory")
; #define PG8_WAIT_L(n) asm volatile("s_waitcnt lgkmcnt(" #n ")" ::: "memory")
; #define PG8_BAR __builtin_amdgcn_s_barrier()
; template <class Epi, class Sched, bool ALIGN_EPI = false, bool SP2 = false>
; __device__ __forceinline__ void gemm_phase(PG8_LAS unsigned char* lds, const Gemm g, const Sched& S, const Epi& E, const int wave_id) {
;     ...
;         for (int t = 0; t < nt; t += 2) {
;             const bool last = (t == nt - 2);
;             const char* a1 = cA + (size_t)(t + 1) * kstep;
;             const char* a2 = last ? nA : cA + (size_t)(t + 2) * kstep; const char* b2 = last ? nB : cB + (size_t)(t + 2) * kstep;
;             const char* a3 = a2 + kstep; const char* b3 = b2 + kstep;
;             if (last && has_next) S.a_ready(nxt);
;             if constexpr (SP2) {
;             PG8_LDB(B0, 0, 0); PG8_LDB(B1, 0, 1); PG8_SCHED; PG8_LDA(At, 0, 0); PG8_STAGE(PG8_SA(1, 1), a1 + hstep, voffA);
;             PG8_WAIT_V(8); PG8_WAIT_L(0); PG8_BAR; PG8_MMA(0, 0, At, B0); PG8_MMA(0, 1, At, B1); PG8_BAR; PG8_SCHED;
;             PG8_LDA(At, 0, 1); PG8_STAGE(PG8_SB(0, 0), b2, voffB); PG8_STAGE(PG8_SB(0, 1), b2 + hstep, voffB); PG8_STAGE(PG8_SA(0, 0), a2, voffA);
;             PG8_WAIT_V(8); PG8_WAIT_L(0); PG8_BAR; PG8_MMA(1, 0, At, B0); PG8_MMA(1, 1, At, B1); PG8_BAR; PG8_SCHED;
;             PG8_LDB(B0, 1, 0); PG8_LDB(B1, 1, 1); PG8_SCHED; PG8_LDA(At, 1, 0); PG8_STAGE(PG8_SA(0, 1), a2 + hstep, voffA);
;             PG8_WAIT_V(8); PG8_WAIT_L(0); PG8_BAR; PG8_MMA(0, 0, At, B0); PG8_MMA(0, 1, At, B1); PG8_BAR; PG8_SCHED;
;             PG8_LDA(At, 1, 1); PG8_STAGE(PG8_SB(1, 0), b3, voffB); PG8_STAGE(PG8_SB(1, 1), b3 + hstep, voffB); PG8_STAGE(PG8_SA(1, 0), a3, voffA);
;             PG8_WAIT_V(8); PG8_WAIT_L(0); PG8_BAR; PG8_MMA(1, 0, At, B0); PG8_MMA(1, 1, At, B1); PG8_BAR; PG8_SCHED;
	s_add_u32 vcc_lo, s44, 0xfff80080
	s_addc_u32 vcc_hi, s45, -1
	s_mov_b32 m0, s68
	s_nop 0
	global_load_lds_dwordx4 v130, vcc
	ds_read_b128 v[182:185], v175 offset:49152
	ds_read_b128 v[186:189], v175 offset:50176
	s_mov_b32 m0, s69
	s_add_i32 s44, s76, s53
	global_load_lds_dwordx4 v134, vcc
	ds_read_b128 v[190:193], v175 offset:51200
	ds_read_b128 v[206:209], v175 offset:52224
	s_add_u32 vcc_lo, s42, 0x80
	s_addc_u32 vcc_hi, s43, 0
	s_mov_b32 m0, s44
	s_nop 0
	global_load_lds_dwordx4 v132, vcc
	ds_read_b128 v[210:213], v175 offset:53248
	ds_read_b128 v[214:217], v175 offset:54272
	s_add_i32 m0, s44, 0x2000
	s_add_u32 s42, s42, 0x80080
	s_addc_u32 s43, s43, 0
	global_load_lds_dwordx4 v136, vcc
	ds_read_b128 v[226:229], v175 offset:55296
	ds_read_b128 v[234:237], v175 offset:56320
	s_add_i32 s44, s77, s53
	s_mov_b32 m0, s44
	s_nop 0
	global_load_lds_dwordx4 v132, s[42:43]
	s_add_i32 m0, s44, 0x2000
	s_nop 0
	global_load_lds_dwordx4 v136, s[42:43]
	s_waitcnt lgkmcnt(0)
	v_mfma_f32_16x16x32_bf16 v[62:65], v[142:145], v[182:185], v[62:65]
	v_mfma_f32_16x16x32_bf16 v[54:57], v[150:153], v[182:185], v[54:57]
	v_mfma_f32_16x16x32_bf16 v[46:49], v[142:145], v[190:193], v[46:49]
	v_mfma_f32_16x16x32_bf16 v[38:41], v[150:153], v[190:193], v[38:41]
	s_waitcnt vmcnt(8)
	s_barrier
	v_mfma_f32_16x16x32_bf16 v[30:33], v[142:145], v[210:213], v[30:33]
	v_mfma_f32_16x16x32_bf16 v[22:25], v[150:153], v[210:213], v[22:25]
	v_mfma_f32_16x16x32_bf16 v[14:17], v[142:145], v[226:229], v[14:17]
	v_mfma_f32_16x16x32_bf16 v[6:9], v[150:153], v[226:229], v[6:9]
	v_mfma_f32_16x16x32_bf16 v[62:65], v[146:149], v[186:189], v[62:65]
	v_mfma_f32_16x16x32_bf16 v[54:57], v[154:157], v[186:189], v[54:57]
	v_mfma_f32_16x16x32_bf16 v[46:49], v[146:149], v[206:209], v[46:49]
	v_mfma_f32_16x16x32_bf16 v[38:41], v[154:157], v[206:209], v[38:41]
	v_mfma_f32_16x16x32_bf16 v[30:33], v[146:149], v[214:217], v[30:33]
	v_mfma_f32_16x16x32_bf16 v[22:25], v[154:157], v[214:217], v[22:25]
	v_mfma_f32_16x16x32_bf16 v[14:17], v[146:149], v[234:237], v[14:17]
	v_mfma_f32_16x16x32_bf16 v[6:9], v[154:157], v[234:237], v[6:9]
	v_mfma_f32_16x16x32_bf16 v[58:61], v[158:161], v[182:185], v[58:61]
	v_mfma_f32_16x16x32_bf16 v[50:53], v[166:169], v[182:185], v[50:53]
	v_mfma_f32_16x16x32_bf16 v[42:45], v[158:161], v[190:193], v[42:45]
	v_mfma_f32_16x16x32_bf16 v[34:37], v[166:169], v[190:193], v[34:37]
	v_mfma_f32_16x16x32_bf16 v[26:29], v[158:161], v[210:213], v[26:29]
	v_mfma_f32_16x16x32_bf16 v[18:21], v[166:169], v[210:213], v[18:21]
	v_mfma_f32_16x16x32_bf16 v[10:13], v[158:161], v[226:229], v[10:13]
	v_mfma_f32_16x16x32_bf16 v[2:5], v[166:169], v[226:229], v[2:5]
	v_mfma_f32_16x16x32_bf16 v[58:61], v[162:165], v[186:189], v[58:61]
	v_mfma_f32_16x16x32_bf16 v[50:53], v[178:181], v[186:189], v[50:53]
	v_mfma_f32_16x16x32_bf16 v[42:45], v[162:165], v[206:209], v[42:45]
	v_mfma_f32_16x16x32_bf16 v[34:37], v[178:181], v[206:209], v[34:37]
	v_mfma_f32_16x16x32_bf16 v[26:29], v[162:165], v[214:217], v[26:29]
	v_mfma_f32_16x16x32_bf16 v[18:21], v[178:181], v[214:217], v[18:21]
	v_mfma_f32_16x16x32_bf16 v[10:13], v[162:165], v[234:237], v[10:13]
	v_mfma_f32_16x16x32_bf16 v[2:5], v[178:181], v[234:237], v[2:5]
	s_barrier
	s_add_i32 s75, s75, 2
	s_add_u32 s20, s20, 0x100
	s_addc_u32 s21, s21, 0
	s_add_u32 s73, s73, 0x100
	s_addc_u32 s74, s74, 0
	s_cmp_gt_u32 s75, 29
	s_cbranch_scc1 .Lpeel_exit_g1
.LBB0_174:
	s_add_u32 s42, s20, 0xfff80080
	s_addc_u32 s43, s21, -1
	s_add_i32 s76, 0, 0x10000
	s_cmp_eq_u32 s75, 28
	s_cselect_b32 s45, s15, s43
	s_cselect_b32 s44, s41, s42
	s_cselect_b32 s43, s13, s74
	s_cselect_b32 s42, s72, s73
	s_add_i32 s79, 0, 0x14000
	s_add_i32 m0, s56, 0xc000
	s_nop 0
	global_load_lds_dwordx4 v138, s[20:21]
	ds_read_b128 v[142:145], v230
	ds_read_b128 v[146:149], v230 offset:1024
	ds_read_b128 v[150:153], v230 offset:2048
	ds_read_b128 v[154:157], v230 offset:3072
	ds_read_b128 v[158:161], v230 offset:16384
	ds_read_b128 v[162:165], v230 offset:17408
	ds_read_b128 v[166:169], v230 offset:18432
	ds_read_b128 v[178:181], v230 offset:19456
	s_add_i32 m0, s56, 0xe000
	s_nop 0
	global_load_lds_dwordx4 v140, s[20:21]
	ds_read_b128 v[182:185], v175
	ds_read_b128 v[186:189], v175 offset:1024
	ds_read_b128 v[190:193], v175 offset:2048
	ds_read_b128 v[206:209], v175 offset:3072
	ds_read_b128 v[210:213], v175 offset:4096
	ds_read_b128 v[214:217], v175 offset:5120
	ds_read_b128 v[226:229], v175 offset:6144
	ds_read_b128 v[234:237], v175 offset:7168
	s_waitcnt lgkmcnt(0)
	v_mfma_f32_16x16x32_bf16 v[126:129], v[142:145], v[182:185], v[126:129]
	v_mfma_f32_16x16x32_bf16 v[118:121], v[150:153], v[182:185], v[118:121]
	v_mfma_f32_16x16x32_bf16 v[110:113], v[142:145], v[190:193], v[110:113]
	v_mfma_f32_16x16x32_bf16 v[102:105], v[150:153], v[190:193], v[102:105]
	s_waitcnt vmcnt(8)
	s_barrier
; #define PG8_STAGE(bufoff, gbase, voff) do { _Pragma("unroll") for (int _i = 0; _i < 2; ++_i) \
;         __builtin_amdgcn_global_load_lds((const unsigned*)((const char*)(gbase) + (voff)[_i]), (PG8_LAS unsigned*)(lds + (bufoff) + ldsw + _i * 8192), 16, 0, 0); } while (0)
; #define PG8_LDA(dst, b, h) do { _Pragma("unroll") for (int m = 0; m < 4; ++m) _Pragma("unroll") for (int k = 0; k < 2; ++k) dst[m][k] = *(const PG8_LAS bf16x8*)(lds + PG8_SA(b, h) + aoff + m * 2048 + k * 1024); } while (0)
; #define PG8_LDB(dst, b, h) do { _Pragma("unroll") for (int n = 0; n < 2; ++n) _Pragma("unroll") for (int k = 0; k < 2; ++k) dst[n][k] = *(const PG8_LAS bf16x8*)(lds + PG8_SB(b, h) + boff + n * 2048 + k * 1024); } while (0)
; #define PG8_MMA(ai, bj, At, Bt) do { __builtin_amdgcn_s_setprio(1); _Pragma("unroll") for (int m = 0; m < 4; ++m) _Pragma("unroll") for (int n = 0; n < 2; ++n) _Pragma("unroll") for (int k = 0; k < 2; ++k) \
;         acc[ai][bj][m][n] = __builtin_amdgcn_mfma_f32_16x16x32_bf16(Bt[n][k], At[m][k], acc[ai][bj][m][n], 0, 0, 0); __builtin_amdgcn_s_setprio(0); } while (0)
; #define PG8_BAR __builtin_amdgcn_s_barrier()
; template <class Epi, class Sched, bool ALIGN_EPI = false, bool SP2 = false>
; __device__ __forceinline__ void gemm_phase(PG8_LAS unsigned char* lds, const Gemm g, const Sched& S, const Epi& E, const int wave_id) {
;     ...
;             PG8_LDB(B0, 0, 0); PG8_LDB(B1, 0, 1); PG8_SCHED; PG8_LDA(At, 0, 0); PG8_STAGE(PG8_SA(1, 1), a1 + hstep, voffA);
;             PG8_WAIT_V(8); PG8_WAIT_L(0); PG8_BAR; PG8_MMA(0, 0, At, B0); PG8_MMA(0, 1, At, B1); PG8_BAR; PG8_SCHED;
;             PG8_LDA(At, 0, 1); PG8_STAGE(PG8_SB(0, 0), b2, voffB); PG8_STAGE(PG8_SB(0, 1), b2 + hstep, voffB); PG8_STAGE(PG8_SA(0, 0), a2, voffA);
;             PG8_WAIT_V(8); PG8_WAIT_L(0); PG8_BAR; PG8_MMA(1, 0, At, B0); PG8_MMA(1, 1, At, B1); PG8_BAR; PG8_SCHED;
;             PG8_LDB(B0, 1, 0); PG8_LDB(B1, 1, 1); PG8_SCHED; PG8_LDA(At, 1, 0); PG8_STAGE(PG8_SA(0, 1), a2 + hstep, voffA);
;             PG8_WAIT_V(8); PG8_WAIT_L(0); PG8_BAR; PG8_MMA(0, 0, At, B0); PG8_MMA(0, 1, At, B1); PG8_BAR; PG8_SCHED;
;             PG8_LDA(At, 1, 1); PG8_STAGE(PG8_SB(1, 0), b3, voffB); PG8_STAGE(PG8_SB(1, 1), b3 + hstep, voffB); PG8_STAGE(PG8_SA(1, 0), a3, voffA);
;             PG8_WAIT_V(8); PG8_WAIT_L(0); PG8_BAR; PG8_MMA(1, 0, At, B0); PG8_MMA(1, 1, At, B1); PG8_BAR; PG8_SCHED;
	v_mfma_f32_16x16x32_bf16 v[94:97], v[142:145], v[210:213], v[94:97]
	v_mfma_f32_16x16x32_bf16 v[86:89], v[150:153], v[210:213], v[86:89]
	v_mfma_f32_16x16x32_bf16 v[78:81], v[142:145], v[226:229], v[78:81]
	v_mfma_f32_16x16x32_bf16 v[70:73], v[150:153], v[226:229], v[70:73]
	v_mfma_f32_16x16x32_bf16 v[126:129], v[146:149], v[186:189], v[126:129]
	v_mfma_f32_16x16x32_bf16 v[118:121], v[154:157], v[186:189], v[118:121]
	v_mfma_f32_16x16x32_bf16 v[110:113], v[146:149], v[206:209], v[110:113]
	v_mfma_f32_16x16x32_bf16 v[102:105], v[154:157], v[206:209], v[102:105]
	v_mfma_f32_16x16x32_bf16 v[94:97], v[146:149], v[214:217], v[94:97]
	v_mfma_f32_16x16x32_bf16 v[86:89], v[154:157], v[214:217], v[86:89]
	v_mfma_f32_16x16x32_bf16 v[78:81], v[146:149], v[234:237], v[78:81]
	v_mfma_f32_16x16x32_bf16 v[70:73], v[154:157], v[234:237], v[70:73]
	v_mfma_f32_16x16x32_bf16 v[122:125], v[158:161], v[182:185], v[122:125]
	v_mfma_f32_16x16x32_bf16 v[114:117], v[166:169], v[182:185], v[114:117]
	v_mfma_f32_16x16x32_bf16 v[106:109], v[158:161], v[190:193], v[106:109]
	v_mfma_f32_16x16x32_bf16 v[98:101], v[166:169], v[190:193], v[98:101]
	v_mfma_f32_16x16x32_bf16 v[90:93], v[158:161], v[210:213], v[90:93]
	v_mfma_f32_16x16x32_bf16 v[82:85], v[166:169], v[210:213], v[82:85]
	v_mfma_f32_16x16x32_bf16 v[74:77], v[158:161], v[226:229], v[74:77]
	v_mfma_f32_16x16x32_bf16 v[66:69], v[166:169], v[226:229], v[66:69]
	v_mfma_f32_16x16x32_bf16 v[122:125], v[162:165], v[186:189], v[122:125]
	v_mfma_f32_16x16x32_bf16 v[114:117], v[178:181], v[186:189], v[114:117]
	v_mfma_f32_16x16x32_bf16 v[106:109], v[162:165], v[206:209], v[106:109]
	v_mfma_f32_16x16x32_bf16 v[98:101], v[178:181], v[206:209], v[98:101]
	v_mfma_f32_16x16x32_bf16 v[90:93], v[162:165], v[214:217], v[90:93]
	v_mfma_f32_16x16x32_bf16 v[82:85], v[178:181], v[214:217], v[82:85]
	v_mfma_f32_16x16x32_bf16 v[74:77], v[162:165], v[234:237], v[74:77]
	v_mfma_f32_16x16x32_bf16 v[66:69], v[178:181], v[234:237], v[66:69]
	s_barrier
	s_add_i32 s76, s76, s53
	s_mov_b32 m0, s76
	s_nop 0
	global_load_lds_dwordx4 v132, s[42:43]
	ds_read_b128 v[182:185], v175 offset:16384
	ds_read_b128 v[186:189], v175 offset:17408
	s_add_i32 m0, s76, 0x2000
	s_add_u32 s76, s42, 0x80000
	s_addc_u32 s77, s43, 0
	s_add_i32 s79, s79, s53
	global_load_lds_dwordx4 v136, s[42:43]
	ds_read_b128 v[190:193], v175 offset:18432
	ds_read_b128 v[206:209], v175 offset:19456
	s_mov_b32 m0, s79
	s_nop 0
	global_load_lds_dwordx4 v132, s[76:77]
	ds_read_b128 v[210:213], v175 offset:20480
	ds_read_b128 v[214:217], v175 offset:21504
	s_add_i32 m0, s79, 0x2000
	s_nop 0
	global_load_lds_dwordx4 v136, s[76:77]
	ds_read_b128 v[226:229], v175 offset:22528
	ds_read_b128 v[234:237], v175 offset:23552
	s_mov_b32 m0, s56
	s_nop 0
	global_load_lds_dwordx4 v130, s[44:45]
	s_mov_b32 m0, s57
	s_nop 0
	global_load_lds_dwordx4 v134, s[44:45]
	s_waitcnt lgkmcnt(0)
	v_mfma_f32_16x16x32_bf16 v[62:65], v[142:145], v[182:185], v[62:65]
	v_mfma_f32_16x16x32_bf16 v[54:57], v[150:153], v[182:185], v[54:57]
	v_mfma_f32_16x16x32_bf16 v[46:49], v[142:145], v[190:193], v[46:49]
	v_mfma_f32_16x16x32_bf16 v[38:41], v[150:153], v[190:193], v[38:41]
	s_waitcnt vmcnt(8)
	s_barrier
	v_mfma_f32_16x16x32_bf16 v[30:33], v[142:145], v[210:213], v[30:33]
	v_mfma_f32_16x16x32_bf16 v[22:25], v[150:153], v[210:213], v[22:25]
	v_mfma_f32_16x16x32_bf16 v[14:17], v[142:145], v[226:229], v[14:17]
	v_mfma_f32_16x16x32_bf16 v[6:9], v[150:153], v[226:229], v[6:9]
	v_mfma_f32_16x16x32_bf16 v[62:65], v[146:149], v[186:189], v[62:65]
	v_mfma_f32_16x16x32_bf16 v[54:57], v[154:157], v[186:189], v[54:57]
	v_mfma_f32_16x16x32_bf16 v[46:49], v[146:149], v[206:209], v[46:49]
	v_mfma_f32_16x16x32_bf16 v[38:41], v[154:157], v[206:209], v[38:41]
	v_mfma_f32_16x16x32_bf16 v[30:33], v[146:149], v[214:217], v[30:33]
	v_mfma_f32_16x16x32_bf16 v[22:25], v[154:157], v[214:217], v[22:25]
	v_mfma_f32_16x16x32_bf16 v[14:17], v[146:149], v[234:237], v[14:17]
	v_mfma_f32_16x16x32_bf16 v[6:9], v[154:157], v[234:237], v[6:9]
	v_mfma_f32_16x16x32_bf16 v[58:61], v[158:161], v[182:185], v[58:61]
	v_mfma_f32_16x16x32_bf16 v[50:53], v[166:169], v[182:185], v[50:53]
	v_mfma_f32_16x16x32_bf16 v[42:45], v[158:161], v[190:193], v[42:45]
	v_mfma_f32_16x16x32_bf16 v[34:37], v[166:169], v[190:193], v[34:37]
	v_mfma_f32_16x16x32_bf16 v[26:29], v[158:161], v[210:213], v[26:29]
	v_mfma_f32_16x16x32_bf16 v[18:21], v[166:169], v[210:213], v[18:21]
	v_mfma_f32_16x16x32_bf16 v[10:13], v[158:161], v[226:229], v[10:13]
	v_mfma_f32_16x16x32_bf16 v[2:5], v[166:169], v[226:229], v[2:5]
	v_mfma_f32_16x16x32_bf16 v[58:61], v[162:165], v[186:189], v[58:61]
	v_mfma_f32_16x16x32_bf16 v[50:53], v[178:181], v[186:189], v[50:53]
	v_mfma_f32_16x16x32_bf16 v[42:45], v[162:165], v[206:209], v[42:45]
	v_mfma_f32_16x16x32_bf16 v[34:37], v[178:181], v[206:209], v[34:37]
	v_mfma_f32_16x16x32_bf16 v[26:29], v[162:165], v[214:217], v[26:29]
	v_mfma_f32_16x16x32_bf16 v[18:21], v[178:181], v[214:217], v[18:21]
	v_mfma_f32_16x16x32_bf16 v[10:13], v[162:165], v[234:237], v[10:13]
	v_mfma_f32_16x16x32_bf16 v[2:5], v[178:181], v[234:237], v[2:5]
	s_barrier
; #define PG8_STAGE(bufoff, gbase, voff) do { _Pragma("unroll") for (int _i = 0; _i < 2; ++_i) \
;         __builtin_amdgcn_global_load_lds((const unsigned*)((const char*)(gbase) + (voff)[_i]), (PG8_LAS unsigned*)(lds + (bufoff) + ldsw + _i * 8192), 16, 0, 0); } while (0)
; #define PG8_LDA(dst, b, h) do { _Pragma("unroll") for (int m = 0; m < 4; ++m) _Pragma("unroll") for (int k = 0; k < 2; ++k) dst[m][k] = *(const PG8_LAS bf16x8*)(lds + PG8_SA(b, h) + aoff + m * 2048 + k * 1024); } while (0)
; #define PG8_LDB(dst, b, h) do { _Pragma("unroll") for (int n = 0; n < 2; ++n) _Pragma("unroll") for (int k = 0; k < 2; ++k) dst[n][k] = *(const PG8_LAS bf16x8*)(lds + PG8_SB(b, h) + boff + n * 2048 + k * 1024); } while (0)
; #define PG8_MMA(ai, bj, At, Bt) do { __builtin_amdgcn_s_setprio(1); _Pragma("unroll") for (int m = 0; m < 4; ++m) _Pragma("unroll") for (int n = 0; n < 2; ++n) _Pragma("unroll") for (int k = 0; k < 2; ++k) \
;         acc[ai][bj][m][n] = __builtin_amdgcn_mfma_f32_16x16x32_bf16(Bt[n][k], At[m][k], acc[ai][bj][m][n], 0, 0, 0); __builtin_amdgcn_s_setprio(0); } while (0)
; template <class Epi, class Sched, bool ALIGN_EPI = false, bool SP2 = false>
; __device__ __forceinline__ void gemm_phase(PG8_LAS unsigned char* lds, const Gemm g, const Sched& S, const Epi& E, const int wave_id) {
;     ...
;             PG8_LDB(B0, 0, 0); PG8_LDB(B1, 0, 1); PG8_SCHED; PG8_LDA(At, 0, 0); PG8_STAGE(PG8_SA(1, 1), a1 + hstep, voffA);
;             PG8_WAIT_V(8); PG8_WAIT_L(0); PG8_BAR; PG8_MMA(0, 0, At, B0); PG8_MMA(0, 1, At, B1); PG8_BAR; PG8_SCHED;
;             PG8_LDA(At, 0, 1); PG8_STAGE(PG8_SB(0, 0), b2, voffB); PG8_STAGE(PG8_SB(0, 1), b2 + hstep, voffB); PG8_STAGE(PG8_SA(0, 0), a2, voffA);
;             PG8_WAIT_V(8); PG8_WAIT_L(0); PG8_BAR; PG8_MMA(1, 0, At, B0); PG8_MMA(1, 1, At, B1); PG8_BAR; PG8_SCHED;
;             PG8_LDB(B0, 1, 0); PG8_LDB(B1, 1, 1); PG8_SCHED; PG8_LDA(At, 1, 0); PG8_STAGE(PG8_SA(0, 1), a2 + hstep, voffA);
;             PG8_WAIT_V(8); PG8_WAIT_L(0); PG8_BAR; PG8_MMA(0, 0, At, B0); PG8_MMA(0, 1, At, B1); PG8_BAR; PG8_SCHED;
;             PG8_LDA(At, 1, 1); PG8_STAGE(PG8_SB(1, 0), b3, voffB); PG8_STAGE(PG8_SB(1, 1), b3 + hstep, voffB); PG8_STAGE(PG8_SA(1, 0), a3, voffA);
;             PG8_WAIT_V(8); PG8_WAIT_L(0); PG8_BAR; PG8_MMA(1, 0, At, B0); PG8_MMA(1, 1, At, B1); PG8_BAR; PG8_SCHED;
;     ...
;         if constexpr (ALIGN_EPI) { if (wr == 0) PG8_BAR; }
	s_add_i32 s76, 0, 0x18000
	s_add_i32 s77, 0, 0x1c000
	s_add_u32 s44, s44, 0x80000
	s_addc_u32 s45, s45, 0
	s_mov_b32 m0, s64
	s_nop 0
	global_load_lds_dwordx4 v130, s[44:45]
	ds_read_b128 v[142:145], v230 offset:32768
	ds_read_b128 v[146:149], v230 offset:33792
	ds_read_b128 v[150:153], v230 offset:34816
	ds_read_b128 v[154:157], v230 offset:35840
	ds_read_b128 v[158:161], v230 offset:49152
	ds_read_b128 v[162:165], v230 offset:50176
	ds_read_b128 v[166:169], v230 offset:51200
	ds_read_b128 v[178:181], v230 offset:52224
	s_mov_b32 m0, s65
	s_nop 0
	global_load_lds_dwordx4 v134, s[44:45]
	ds_read_b128 v[182:185], v175 offset:32768
	ds_read_b128 v[186:189], v175 offset:33792
	ds_read_b128 v[190:193], v175 offset:34816
	ds_read_b128 v[206:209], v175 offset:35840
	ds_read_b128 v[210:213], v175 offset:36864
	ds_read_b128 v[214:217], v175 offset:37888
	ds_read_b128 v[226:229], v175 offset:38912
	ds_read_b128 v[234:237], v175 offset:39936
	s_waitcnt lgkmcnt(0)
	v_mfma_f32_16x16x32_bf16 v[126:129], v[142:145], v[182:185], v[126:129]
	v_mfma_f32_16x16x32_bf16 v[118:121], v[150:153], v[182:185], v[118:121]
	v_mfma_f32_16x16x32_bf16 v[110:113], v[142:145], v[190:193], v[110:113]
	v_mfma_f32_16x16x32_bf16 v[102:105], v[150:153], v[190:193], v[102:105]
	s_waitcnt vmcnt(8)
	s_barrier
	v_mfma_f32_16x16x32_bf16 v[94:97], v[142:145], v[210:213], v[94:97]
	v_mfma_f32_16x16x32_bf16 v[86:89], v[150:153], v[210:213], v[86:89]
	v_mfma_f32_16x16x32_bf16 v[78:81], v[142:145], v[226:229], v[78:81]
	v_mfma_f32_16x16x32_bf16 v[70:73], v[150:153], v[226:229], v[70:73]
	v_mfma_f32_16x16x32_bf16 v[126:129], v[146:149], v[186:189], v[126:129]
	v_mfma_f32_16x16x32_bf16 v[118:121], v[154:157], v[186:189], v[118:121]
	v_mfma_f32_16x16x32_bf16 v[110:113], v[146:149], v[206:209], v[110:113]
	v_mfma_f32_16x16x32_bf16 v[102:105], v[154:157], v[206:209], v[102:105]
	v_mfma_f32_16x16x32_bf16 v[94:97], v[146:149], v[214:217], v[94:97]
	v_mfma_f32_16x16x32_bf16 v[86:89], v[154:157], v[214:217], v[86:89]
	v_mfma_f32_16x16x32_bf16 v[78:81], v[146:149], v[234:237], v[78:81]
	v_mfma_f32_16x16x32_bf16 v[70:73], v[154:157], v[234:237], v[70:73]
	v_mfma_f32_16x16x32_bf16 v[122:125], v[158:161], v[182:185], v[122:125]
	v_mfma_f32_16x16x32_bf16 v[114:117], v[166:169], v[182:185], v[114:117]
	v_mfma_f32_16x16x32_bf16 v[106:109], v[158:161], v[190:193], v[106:109]
	v_mfma_f32_16x16x32_bf16 v[98:101], v[166:169], v[190:193], v[98:101]
	v_mfma_f32_16x16x32_bf16 v[90:93], v[158:161], v[210:213], v[90:93]
	v_mfma_f32_16x16x32_bf16 v[82:85], v[166:169], v[210:213], v[82:85]
	v_mfma_f32_16x16x32_bf16 v[74:77], v[158:161], v[226:229], v[74:77]
	v_mfma_f32_16x16x32_bf16 v[66:69], v[166:169], v[226:229], v[66:69]
	v_mfma_f32_16x16x32_bf16 v[122:125], v[162:165], v[186:189], v[122:125]
	v_mfma_f32_16x16x32_bf16 v[114:117], v[178:181], v[186:189], v[114:117]
	v_mfma_f32_16x16x32_bf16 v[106:109], v[162:165], v[206:209], v[106:109]
	v_mfma_f32_16x16x32_bf16 v[98:101], v[178:181], v[206:209], v[98:101]
	v_mfma_f32_16x16x32_bf16 v[90:93], v[162:165], v[214:217], v[90:93]
	v_mfma_f32_16x16x32_bf16 v[82:85], v[178:181], v[214:217], v[82:85]
	v_mfma_f32_16x16x32_bf16 v[74:77], v[162:165], v[234:237], v[74:77]
	v_mfma_f32_16x16x32_bf16 v[66:69], v[178:181], v[234:237], v[66:69]
	s_barrier
	s_add_u32 vcc_lo, s44, 0xfff80080
	s_addc_u32 vcc_hi, s45, -1
	s_mov_b32 m0, s68
	s_nop 0
	global_load_lds_dwordx4 v130, vcc
	ds_read_b128 v[182:185], v175 offset:49152
	ds_read_b128 v[186:189], v175 offset:50176
	s_mov_b32 m0, s69
	s_add_i32 s44, s76, s53
	global_load_lds_dwordx4 v134, vcc
	ds_read_b128 v[190:193], v175 offset:51200
	ds_read_b128 v[206:209], v175 offset:52224
	s_add_u32 vcc_lo, s42, 0x80
	s_addc_u32 vcc_hi, s43, 0
	s_mov_b32 m0, s44
	s_nop 0
	global_load_lds_dwordx4 v132, vcc
	ds_read_b128 v[210:213], v175 offset:53248
	ds_read_b128 v[214:217], v175 offset:54272
	s_add_i32 m0, s44, 0x2000
	s_add_u32 s42, s42, 0x80080
	s_addc_u32 s43, s43, 0
	global_load_lds_dwordx4 v136, vcc
	ds_read_b128 v[226:229], v175 offset:55296
	ds_read_b128 v[234:237], v175 offset:56320
	s_add_i32 s44, s77, s53
	s_mov_b32 m0, s44
	s_nop 0
	global_load_lds_dwordx4 v132, s[42:43]
	s_add_i32 m0, s44, 0x2000
	s_nop 0
	global_load_lds_dwordx4 v136, s[42:43]
	s_waitcnt lgkmcnt(0)
	v_mfma_f32_16x16x32_bf16 v[62:65], v[142:145], v[182:185], v[62:65]
	v_mfma_f32_16x16x32_bf16 v[54:57], v[150:153], v[182:185], v[54:57]
	v_mfma_f32_16x16x32_bf16 v[46:49], v[142:145], v[190:193], v[46:49]
	v_mfma_f32_16x16x32_bf16 v[38:41], v[150:153], v[190:193], v[38:41]
	s_waitcnt vmcnt(8)
	s_barrier
	v_mfma_f32_16x16x32_bf16 v[30:33], v[142:145], v[210:213], v[30:33]
	v_mfma_f32_16x16x32_bf16 v[22:25], v[150:153], v[210:213], v[22:25]
	v_mfma_f32_16x16x32_bf16 v[14:17], v[142:145], v[226:229], v[14:17]
	v_mfma_f32_16x16x32_bf16 v[6:9], v[150:153], v[226:229], v[6:9]
	v_mfma_f32_16x16x32_bf16 v[62:65], v[146:149], v[186:189], v[62:65]
	v_mfma_f32_16x16x32_bf16 v[54:57], v[154:157], v[186:189], v[54:57]
	v_mfma_f32_16x16x32_bf16 v[46:49], v[146:149], v[206:209], v[46:49]
	v_mfma_f32_16x16x32_bf16 v[38:41], v[154:157], v[206:209], v[38:41]
	v_mfma_f32_16x16x32_bf16 v[30:33], v[146:149], v[214:217], v[30:33]
	v_mfma_f32_16x16x32_bf16 v[22:25], v[154:157], v[214:217], v[22:25]
	v_mfma_f32_16x16x32_bf16 v[14:17], v[146:149], v[234:237], v[14:17]
	v_mfma_f32_16x16x32_bf16 v[6:9], v[154:157], v[234:237], v[6:9]
	v_mfma_f32_16x16x32_bf16 v[58:61], v[158:161], v[182:185], v[58:61]
	v_mfma_f32_16x16x32_bf16 v[50:53], v[166:169], v[182:185], v[50:53]
	v_mfma_f32_16x16x32_bf16 v[42:45], v[158:161], v[190:193], v[42:45]
	v_mfma_f32_16x16x32_bf16 v[34:37], v[166:169], v[190:193], v[34:37]
	v_mfma_f32_16x16x32_bf16 v[26:29], v[158:161], v[210:213], v[26:29]
	v_mfma_f32_16x16x32_bf16 v[18:21], v[166:169], v[210:213], v[18:21]
	v_mfma_f32_16x16x32_bf16 v[10:13], v[158:161], v[226:229], v[10:13]
	v_mfma_f32_16x16x32_bf16 v[2:5], v[166:169], v[226:229], v[2:5]
	v_mfma_f32_16x16x32_bf16 v[58:61], v[162:165], v[186:189], v[58:61]
	v_mfma_f32_16x16x32_bf16 v[50:53], v[178:181], v[186:189], v[50:53]
	v_mfma_f32_16x16x32_bf16 v[42:45], v[162:165], v[206:209], v[42:45]
	v_mfma_f32_16x16x32_bf16 v[34:37], v[178:181], v[206:209], v[34:37]
	v_mfma_f32_16x16x32_bf16 v[26:29], v[162:165], v[214:217], v[26:29]
	v_mfma_f32_16x16x32_bf16 v[18:21], v[178:181], v[214:217], v[18:21]
	v_mfma_f32_16x16x32_bf16 v[10:13], v[162:165], v[234:237], v[10:13]
	v_mfma_f32_16x16x32_bf16 v[2:5], v[178:181], v[234:237], v[2:5]
	s_barrier
	s_add_i32 s75, s75, 2
	s_add_u32 s20, s20, 0x100
	s_addc_u32 s21, s21, 0
	s_add_u32 s73, s73, 0x100
	s_addc_u32 s74, s74, 0
	s_cmp_gt_u32 s75, 29
	s_cbranch_scc0 .LBB0_174
.Lpeel_exit_g1:
	s_setprio 0
	s_and_b64 vcc, exec, s[10:11]
	s_cbranch_vccz .LBB0_177
	s_barrier

;     __host__ __device__ bool next(int i, Unit& u) const { const bool ok = StaticOrder::next(i, u); u.lm = 0; u.ln = 0; return ok; }
; #define PG8_STAGE(bufoff, gbase, voff) do { _Pragma("unroll") for (int _i = 0; _i < 2; ++_i) \
;         __builtin_amdgcn_global_load_lds((const unsigned*)((const char*)(gbase) + (voff)[_i]), (PG8_LAS unsigned*)(lds + (bufoff) + ldsw + _i * 8192), 16, 0, 0); } while (0)
; #define PG8_BAR __builtin_amdgcn_s_barrier()
; template <class Epi, class Sched, bool ALIGN_EPI = false, bool SP2 = false>
; __device__ __forceinline__ void gemm_phase(PG8_LAS unsigned char* lds, const Gemm g, const Sched& S, const Epi& E, const int wave_id) {
;     ...
;         const bool has_next = S.next(ui + 1, nxt);
;         const char* nA = has_next ? (const char*)g.A + (size_t)nxt.lm * tstep : cA; const char* nB = has_next ? (const char*)g.Bt + (size_t)nxt.ln * tstep : cB;
; #pragma unroll 1
;         for (int t = 0; t < nt; t += 2) {
;             const bool last = (t == nt - 2);
;             const char* a1 = cA + (size_t)(t + 1) * kstep;
;             const char* a2 = last ? nA : cA + (size_t)(t + 2) * kstep; const char* b2 = last ? nB : cB + (size_t)(t + 2) * kstep;
;             const char* a3 = a2 + kstep; const char* b3 = b2 + kstep;
;             if (last && has_next) S.a_ready(nxt);
;             if constexpr (SP2) {
;             PG8_LDB(B0, 0, 0); PG8_LDB(B1, 0, 1); PG8_SCHED; PG8_LDA(At, 0, 0); PG8_STAGE(PG8_SA(1, 1), a1 + hstep, voffA);
;             PG8_WAIT_V(8); PG8_WAIT_L(0); PG8_BAR; PG8_MMA(0, 0, At, B0); PG8_MMA(0, 1, At, B1); PG8_BAR; PG8_SCHED;
;             PG8_LDA(At, 0, 1); PG8_STAGE(PG8_SB(0, 0), b2, voffB); PG8_STAGE(PG8_SB(0, 1), b2 + hstep, voffB); PG8_STAGE(PG8_SA(0, 0), a2, voffA);
;             PG8_WAIT_V(8); PG8_WAIT_L(0); PG8_BAR; PG8_MMA(1, 0, At, B0); PG8_MMA(1, 1, At, B1); PG8_BAR; PG8_SCHED;
;             PG8_LDB(B0, 1, 0); PG8_LDB(B1, 1, 1); PG8_SCHED; PG8_LDA(At, 1, 0); PG8_STAGE(PG8_SA(0, 1), a2 + hstep, voffA);
;             PG8_WAIT_V(8); PG8_WAIT_L(0); PG8_BAR; PG8_MMA(0, 0, At, B0); PG8_MMA(0, 1, At, B1); PG8_BAR; PG8_SCHED;
;             PG8_LDA(At, 1, 1); PG8_STAGE(PG8_SB(1, 0), b3, voffB); PG8_STAGE(PG8_SB(1, 1), b3 + hstep, voffB); PG8_STAGE(PG8_SA(1, 0), a3, voffA);
;             PG8_WAIT_V(8); PG8_WAIT_L(0); PG8_BAR; PG8_MMA(1, 0, At, B0); PG8_MMA(1, 1, At, B1); PG8_BAR; PG8_SCHED;
.LBB0_523:
	s_ashr_i32 s15, s14, 31
	s_lshl_b64 s[16:17], s[14:15], 20
	s_add_u32 s16, s47, s16
	s_addc_u32 s17, s48, s17
	s_and_b64 s[18:19], s[38:39], exec
	s_cselect_b32 s15, s17, s41
	s_cselect_b32 s21, s16, s40
	s_ashr_i32 s13, s12, 31
	s_lshl_b64 s[18:19], s[12:13], 20
	s_add_u32 s18, s49, s18
	s_addc_u32 s19, s52, s19
	s_and_b64 s[44:45], s[38:39], exec
	s_cselect_b32 s13, s19, s43
	s_cselect_b32 s73, s18, s42
	s_add_u32 s40, s40, 0x80080
	s_addc_u32 s41, s41, 0
	s_add_u32 s74, s42, 0x100
	s_addc_u32 s75, s43, 0
	s_mov_b32 s76, -2
	v_add_u32_e32 v226, 0x10000, v218
	s_cmp_eq_u64 s[10:11], 0
	s_cbranch_scc0 .Lprio_g2
	s_setprio 1
.Lprio_g2:
	s_add_u32 s42, s40, 0xfff80080
	s_addc_u32 s43, s41, -1
	s_add_i32 s77, 0, 0x10000
	s_cmp_eq_u32 s76, 28
	s_cselect_b32 s45, s15, s43
	s_cselect_b32 s44, s21, s42
	s_cselect_b32 s43, s13, s75
	s_cselect_b32 s42, s73, s74
	s_add_i32 s79, 0, 0x14000
	s_add_i32 m0, s56, 0xc000
	s_nop 0
	global_load_lds_dwordx4 v210, s[40:41]
	ds_read_b128 v[118:121], v226
	ds_read_b128 v[122:125], v226 offset:1024
	ds_read_b128 v[130:133], v226 offset:2048
	ds_read_b128 v[134:137], v226 offset:3072
	ds_read_b128 v[146:149], v226 offset:16384
	ds_read_b128 v[150:153], v226 offset:17408
	ds_read_b128 v[154:157], v226 offset:18432
	ds_read_b128 v[158:161], v226 offset:19456
	s_add_i32 m0, s56, 0xe000
	s_nop 0
	global_load_lds_dwordx4 v212, s[40:41]
	ds_read_b128 v[162:165], v222
	ds_read_b128 v[166:169], v222 offset:1024
	ds_read_b128 v[170:173], v222 offset:2048
	ds_read_b128 v[174:177], v222 offset:3072
	ds_read_b128 v[178:181], v222 offset:4096
	ds_read_b128 v[182:185], v222 offset:5120
	ds_read_b128 v[186:189], v222 offset:6144
	ds_read_b128 v[214:217], v222 offset:7168
	s_waitcnt lgkmcnt(0)
	v_mfma_f32_16x16x32_bf16 v[142:145], v[118:121], v[162:165], 0
	v_mfma_f32_16x16x32_bf16 v[138:141], v[130:133], v[162:165], 0
	v_mfma_f32_16x16x32_bf16 v[110:113], v[118:121], v[170:173], 0
	v_mfma_f32_16x16x32_bf16 v[106:109], v[130:133], v[170:173], 0
	s_waitcnt vmcnt(8)
	s_barrier
	v_mfma_f32_16x16x32_bf16 v[94:97], v[118:121], v[178:181], 0
	v_mfma_f32_16x16x32_bf16 v[90:93], v[130:133], v[178:181], 0
	v_mfma_f32_16x16x32_bf16 v[78:81], v[118:121], v[186:189], 0
	v_mfma_f32_16x16x32_bf16 v[74:77], v[130:133], v[186:189], 0
	v_mfma_f32_16x16x32_bf16 v[142:145], v[122:125], v[166:169], v[142:145]
	v_mfma_f32_16x16x32_bf16 v[138:141], v[134:137], v[166:169], v[138:141]
	v_mfma_f32_16x16x32_bf16 v[110:113], v[122:125], v[174:177], v[110:113]
	v_mfma_f32_16x16x32_bf16 v[106:109], v[134:137], v[174:177], v[106:109]
	v_mfma_f32_16x16x32_bf16 v[94:97], v[122:125], v[182:185], v[94:97]
	v_mfma_f32_16x16x32_bf16 v[90:93], v[134:137], v[182:185], v[90:93]
	v_mfma_f32_16x16x32_bf16 v[78:81], v[122:125], v[214:217], v[78:81]
	v_mfma_f32_16x16x32_bf16 v[74:77], v[134:137], v[214:217], v[74:77]
	v_mfma_f32_16x16x32_bf16 v[126:129], v[146:149], v[162:165], 0
	v_mfma_f32_16x16x32_bf16 v[114:117], v[154:157], v[162:165], 0
	v_mfma_f32_16x16x32_bf16 v[102:105], v[146:149], v[170:173], 0
	v_mfma_f32_16x16x32_bf16 v[98:101], v[154:157], v[170:173], 0
	v_mfma_f32_16x16x32_bf16 v[86:89], v[146:149], v[178:181], 0
	v_mfma_f32_16x16x32_bf16 v[82:85], v[154:157], v[178:181], 0
	v_mfma_f32_16x16x32_bf16 v[70:73], v[146:149], v[186:189], 0
	v_mfma_f32_16x16x32_bf16 v[66:69], v[154:157], v[186:189], 0
	v_mfma_f32_16x16x32_bf16 v[126:129], v[150:153], v[166:169], v[126:129]
	v_mfma_f32_16x16x32_bf16 v[114:117], v[158:161], v[166:169], v[114:117]
	v_mfma_f32_16x16x32_bf16 v[102:105], v[150:153], v[174:177], v[102:105]
	v_mfma_f32_16x16x32_bf16 v[98:101], v[158:161], v[174:177], v[98:101]
	v_mfma_f32_16x16x32_bf16 v[86:89], v[150:153], v[182:185], v[86:89]
	v_mfma_f32_16x16x32_bf16 v[82:85], v[158:161], v[182:185], v[82:85]
	v_mfma_f32_16x16x32_bf16 v[70:73], v[150:153], v[214:217], v[70:73]
	v_mfma_f32_16x16x32_bf16 v[66:69], v[158:161], v[214:217], v[66:69]
	s_barrier
	s_add_i32 s77, s77, s53
	s_mov_b32 m0, s77
	s_nop 0
	global_load_lds_dwordx4 v192, s[42:43]
	ds_read_b128 v[162:165], v222 offset:16384
	ds_read_b128 v[166:169], v222 offset:17408
	s_add_i32 m0, s77, 0x2000
	s_add_u32 s80, s42, 0x80000
	s_addc_u32 s81, s43, 0
	s_add_i32 s77, s79, s53
	global_load_lds_dwordx4 v208, s[42:43]
	ds_read_b128 v[170:173], v222 offset:18432
	ds_read_b128 v[174:177], v222 offset:19456
	s_mov_b32 m0, s77
	s_nop 0
	global_load_lds_dwordx4 v192, s[80:81]
	ds_read_b128 v[178:181], v222 offset:20480
	ds_read_b128 v[182:185], v222 offset:21504
	s_add_i32 m0, s77, 0x2000
	s_nop 0
	global_load_lds_dwordx4 v208, s[80:81]
	ds_read_b128 v[186:189], v222 offset:22528
	ds_read_b128 v[214:217], v222 offset:23552
	s_mov_b32 m0, s56
	s_nop 0
	global_load_lds_dwordx4 v190, s[44:45]
	s_mov_b32 m0, s57
	s_nop 0
	global_load_lds_dwordx4 v206, s[44:45]
	s_waitcnt lgkmcnt(0)
	v_mfma_f32_16x16x32_bf16 v[62:65], v[118:121], v[162:165], 0
	v_mfma_f32_16x16x32_bf16 v[58:61], v[130:133], v[162:165], 0
	v_mfma_f32_16x16x32_bf16 v[46:49], v[118:121], v[170:173], 0
	v_mfma_f32_16x16x32_bf16 v[42:45], v[130:133], v[170:173], 0
	s_waitcnt vmcnt(8)
	s_barrier
; #define PG8_STAGE(bufoff, gbase, voff) do { _Pragma("unroll") for (int _i = 0; _i < 2; ++_i) \
;         __builtin_amdgcn_global_load_lds((const unsigned*)((const char*)(gbase) + (voff)[_i]), (PG8_LAS unsigned*)(lds + (bufoff) + ldsw + _i * 8192), 16, 0, 0); } while (0)
; #define PG8_LDA(dst, b, h) do { _Pragma("unroll") for (int m = 0; m < 4; ++m) _Pragma("unroll") for (int k = 0; k < 2; ++k) dst[m][k] = *(const PG8_LAS bf16x8*)(lds + PG8_SA(b, h) + aoff + m * 2048 + k * 1024); } while (0)
; #define PG8_LDB(dst, b, h) do { _Pragma("unroll") for (int n = 0; n < 2; ++n) _Pragma("unroll") for (int k = 0; k < 2; ++k) dst[n][k] = *(const PG8_LAS bf16x8*)(lds + PG8_SB(b, h) + boff + n * 2048 + k * 1024); } while (0)
; #define PG8_MMA(ai, bj, At, Bt) do { __builtin_amdgcn_s_setprio(1); _Pragma("unroll") for (int m = 0; m < 4; ++m) _Pragma("unroll") for (int n = 0; n < 2; ++n) _Pragma("unroll") for (int k = 0; k < 2; ++k) \
;         acc[ai][bj][m][n] = __builtin_amdgcn_mfma_f32_16x16x32_bf16(Bt[n][k], At[m][k], acc[ai][bj][m][n], 0, 0, 0); __builtin_amdgcn_s_setprio(0); } while (0)
; #define PG8_BAR __builtin_amdgcn_s_barrier()
; template <class Epi, class Sched, bool ALIGN_EPI = false, bool SP2 = false>
; __device__ __forceinline__ void gemm_phase(PG8_LAS unsigned char* lds, const Gemm g, const Sched& S, const Epi& E, const int wave_id) {
;     ...
;             PG8_LDB(B0, 0, 0); PG8_LDB(B1, 0, 1); PG8_SCHED; PG8_LDA(At, 0, 0); PG8_STAGE(PG8_SA(1, 1), a1 + hstep, voffA);
;             PG8_WAIT_V(8); PG8_WAIT_L(0); PG8_BAR; PG8_MMA(0, 0, At, B0); PG8_MMA(0, 1, At, B1); PG8_BAR; PG8_SCHED;
;             PG8_LDA(At, 0, 1); PG8_STAGE(PG8_SB(0, 0), b2, voffB); PG8_STAGE(PG8_SB(0, 1), b2 + hstep, voffB); PG8_STAGE(PG8_SA(0, 0), a2, voffA);
;             PG8_WAIT_V(8); PG8_WAIT_L(0); PG8_BAR; PG8_MMA(1, 0, At, B0); PG8_MMA(1, 1, At, B1); PG8_BAR; PG8_SCHED;
;             PG8_LDB(B0, 1, 0); PG8_LDB(B1, 1, 1); PG8_SCHED; PG8_LDA(At, 1, 0); PG8_STAGE(PG8_SA(0, 1), a2 + hstep, voffA);
;             PG8_WAIT_V(8); PG8_WAIT_L(0); PG8_BAR; PG8_MMA(0, 0, At, B0); PG8_MMA(0, 1, At, B1); PG8_BAR; PG8_SCHED;
;             PG8_LDA(At, 1, 1); PG8_STAGE(PG8_SB(1, 0), b3, voffB); PG8_STAGE(PG8_SB(1, 1), b3 + hstep, voffB); PG8_STAGE(PG8_SA(1, 0), a3, voffA);
;             PG8_WAIT_V(8); PG8_WAIT_L(0); PG8_BAR; PG8_MMA(1, 0, At, B0); PG8_MMA(1, 1, At, B1); PG8_BAR; PG8_SCHED;
	v_mfma_f32_16x16x32_bf16 v[30:33], v[118:121], v[178:181], 0
	v_mfma_f32_16x16x32_bf16 v[26:29], v[130:133], v[178:181], 0
	v_mfma_f32_16x16x32_bf16 v[14:17], v[118:121], v[186:189], 0
	v_mfma_f32_16x16x32_bf16 v[10:13], v[130:133], v[186:189], 0
	v_mfma_f32_16x16x32_bf16 v[62:65], v[122:125], v[166:169], v[62:65]
	v_mfma_f32_16x16x32_bf16 v[58:61], v[134:137], v[166:169], v[58:61]
	v_mfma_f32_16x16x32_bf16 v[46:49], v[122:125], v[174:177], v[46:49]
	v_mfma_f32_16x16x32_bf16 v[42:45], v[134:137], v[174:177], v[42:45]
	v_mfma_f32_16x16x32_bf16 v[30:33], v[122:125], v[182:185], v[30:33]
	v_mfma_f32_16x16x32_bf16 v[26:29], v[134:137], v[182:185], v[26:29]
	v_mfma_f32_16x16x32_bf16 v[14:17], v[122:125], v[214:217], v[14:17]
	v_mfma_f32_16x16x32_bf16 v[10:13], v[134:137], v[214:217], v[10:13]
	v_mfma_f32_16x16x32_bf16 v[54:57], v[146:149], v[162:165], 0
	v_mfma_f32_16x16x32_bf16 v[50:53], v[154:157], v[162:165], 0
	v_mfma_f32_16x16x32_bf16 v[38:41], v[146:149], v[170:173], 0
	v_mfma_f32_16x16x32_bf16 v[34:37], v[154:157], v[170:173], 0
	v_mfma_f32_16x16x32_bf16 v[22:25], v[146:149], v[178:181], 0
	v_mfma_f32_16x16x32_bf16 v[18:21], v[154:157], v[178:181], 0
	v_mfma_f32_16x16x32_bf16 v[6:9], v[146:149], v[186:189], 0
	v_mfma_f32_16x16x32_bf16 v[2:5], v[154:157], v[186:189], 0
	v_mfma_f32_16x16x32_bf16 v[54:57], v[150:153], v[166:169], v[54:57]
	v_mfma_f32_16x16x32_bf16 v[50:53], v[158:161], v[166:169], v[50:53]
	v_mfma_f32_16x16x32_bf16 v[38:41], v[150:153], v[174:177], v[38:41]
	v_mfma_f32_16x16x32_bf16 v[34:37], v[158:161], v[174:177], v[34:37]
	v_mfma_f32_16x16x32_bf16 v[22:25], v[150:153], v[182:185], v[22:25]
	v_mfma_f32_16x16x32_bf16 v[18:21], v[158:161], v[182:185], v[18:21]
	v_mfma_f32_16x16x32_bf16 v[6:9], v[150:153], v[214:217], v[6:9]
	v_mfma_f32_16x16x32_bf16 v[2:5], v[158:161], v[214:217], v[2:5]
	s_barrier
	s_add_i32 s77, 0, 0x18000
	s_add_i32 s79, 0, 0x1c000
	s_add_u32 s44, s44, 0x80000
	s_addc_u32 s45, s45, 0
	s_mov_b32 m0, s64
	s_nop 0
	global_load_lds_dwordx4 v190, s[44:45]
	ds_read_b128 v[118:121], v226 offset:32768
	ds_read_b128 v[122:125], v226 offset:33792
	ds_read_b128 v[130:133], v226 offset:34816
	ds_read_b128 v[134:137], v226 offset:35840
	ds_read_b128 v[146:149], v226 offset:49152
	ds_read_b128 v[150:153], v226 offset:50176
	ds_read_b128 v[154:157], v226 offset:51200
	ds_read_b128 v[158:161], v226 offset:52224
	s_mov_b32 m0, s65
	s_nop 0
	global_load_lds_dwordx4 v206, s[44:45]
	ds_read_b128 v[162:165], v222 offset:32768
	ds_read_b128 v[166:169], v222 offset:33792
	ds_read_b128 v[170:173], v222 offset:34816
	ds_read_b128 v[174:177], v222 offset:35840
	ds_read_b128 v[178:181], v222 offset:36864
	ds_read_b128 v[182:185], v222 offset:37888
	ds_read_b128 v[186:189], v222 offset:38912
	ds_read_b128 v[214:217], v222 offset:39936
	s_waitcnt lgkmcnt(0)
	v_mfma_f32_16x16x32_bf16 v[142:145], v[118:121], v[162:165], v[142:145]
	v_mfma_f32_16x16x32_bf16 v[138:141], v[130:133], v[162:165], v[138:141]
	v_mfma_f32_16x16x32_bf16 v[110:113], v[118:121], v[170:173], v[110:113]
	v_mfma_f32_16x16x32_bf16 v[106:109], v[130:133], v[170:173], v[106:109]
	s_waitcnt vmcnt(8)
	s_barrier
	v_mfma_f32_16x16x32_bf16 v[94:97], v[118:121], v[178:181], v[94:97]
	v_mfma_f32_16x16x32_bf16 v[90:93], v[130:133], v[178:181], v[90:93]
	v_mfma_f32_16x16x32_bf16 v[78:81], v[118:121], v[186:189], v[78:81]
	v_mfma_f32_16x16x32_bf16 v[74:77], v[130:133], v[186:189], v[74:77]
	v_mfma_f32_16x16x32_bf16 v[142:145], v[122:125], v[166:169], v[142:145]
	v_mfma_f32_16x16x32_bf16 v[138:141], v[134:137], v[166:169], v[138:141]
	v_mfma_f32_16x16x32_bf16 v[110:113], v[122:125], v[174:177], v[110:113]
	v_mfma_f32_16x16x32_bf16 v[106:109], v[134:137], v[174:177], v[106:109]
	v_mfma_f32_16x16x32_bf16 v[94:97], v[122:125], v[182:185], v[94:97]
	v_mfma_f32_16x16x32_bf16 v[90:93], v[134:137], v[182:185], v[90:93]
	v_mfma_f32_16x16x32_bf16 v[78:81], v[122:125], v[214:217], v[78:81]
	v_mfma_f32_16x16x32_bf16 v[74:77], v[134:137], v[214:217], v[74:77]
	v_mfma_f32_16x16x32_bf16 v[126:129], v[146:149], v[162:165], v[126:129]
	v_mfma_f32_16x16x32_bf16 v[114:117], v[154:157], v[162:165], v[114:117]
	v_mfma_f32_16x16x32_bf16 v[102:105], v[146:149], v[170:173], v[102:105]
	v_mfma_f32_16x16x32_bf16 v[98:101], v[154:157], v[170:173], v[98:101]
	v_mfma_f32_16x16x32_bf16 v[86:89], v[146:149], v[178:181], v[86:89]
	v_mfma_f32_16x16x32_bf16 v[82:85], v[154:157], v[178:181], v[82:85]
	v_mfma_f32_16x16x32_bf16 v[70:73], v[146:149], v[186:189], v[70:73]
	v_mfma_f32_16x16x32_bf16 v[66:69], v[154:157], v[186:189], v[66:69]
	v_mfma_f32_16x16x32_bf16 v[126:129], v[150:153], v[166:169], v[126:129]
	v_mfma_f32_16x16x32_bf16 v[114:117], v[158:161], v[166:169], v[114:117]
	v_mfma_f32_16x16x32_bf16 v[102:105], v[150:153], v[174:177], v[102:105]
	v_mfma_f32_16x16x32_bf16 v[98:101], v[158:161], v[174:177], v[98:101]
	v_mfma_f32_16x16x32_bf16 v[86:89], v[150:153], v[182:185], v[86:89]
	v_mfma_f32_16x16x32_bf16 v[82:85], v[158:161], v[182:185], v[82:85]
	v_mfma_f32_16x16x32_bf16 v[70:73], v[150:153], v[214:217], v[70:73]
	v_mfma_f32_16x16x32_bf16 v[66:69], v[158:161], v[214:217], v[66:69]
	s_barrier
; #define PG8_STAGE(bufoff, gbase, voff) do { _Pragma("unroll") for (int _i = 0; _i < 2; ++_i) \
;         __builtin_amdgcn_global_load_lds((const unsigned*)((const char*)(gbase) + (voff)[_i]), (PG8_LAS unsigned*)(lds + (bufoff) + ldsw + _i * 8192), 16, 0, 0); } while (0)
; #define PG8_LDA(dst, b, h) do { _Pragma("unroll") for (int m = 0; m < 4; ++m) _Pragma("unroll") for (int k = 0; k < 2; ++k) dst[m][k] = *(const PG8_LAS bf16x8*)(lds + PG8_SA(b, h) + aoff + m * 2048 + k * 1024); } while (0)
; #define PG8_WAIT_V(n) asm volatile("s_waitcnt vmcnt(" #n ")" ::: "memory")
; #define PG8_WAIT_L(n) asm volatile("s_waitcnt lgkmcnt(" #n ")" ::: "memory")
; #define PG8_BAR __builtin_amdgcn_s_barrier()
; template <class Epi, class Sched, bool ALIGN_EPI = false, bool SP2 = false>
; __device__ __forceinline__ void gemm_phase(PG8_LAS unsigned char* lds, const Gemm g, const Sched& S, const Epi& E, const int wave_id) {
;     ...
;         for (int t = 0; t < nt; t += 2) {
;             const bool last = (t == nt - 2);
;             const char* a1 = cA + (size_t)(t + 1) * kstep;
;             const char* a2 = last ? nA : cA + (size_t)(t + 2) * kstep; const char* b2 = last ? nB : cB + (size_t)(t + 2) * kstep;
;             const char* a3 = a2 + kstep; const char* b3 = b2 + kstep;
;             if (last && has_next) S.a_ready(nxt);
;             if constexpr (SP2) {
;             PG8_LDB(B0, 0, 0); PG8_LDB(B1, 0, 1); PG8_SCHED; PG8_LDA(At, 0, 0); PG8_STAGE(PG8_SA(1, 1), a1 + hstep, voffA);
;             PG8_WAIT_V(8); PG8_WAIT_L(0); PG8_BAR; PG8_MMA(0, 0, At, B0); PG8_MMA(0, 1, At, B1); PG8_BAR; PG8_SCHED;
;             PG8_LDA(At, 0, 1); PG8_STAGE(PG8_SB(0, 0), b2, voffB); PG8_STAGE(PG8_SB(0, 1), b2 + hstep, voffB); PG8_STAGE(PG8_SA(0, 0), a2, voffA);
;             PG8_WAIT_V(8); PG8_WAIT_L(0); PG8_BAR; PG8_MMA(1, 0, At, B0); PG8_MMA(1, 1, At, B1); PG8_BAR; PG8_SCHED;
;             PG8_LDB(B0, 1, 0); PG8_LDB(B1, 1, 1); PG8_SCHED; PG8_LDA(At, 1, 0); PG8_STAGE(PG8_SA(0, 1), a2 + hstep, voffA);
;             PG8_WAIT_V(8); PG8_WAIT_L(0); PG8_BAR; PG8_MMA(0, 0, At, B0); PG8_MMA(0, 1, At, B1); PG8_BAR; PG8_SCHED;
;             PG8_LDA(At, 1, 1); PG8_STAGE(PG8_SB(1, 0), b3, voffB); PG8_STAGE(PG8_SB(1, 1), b3 + hstep, voffB); PG8_STAGE(PG8_SA(1, 0), a3, voffA);
;             PG8_WAIT_V(8); PG8_WAIT_L(0); PG8_BAR; PG8_MMA(1, 0, At, B0); PG8_MMA(1, 1, At, B1); PG8_BAR; PG8_SCHED;
	s_add_u32 vcc_lo, s44, 0xfff80080
	s_addc_u32 vcc_hi, s45, -1
	s_mov_b32 m0, s70
	s_nop 0
	global_load_lds_dwordx4 v190, vcc
	ds_read_b128 v[162:165], v222 offset:49152
	ds_read_b128 v[166:169], v222 offset:50176
	s_mov_b32 m0, s71
	s_add_i32 s44, s77, s53
	global_load_lds_dwordx4 v206, vcc
	ds_read_b128 v[170:173], v222 offset:51200
	ds_read_b128 v[174:177], v222 offset:52224
	s_add_u32 vcc_lo, s42, 0x80
	s_addc_u32 vcc_hi, s43, 0
	s_mov_b32 m0, s44
	s_nop 0
	global_load_lds_dwordx4 v192, vcc
	ds_read_b128 v[178:181], v222 offset:53248
	ds_read_b128 v[182:185], v222 offset:54272
	s_add_i32 m0, s44, 0x2000
	s_add_u32 s42, s42, 0x80080
	s_addc_u32 s43, s43, 0
	global_load_lds_dwordx4 v208, vcc
	ds_read_b128 v[186:189], v222 offset:55296
	ds_read_b128 v[214:217], v222 offset:56320
	s_add_i32 s44, s79, s53
	s_mov_b32 m0, s44
	s_nop 0
	global_load_lds_dwordx4 v192, s[42:43]
	s_add_i32 m0, s44, 0x2000
	s_nop 0
	global_load_lds_dwordx4 v208, s[42:43]
	s_waitcnt lgkmcnt(0)
	v_mfma_f32_16x16x32_bf16 v[62:65], v[118:121], v[162:165], v[62:65]
	v_mfma_f32_16x16x32_bf16 v[58:61], v[130:133], v[162:165], v[58:61]
	v_mfma_f32_16x16x32_bf16 v[46:49], v[118:121], v[170:173], v[46:49]
	v_mfma_f32_16x16x32_bf16 v[42:45], v[130:133], v[170:173], v[42:45]
	s_waitcnt vmcnt(8)
	s_barrier
	v_mfma_f32_16x16x32_bf16 v[30:33], v[118:121], v[178:181], v[30:33]
	v_mfma_f32_16x16x32_bf16 v[26:29], v[130:133], v[178:181], v[26:29]
	v_mfma_f32_16x16x32_bf16 v[14:17], v[118:121], v[186:189], v[14:17]
	v_mfma_f32_16x16x32_bf16 v[10:13], v[130:133], v[186:189], v[10:13]
	v_mfma_f32_16x16x32_bf16 v[62:65], v[122:125], v[166:169], v[62:65]
	v_mfma_f32_16x16x32_bf16 v[58:61], v[134:137], v[166:169], v[58:61]
	v_mfma_f32_16x16x32_bf16 v[46:49], v[122:125], v[174:177], v[46:49]
	v_mfma_f32_16x16x32_bf16 v[42:45], v[134:137], v[174:177], v[42:45]
	v_mfma_f32_16x16x32_bf16 v[30:33], v[122:125], v[182:185], v[30:33]
	v_mfma_f32_16x16x32_bf16 v[26:29], v[134:137], v[182:185], v[26:29]
	v_mfma_f32_16x16x32_bf16 v[14:17], v[122:125], v[214:217], v[14:17]
	v_mfma_f32_16x16x32_bf16 v[10:13], v[134:137], v[214:217], v[10:13]
	v_mfma_f32_16x16x32_bf16 v[54:57], v[146:149], v[162:165], v[54:57]
	v_mfma_f32_16x16x32_bf16 v[50:53], v[154:157], v[162:165], v[50:53]
	v_mfma_f32_16x16x32_bf16 v[38:41], v[146:149], v[170:173], v[38:41]
	v_mfma_f32_16x16x32_bf16 v[34:37], v[154:157], v[170:173], v[34:37]
	v_mfma_f32_16x16x32_bf16 v[22:25], v[146:149], v[178:181], v[22:25]
	v_mfma_f32_16x16x32_bf16 v[18:21], v[154:157], v[178:181], v[18:21]
	v_mfma_f32_16x16x32_bf16 v[6:9], v[146:149], v[186:189], v[6:9]
	v_mfma_f32_16x16x32_bf16 v[2:5], v[154:157], v[186:189], v[2:5]
	v_mfma_f32_16x16x32_bf16 v[54:57], v[150:153], v[166:169], v[54:57]
	v_mfma_f32_16x16x32_bf16 v[50:53], v[158:161], v[166:169], v[50:53]
	v_mfma_f32_16x16x32_bf16 v[38:41], v[150:153], v[174:177], v[38:41]
	v_mfma_f32_16x16x32_bf16 v[34:37], v[158:161], v[174:177], v[34:37]
	v_mfma_f32_16x16x32_bf16 v[22:25], v[150:153], v[182:185], v[22:25]
	v_mfma_f32_16x16x32_bf16 v[18:21], v[158:161], v[182:185], v[18:21]
	v_mfma_f32_16x16x32_bf16 v[6:9], v[150:153], v[214:217], v[6:9]
	v_mfma_f32_16x16x32_bf16 v[2:5], v[158:161], v[214:217], v[2:5]
	s_barrier
	s_add_i32 s76, s76, 2
	s_add_u32 s40, s40, 0x100
	s_addc_u32 s41, s41, 0
	s_add_u32 s74, s74, 0x100
	s_addc_u32 s75, s75, 0
	s_cmp_gt_u32 s76, 29
	s_cbranch_scc1 .Lpeel_exit_g2
.LBB0_524:
	s_add_u32 s42, s40, 0xfff80080
	s_addc_u32 s43, s41, -1
	s_add_i32 s77, 0, 0x10000
	s_cmp_eq_u32 s76, 28
	s_cselect_b32 s45, s15, s43
	s_cselect_b32 s44, s21, s42
	s_cselect_b32 s43, s13, s75
	s_cselect_b32 s42, s73, s74
	s_add_i32 s79, 0, 0x14000
	s_add_i32 m0, s56, 0xc000
	s_nop 0
	global_load_lds_dwordx4 v210, s[40:41]
	ds_read_b128 v[118:121], v226
	ds_read_b128 v[122:125], v226 offset:1024
	ds_read_b128 v[130:133], v226 offset:2048
	ds_read_b128 v[134:137], v226 offset:3072
	ds_read_b128 v[146:149], v226 offset:16384
	ds_read_b128 v[150:153], v226 offset:17408
	ds_read_b128 v[154:157], v226 offset:18432
	ds_read_b128 v[158:161], v226 offset:19456
	s_add_i32 m0, s56, 0xe000
	s_nop 0
	global_load_lds_dwordx4 v212, s[40:41]
	ds_read_b128 v[162:165], v222
	ds_read_b128 v[166:169], v222 offset:1024
	ds_read_b128 v[170:173], v222 offset:2048
	ds_read_b128 v[174:177], v222 offset:3072
	ds_read_b128 v[178:181], v222 offset:4096
	ds_read_b128 v[182:185], v222 offset:5120
	ds_read_b128 v[186:189], v222 offset:6144
	ds_read_b128 v[214:217], v222 offset:7168
	s_waitcnt lgkmcnt(0)
	v_mfma_f32_16x16x32_bf16 v[142:145], v[118:121], v[162:165], v[142:145]
	v_mfma_f32_16x16x32_bf16 v[138:141], v[130:133], v[162:165], v[138:141]
	v_mfma_f32_16x16x32_bf16 v[110:113], v[118:121], v[170:173], v[110:113]
	v_mfma_f32_16x16x32_bf16 v[106:109], v[130:133], v[170:173], v[106:109]
	s_waitcnt vmcnt(8)
	s_barrier
; #define PG8_STAGE(bufoff, gbase, voff) do { _Pragma("unroll") for (int _i = 0; _i < 2; ++_i) \
;         __builtin_amdgcn_global_load_lds((const unsigned*)((const char*)(gbase) + (voff)[_i]), (PG8_LAS unsigned*)(lds + (bufoff) + ldsw + _i * 8192), 16, 0, 0); } while (0)
; #define PG8_LDA(dst, b, h) do { _Pragma("unroll") for (int m = 0; m < 4; ++m) _Pragma("unroll") for (int k = 0; k < 2; ++k) dst[m][k] = *(const PG8_LAS bf16x8*)(lds + PG8_SA(b, h) + aoff + m * 2048 + k * 1024); } while (0)
; #define PG8_LDB(dst, b, h) do { _Pragma("unroll") for (int n = 0; n < 2; ++n) _Pragma("unroll") for (int k = 0; k < 2; ++k) dst[n][k] = *(const PG8_LAS bf16x8*)(lds + PG8_SB(b, h) + boff + n * 2048 + k * 1024); } while (0)
; #define PG8_MMA(ai, bj, At, Bt) do { __builtin_amdgcn_s_setprio(1); _Pragma("unroll") for (int m = 0; m < 4; ++m) _Pragma("unroll") for (int n = 0; n < 2; ++n) _Pragma("unroll") for (int k = 0; k < 2; ++k) \
;         acc[ai][bj][m][n] = __builtin_amdgcn_mfma_f32_16x16x32_bf16(Bt[n][k], At[m][k], acc[ai][bj][m][n], 0, 0, 0); __builtin_amdgcn_s_setprio(0); } while (0)
; #define PG8_BAR __builtin_amdgcn_s_barrier()
; template <class Epi, class Sched, bool ALIGN_EPI = false, bool SP2 = false>
; __device__ __forceinline__ void gemm_phase(PG8_LAS unsigned char* lds, const Gemm g, const Sched& S, const Epi& E, const int wave_id) {
;     ...
;             PG8_LDB(B0, 0, 0); PG8_LDB(B1, 0, 1); PG8_SCHED; PG8_LDA(At, 0, 0); PG8_STAGE(PG8_SA(1, 1), a1 + hstep, voffA);
;             PG8_WAIT_V(8); PG8_WAIT_L(0); PG8_BAR; PG8_MMA(0, 0, At, B0); PG8_MMA(0, 1, At, B1); PG8_BAR; PG8_SCHED;
;             PG8_LDA(At, 0, 1); PG8_STAGE(PG8_SB(0, 0), b2, voffB); PG8_STAGE(PG8_SB(0, 1), b2 + hstep, voffB); PG8_STAGE(PG8_SA(0, 0), a2, voffA);
;             PG8_WAIT_V(8); PG8_WAIT_L(0); PG8_BAR; PG8_MMA(1, 0, At, B0); PG8_MMA(1, 1, At, B1); PG8_BAR; PG8_SCHED;
;             PG8_LDB(B0, 1, 0); PG8_LDB(B1, 1, 1); PG8_SCHED; PG8_LDA(At, 1, 0); PG8_STAGE(PG8_SA(0, 1), a2 + hstep, voffA);
;             PG8_WAIT_V(8); PG8_WAIT_L(0); PG8_BAR; PG8_MMA(0, 0, At, B0); PG8_MMA(0, 1, At, B1); PG8_BAR; PG8_SCHED;
;             PG8_LDA(At, 1, 1); PG8_STAGE(PG8_SB(1, 0), b3, voffB); PG8_STAGE(PG8_SB(1, 1), b3 + hstep, voffB); PG8_STAGE(PG8_SA(1, 0), a3, voffA);
;             PG8_WAIT_V(8); PG8_WAIT_L(0); PG8_BAR; PG8_MMA(1, 0, At, B0); PG8_MMA(1, 1, At, B1); PG8_BAR; PG8_SCHED;
	v_mfma_f32_16x16x32_bf16 v[94:97], v[118:121], v[178:181], v[94:97]
	v_mfma_f32_16x16x32_bf16 v[90:93], v[130:133], v[178:181], v[90:93]
	v_mfma_f32_16x16x32_bf16 v[78:81], v[118:121], v[186:189], v[78:81]
	v_mfma_f32_16x16x32_bf16 v[74:77], v[130:133], v[186:189], v[74:77]
	v_mfma_f32_16x16x32_bf16 v[142:145], v[122:125], v[166:169], v[142:145]
	v_mfma_f32_16x16x32_bf16 v[138:141], v[134:137], v[166:169], v[138:141]
	v_mfma_f32_16x16x32_bf16 v[110:113], v[122:125], v[174:177], v[110:113]
	v_mfma_f32_16x16x32_bf16 v[106:109], v[134:137], v[174:177], v[106:109]
	v_mfma_f32_16x16x32_bf16 v[94:97], v[122:125], v[182:185], v[94:97]
	v_mfma_f32_16x16x32_bf16 v[90:93], v[134:137], v[182:185], v[90:93]
	v_mfma_f32_16x16x32_bf16 v[78:81], v[122:125], v[214:217], v[78:81]
	v_mfma_f32_16x16x32_bf16 v[74:77], v[134:137], v[214:217], v[74:77]
	v_mfma_f32_16x16x32_bf16 v[126:129], v[146:149], v[162:165], v[126:129]
	v_mfma_f32_16x16x32_bf16 v[114:117], v[154:157], v[162:165], v[114:117]
	v_mfma_f32_16x16x32_bf16 v[102:105], v[146:149], v[170:173], v[102:105]
	v_mfma_f32_16x16x32_bf16 v[98:101], v[154:157], v[170:173], v[98:101]
	v_mfma_f32_16x16x32_bf16 v[86:89], v[146:149], v[178:181], v[86:89]
	v_mfma_f32_16x16x32_bf16 v[82:85], v[154:157], v[178:181], v[82:85]
	v_mfma_f32_16x16x32_bf16 v[70:73], v[146:149], v[186:189], v[70:73]
	v_mfma_f32_16x16x32_bf16 v[66:69], v[154:157], v[186:189], v[66:69]
	v_mfma_f32_16x16x32_bf16 v[126:129], v[150:153], v[166:169], v[126:129]
	v_mfma_f32_16x16x32_bf16 v[114:117], v[158:161], v[166:169], v[114:117]
	v_mfma_f32_16x16x32_bf16 v[102:105], v[150:153], v[174:177], v[102:105]
	v_mfma_f32_16x16x32_bf16 v[98:101], v[158:161], v[174:177], v[98:101]
	v_mfma_f32_16x16x32_bf16 v[86:89], v[150:153], v[182:185], v[86:89]
	v_mfma_f32_16x16x32_bf16 v[82:85], v[158:161], v[182:185], v[82:85]
	v_mfma_f32_16x16x32_bf16 v[70:73], v[150:153], v[214:217], v[70:73]
	v_mfma_f32_16x16x32_bf16 v[66:69], v[158:161], v[214:217], v[66:69]
	s_barrier
	s_add_i32 s77, s77, s53
	s_mov_b32 m0, s77
	s_nop 0
	global_load_lds_dwordx4 v192, s[42:43]
	ds_read_b128 v[162:165], v222 offset:16384
	ds_read_b128 v[166:169], v222 offset:17408
	s_add_i32 m0, s77, 0x2000
	s_add_u32 s80, s42, 0x80000
	s_addc_u32 s81, s43, 0
	s_add_i32 s77, s79, s53
	global_load_lds_dwordx4 v208, s[42:43]
	ds_read_b128 v[170:173], v222 offset:18432
	ds_read_b128 v[174:177], v222 offset:19456
	s_mov_b32 m0, s77
	s_nop 0
	global_load_lds_dwordx4 v192, s[80:81]
	ds_read_b128 v[178:181], v222 offset:20480
	ds_read_b128 v[182:185], v222 offset:21504
	s_add_i32 m0, s77, 0x2000
	s_nop 0
	global_load_lds_dwordx4 v208, s[80:81]
	ds_read_b128 v[186:189], v222 offset:22528
	ds_read_b128 v[214:217], v222 offset:23552
	s_mov_b32 m0, s56
	s_nop 0
	global_load_lds_dwordx4 v190, s[44:45]
	s_mov_b32 m0, s57
	s_nop 0
	global_load_lds_dwordx4 v206, s[44:45]
	s_waitcnt lgkmcnt(0)
	v_mfma_f32_16x16x32_bf16 v[62:65], v[118:121], v[162:165], v[62:65]
	v_mfma_f32_16x16x32_bf16 v[58:61], v[130:133], v[162:165], v[58:61]
	v_mfma_f32_16x16x32_bf16 v[46:49], v[118:121], v[170:173], v[46:49]
	v_mfma_f32_16x16x32_bf16 v[42:45], v[130:133], v[170:173], v[42:45]
	s_waitcnt vmcnt(8)
	s_barrier
	v_mfma_f32_16x16x32_bf16 v[30:33], v[118:121], v[178:181], v[30:33]
	v_mfma_f32_16x16x32_bf16 v[26:29], v[130:133], v[178:181], v[26:29]
	v_mfma_f32_16x16x32_bf16 v[14:17], v[118:121], v[186:189], v[14:17]
	v_mfma_f32_16x16x32_bf16 v[10:13], v[130:133], v[186:189], v[10:13]
	v_mfma_f32_16x16x32_bf16 v[62:65], v[122:125], v[166:169], v[62:65]
	v_mfma_f32_16x16x32_bf16 v[58:61], v[134:137], v[166:169], v[58:61]
	v_mfma_f32_16x16x32_bf16 v[46:49], v[122:125], v[174:177], v[46:49]
	v_mfma_f32_16x16x32_bf16 v[42:45], v[134:137], v[174:177], v[42:45]
	v_mfma_f32_16x16x32_bf16 v[30:33], v[122:125], v[182:185], v[30:33]
	v_mfma_f32_16x16x32_bf16 v[26:29], v[134:137], v[182:185], v[26:29]
	v_mfma_f32_16x16x32_bf16 v[14:17], v[122:125], v[214:217], v[14:17]
	v_mfma_f32_16x16x32_bf16 v[10:13], v[134:137], v[214:217], v[10:13]
	v_mfma_f32_16x16x32_bf16 v[54:57], v[146:149], v[162:165], v[54:57]
	v_mfma_f32_16x16x32_bf16 v[50:53], v[154:157], v[162:165], v[50:53]
	v_mfma_f32_16x16x32_bf16 v[38:41], v[146:149], v[170:173], v[38:41]
	v_mfma_f32_16x16x32_bf16 v[34:37], v[154:157], v[170:173], v[34:37]
	v_mfma_f32_16x16x32_bf16 v[22:25], v[146:149], v[178:181], v[22:25]
	v_mfma_f32_16x16x32_bf16 v[18:21], v[154:157], v[178:181], v[18:21]
	v_mfma_f32_16x16x32_bf16 v[6:9], v[146:149], v[186:189], v[6:9]
	v_mfma_f32_16x16x32_bf16 v[2:5], v[154:157], v[186:189], v[2:5]
	v_mfma_f32_16x16x32_bf16 v[54:57], v[150:153], v[166:169], v[54:57]
	v_mfma_f32_16x16x32_bf16 v[50:53], v[158:161], v[166:169], v[50:53]
	v_mfma_f32_16x16x32_bf16 v[38:41], v[150:153], v[174:177], v[38:41]
	v_mfma_f32_16x16x32_bf16 v[34:37], v[158:161], v[174:177], v[34:37]
	v_mfma_f32_16x16x32_bf16 v[22:25], v[150:153], v[182:185], v[22:25]
	v_mfma_f32_16x16x32_bf16 v[18:21], v[158:161], v[182:185], v[18:21]
	v_mfma_f32_16x16x32_bf16 v[6:9], v[150:153], v[214:217], v[6:9]
	v_mfma_f32_16x16x32_bf16 v[2:5], v[158:161], v[214:217], v[2:5]
	s_barrier
; #define PG8_STAGE(bufoff, gbase, voff) do { _Pragma("unroll") for (int _i = 0; _i < 2; ++_i) \
;         __builtin_amdgcn_global_load_lds((const unsigned*)((const char*)(gbase) + (voff)[_i]), (PG8_LAS unsigned*)(lds + (bufoff) + ldsw + _i * 8192), 16, 0, 0); } while (0)
; #define PG8_LDA(dst, b, h) do { _Pragma("unroll") for (int m = 0; m < 4; ++m) _Pragma("unroll") for (int k = 0; k < 2; ++k) dst[m][k] = *(const PG8_LAS bf16x8*)(lds + PG8_SA(b, h) + aoff + m * 2048 + k * 1024); } while (0)
; #define PG8_LDB(dst, b, h) do { _Pragma("unroll") for (int n = 0; n < 2; ++n) _Pragma("unroll") for (int k = 0; k < 2; ++k) dst[n][k] = *(const PG8_LAS bf16x8*)(lds + PG8_SB(b, h) + boff + n * 2048 + k * 1024); } while (0)
; #define PG8_MMA(ai, bj, At, Bt) do { __builtin_amdgcn_s_setprio(1); _Pragma("unroll") for (int m = 0; m < 4; ++m) _Pragma("unroll") for (int n = 0; n < 2; ++n) _Pragma("unroll") for (int k = 0; k < 2; ++k) \
;         acc[ai][bj][m][n] = __builtin_amdgcn_mfma_f32_16x16x32_bf16(Bt[n][k], At[m][k], acc[ai][bj][m][n], 0, 0, 0); __builtin_amdgcn_s_setprio(0); } while (0)
; #define PG8_BAR __builtin_amdgcn_s_barrier()
; template <class Epi, class Sched, bool ALIGN_EPI = false, bool SP2 = false>
; __device__ __forceinline__ void gemm_phase(PG8_LAS unsigned char* lds, const Gemm g, const Sched& S, const Epi& E, const int wave_id) {
;     ...
;             PG8_LDB(B0, 0, 0); PG8_LDB(B1, 0, 1); PG8_SCHED; PG8_LDA(At, 0, 0); PG8_STAGE(PG8_SA(1, 1), a1 + hstep, voffA);
;             PG8_WAIT_V(8); PG8_WAIT_L(0); PG8_BAR; PG8_MMA(0, 0, At, B0); PG8_MMA(0, 1, At, B1); PG8_BAR; PG8_SCHED;
;             PG8_LDA(At, 0, 1); PG8_STAGE(PG8_SB(0, 0), b2, voffB); PG8_STAGE(PG8_SB(0, 1), b2 + hstep, voffB); PG8_STAGE(PG8_SA(0, 0), a2, voffA);
;             PG8_WAIT_V(8); PG8_WAIT_L(0); PG8_BAR; PG8_MMA(1, 0, At, B0); PG8_MMA(1, 1, At, B1); PG8_BAR; PG8_SCHED;
;             PG8_LDB(B0, 1, 0); PG8_LDB(B1, 1, 1); PG8_SCHED; PG8_LDA(At, 1, 0); PG8_STAGE(PG8_SA(0, 1), a2 + hstep, voffA);
;             PG8_WAIT_V(8); PG8_WAIT_L(0); PG8_BAR; PG8_MMA(0, 0, At, B0); PG8_MMA(0, 1, At, B1); PG8_BAR; PG8_SCHED;
;             PG8_LDA(At, 1, 1); PG8_STAGE(PG8_SB(1, 0), b3, voffB); PG8_STAGE(PG8_SB(1, 1), b3 + hstep, voffB); PG8_STAGE(PG8_SA(1, 0), a3, voffA);
;             PG8_WAIT_V(8); PG8_WAIT_L(0); PG8_BAR; PG8_MMA(1, 0, At, B0); PG8_MMA(1, 1, At, B1); PG8_BAR; PG8_SCHED;
	s_add_i32 s77, 0, 0x18000
	s_add_i32 s79, 0, 0x1c000
	s_add_u32 s44, s44, 0x80000
	s_addc_u32 s45, s45, 0
	s_mov_b32 m0, s64
	s_nop 0
	global_load_lds_dwordx4 v190, s[44:45]
	ds_read_b128 v[118:121], v226 offset:32768
	ds_read_b128 v[122:125], v226 offset:33792
	ds_read_b128 v[130:133], v226 offset:34816
	ds_read_b128 v[134:137], v226 offset:35840
	ds_read_b128 v[146:149], v226 offset:49152
	ds_read_b128 v[150:153], v226 offset:50176
	ds_read_b128 v[154:157], v226 offset:51200
	ds_read_b128 v[158:161], v226 offset:52224
	s_mov_b32 m0, s65
	s_nop 0
	global_load_lds_dwordx4 v206, s[44:45]
	ds_read_b128 v[162:165], v222 offset:32768
	ds_read_b128 v[166:169], v222 offset:33792
	ds_read_b128 v[170:173], v222 offset:34816
	ds_read_b128 v[174:177], v222 offset:35840
	ds_read_b128 v[178:181], v222 offset:36864
	ds_read_b128 v[182:185], v222 offset:37888
	ds_read_b128 v[186:189], v222 offset:38912
	ds_read_b128 v[214:217], v222 offset:39936
	s_waitcnt lgkmcnt(0)
	v_mfma_f32_16x16x32_bf16 v[142:145], v[118:121], v[162:165], v[142:145]
	v_mfma_f32_16x16x32_bf16 v[138:141], v[130:133], v[162:165], v[138:141]
	v_mfma_f32_16x16x32_bf16 v[110:113], v[118:121], v[170:173], v[110:113]
	v_mfma_f32_16x16x32_bf16 v[106:109], v[130:133], v[170:173], v[106:109]
	s_waitcnt vmcnt(8)
	s_barrier
	v_mfma_f32_16x16x32_bf16 v[94:97], v[118:121], v[178:181], v[94:97]
	v_mfma_f32_16x16x32_bf16 v[90:93], v[130:133], v[178:181], v[90:93]
	v_mfma_f32_16x16x32_bf16 v[78:81], v[118:121], v[186:189], v[78:81]
	v_mfma_f32_16x16x32_bf16 v[74:77], v[130:133], v[186:189], v[74:77]
	v_mfma_f32_16x16x32_bf16 v[142:145], v[122:125], v[166:169], v[142:145]
	v_mfma_f32_16x16x32_bf16 v[138:141], v[134:137], v[166:169], v[138:141]
	v_mfma_f32_16x16x32_bf16 v[110:113], v[122:125], v[174:177], v[110:113]
	v_mfma_f32_16x16x32_bf16 v[106:109], v[134:137], v[174:177], v[106:109]
	v_mfma_f32_16x16x32_bf16 v[94:97], v[122:125], v[182:185], v[94:97]
	v_mfma_f32_16x16x32_bf16 v[90:93], v[134:137], v[182:185], v[90:93]
	v_mfma_f32_16x16x32_bf16 v[78:81], v[122:125], v[214:217], v[78:81]
	v_mfma_f32_16x16x32_bf16 v[74:77], v[134:137], v[214:217], v[74:77]
	v_mfma_f32_16x16x32_bf16 v[126:129], v[146:149], v[162:165], v[126:129]
	v_mfma_f32_16x16x32_bf16 v[114:117], v[154:157], v[162:165], v[114:117]
	v_mfma_f32_16x16x32_bf16 v[102:105], v[146:149], v[170:173], v[102:105]
	v_mfma_f32_16x16x32_bf16 v[98:101], v[154:157], v[170:173], v[98:101]
	v_mfma_f32_16x16x32_bf16 v[86:89], v[146:149], v[178:181], v[86:89]
	v_mfma_f32_16x16x32_bf16 v[82:85], v[154:157], v[178:181], v[82:85]
	v_mfma_f32_16x16x32_bf16 v[70:73], v[146:149], v[186:189], v[70:73]
	v_mfma_f32_16x16x32_bf16 v[66:69], v[154:157], v[186:189], v[66:69]
	v_mfma_f32_16x16x32_bf16 v[126:129], v[150:153], v[166:169], v[126:129]
	v_mfma_f32_16x16x32_bf16 v[114:117], v[158:161], v[166:169], v[114:117]
	v_mfma_f32_16x16x32_bf16 v[102:105], v[150:153], v[174:177], v[102:105]
	v_mfma_f32_16x16x32_bf16 v[98:101], v[158:161], v[174:177], v[98:101]
	v_mfma_f32_16x16x32_bf16 v[86:89], v[150:153], v[182:185], v[86:89]
	v_mfma_f32_16x16x32_bf16 v[82:85], v[158:161], v[182:185], v[82:85]
	v_mfma_f32_16x16x32_bf16 v[70:73], v[150:153], v[214:217], v[70:73]
	v_mfma_f32_16x16x32_bf16 v[66:69], v[158:161], v[214:217], v[66:69]
	s_barrier
	s_add_u32 vcc_lo, s44, 0xfff80080
	s_addc_u32 vcc_hi, s45, -1
	s_mov_b32 m0, s70
	s_nop 0
	global_load_lds_dwordx4 v190, vcc
	ds_read_b128 v[162:165], v222 offset:49152
	ds_read_b128 v[166:169], v222 offset:50176
	s_mov_b32 m0, s71
	s_add_i32 s44, s77, s53
	global_load_lds_dwordx4 v206, vcc
	ds_read_b128 v[170:173], v222 offset:51200
	ds_read_b128 v[174:177], v222 offset:52224
	s_add_u32 vcc_lo, s42, 0x80
	s_addc_u32 vcc_hi, s43, 0
	s_mov_b32 m0, s44
	s_nop 0
	global_load_lds_dwordx4 v192, vcc
	ds_read_b128 v[178:181], v222 offset:53248
	ds_read_b128 v[182:185], v222 offset:54272
	s_add_i32 m0, s44, 0x2000
	s_add_u32 s42, s42, 0x80080
	s_addc_u32 s43, s43, 0
	global_load_lds_dwordx4 v208, vcc
	ds_read_b128 v[186:189], v222 offset:55296
	ds_read_b128 v[214:217], v222 offset:56320
	s_add_i32 s44, s79, s53
	s_mov_b32 m0, s44
	s_nop 0
	global_load_lds_dwordx4 v192, s[42:43]
	s_add_i32 m0, s44, 0x2000
	s_nop 0
	global_load_lds_dwordx4 v208, s[42:43]
	s_waitcnt lgkmcnt(0)
	v_mfma_f32_16x16x32_bf16 v[62:65], v[118:121], v[162:165], v[62:65]
	v_mfma_f32_16x16x32_bf16 v[58:61], v[130:133], v[162:165], v[58:61]
	v_mfma_f32_16x16x32_bf16 v[46:49], v[118:121], v[170:173], v[46:49]
	v_mfma_f32_16x16x32_bf16 v[42:45], v[130:133], v[170:173], v[42:45]
	s_waitcnt vmcnt(8)
	s_barrier
	v_mfma_f32_16x16x32_bf16 v[30:33], v[118:121], v[178:181], v[30:33]
	v_mfma_f32_16x16x32_bf16 v[26:29], v[130:133], v[178:181], v[26:29]
	v_mfma_f32_16x16x32_bf16 v[14:17], v[118:121], v[186:189], v[14:17]
	v_mfma_f32_16x16x32_bf16 v[10:13], v[130:133], v[186:189], v[10:13]
	v_mfma_f32_16x16x32_bf16 v[62:65], v[122:125], v[166:169], v[62:65]
	v_mfma_f32_16x16x32_bf16 v[58:61], v[134:137], v[166:169], v[58:61]
	v_mfma_f32_16x16x32_bf16 v[46:49], v[122:125], v[174:177], v[46:49]
	v_mfma_f32_16x16x32_bf16 v[42:45], v[134:137], v[174:177], v[42:45]
	v_mfma_f32_16x16x32_bf16 v[30:33], v[122:125], v[182:185], v[30:33]
	v_mfma_f32_16x16x32_bf16 v[26:29], v[134:137], v[182:185], v[26:29]
	v_mfma_f32_16x16x32_bf16 v[14:17], v[122:125], v[214:217], v[14:17]
	v_mfma_f32_16x16x32_bf16 v[10:13], v[134:137], v[214:217], v[10:13]
	v_mfma_f32_16x16x32_bf16 v[54:57], v[146:149], v[162:165], v[54:57]
	v_mfma_f32_16x16x32_bf16 v[50:53], v[154:157], v[162:165], v[50:53]
	v_mfma_f32_16x16x32_bf16 v[38:41], v[146:149], v[170:173], v[38:41]
	v_mfma_f32_16x16x32_bf16 v[34:37], v[154:157], v[170:173], v[34:37]
	v_mfma_f32_16x16x32_bf16 v[22:25], v[146:149], v[178:181], v[22:25]
	v_mfma_f32_16x16x32_bf16 v[18:21], v[154:157], v[178:181], v[18:21]
	v_mfma_f32_16x16x32_bf16 v[6:9], v[146:149], v[186:189], v[6:9]
	v_mfma_f32_16x16x32_bf16 v[2:5], v[154:157], v[186:189], v[2:5]
	v_mfma_f32_16x16x32_bf16 v[54:57], v[150:153], v[166:169], v[54:57]
	v_mfma_f32_16x16x32_bf16 v[50:53], v[158:161], v[166:169], v[50:53]
	v_mfma_f32_16x16x32_bf16 v[38:41], v[150:153], v[174:177], v[38:41]
	v_mfma_f32_16x16x32_bf16 v[34:37], v[158:161], v[174:177], v[34:37]
	v_mfma_f32_16x16x32_bf16 v[22:25], v[150:153], v[182:185], v[22:25]
	v_mfma_f32_16x16x32_bf16 v[18:21], v[158:161], v[182:185], v[18:21]
	v_mfma_f32_16x16x32_bf16 v[6:9], v[150:153], v[214:217], v[6:9]
	v_mfma_f32_16x16x32_bf16 v[2:5], v[158:161], v[214:217], v[2:5]
	s_barrier
	s_add_i32 s76, s76, 2
	s_add_u32 s40, s40, 0x100
	s_addc_u32 s41, s41, 0
	s_add_u32 s74, s74, 0x100
	s_addc_u32 s75, s75, 0
	s_cmp_gt_u32 s76, 29
	s_cbranch_scc0 .LBB0_524

;     __host__ __device__ bool next(int i, Unit& u) const { const bool ok = StaticOrder::next(i, u); u.lm = 0; u.ln = 0; return ok; }
; #define PG8_STAGE(bufoff, gbase, voff) do { _Pragma("unroll") for (int _i = 0; _i < 2; ++_i) \
;         __builtin_amdgcn_global_load_lds((const unsigned*)((const char*)(gbase) + (voff)[_i]), (PG8_LAS unsigned*)(lds + (bufoff) + ldsw + _i * 8192), 16, 0, 0); } while (0)
; #define PG8_BAR __builtin_amdgcn_s_barrier()
; template <class Epi, class Sched, bool ALIGN_EPI = false, bool SP2 = false>
; __device__ __forceinline__ void gemm_phase(PG8_LAS unsigned char* lds, const Gemm g, const Sched& S, const Epi& E, const int wave_id) {
;     ...
;         const bool has_next = S.next(ui + 1, nxt);
;         const char* nA = has_next ? (const char*)g.A + (size_t)nxt.lm * tstep : cA; const char* nB = has_next ? (const char*)g.Bt + (size_t)nxt.ln * tstep : cB;
; #pragma unroll 1
;         for (int t = 0; t < nt; t += 2) {
;             const bool last = (t == nt - 2);
;             const char* a1 = cA + (size_t)(t + 1) * kstep;
;             const char* a2 = last ? nA : cA + (size_t)(t + 2) * kstep; const char* b2 = last ? nB : cB + (size_t)(t + 2) * kstep;
;             const char* a3 = a2 + kstep; const char* b3 = b2 + kstep;
;             if (last && has_next) S.a_ready(nxt);
;             if constexpr (SP2) {
;             PG8_LDB(B0, 0, 0); PG8_LDB(B1, 0, 1); PG8_SCHED; PG8_LDA(At, 0, 0); PG8_STAGE(PG8_SA(1, 1), a1 + hstep, voffA);
;             PG8_WAIT_V(8); PG8_WAIT_L(0); PG8_BAR; PG8_MMA(0, 0, At, B0); PG8_MMA(0, 1, At, B1); PG8_BAR; PG8_SCHED;
;             PG8_LDA(At, 0, 1); PG8_STAGE(PG8_SB(0, 0), b2, voffB); PG8_STAGE(PG8_SB(0, 1), b2 + hstep, voffB); PG8_STAGE(PG8_SA(0, 0), a2, voffA);
;             PG8_WAIT_V(8); PG8_WAIT_L(0); PG8_BAR; PG8_MMA(1, 0, At, B0); PG8_MMA(1, 1, At, B1); PG8_BAR; PG8_SCHED;
;             PG8_LDB(B0, 1, 0); PG8_LDB(B1, 1, 1); PG8_SCHED; PG8_LDA(At, 1, 0); PG8_STAGE(PG8_SA(0, 1), a2 + hstep, voffA);
;             PG8_WAIT_V(8); PG8_WAIT_L(0); PG8_BAR; PG8_MMA(0, 0, At, B0); PG8_MMA(0, 1, At, B1); PG8_BAR; PG8_SCHED;
;             PG8_LDA(At, 1, 1); PG8_STAGE(PG8_SB(1, 0), b3, voffB); PG8_STAGE(PG8_SB(1, 1), b3 + hstep, voffB); PG8_STAGE(PG8_SA(1, 0), a3, voffA);
;             PG8_WAIT_V(8); PG8_WAIT_L(0); PG8_BAR; PG8_MMA(1, 0, At, B0); PG8_MMA(1, 1, At, B1); PG8_BAR; PG8_SCHED;
.LBB0_640:
	s_ashr_i32 s15, s14, 31
	s_lshl_b64 s[16:17], s[14:15], 20
	s_add_u32 s16, s47, s16
	s_addc_u32 s17, s48, s17
	s_and_b64 s[18:19], s[38:39], exec
	s_cselect_b32 s15, s17, s21
	s_cselect_b32 s71, s16, s20
	s_ashr_i32 s13, s12, 31
	s_lshl_b64 s[18:19], s[12:13], 20
	s_add_u32 s18, s49, s18
	s_addc_u32 s19, s52, s19
	s_and_b64 s[44:45], s[38:39], exec
	s_cselect_b32 s13, s19, s43
	s_cselect_b32 s72, s18, s42
	s_add_u32 s20, s20, 0x80080
	s_addc_u32 s21, s21, 0
	s_add_u32 s73, s42, 0x100
	s_addc_u32 s74, s43, 0
	s_mov_b32 s75, -2
	v_add_u32_e32 v144, 0x10000, v147
	s_cmp_eq_u64 s[10:11], 0
	s_cbranch_scc0 .Lprio_g3
	s_setprio 1
.Lprio_g3:
	s_add_u32 s42, s20, 0xfff80080
	s_addc_u32 s43, s21, -1
	s_add_i32 s76, 0, 0x10000
	s_cmp_eq_u32 s75, 28
	s_cselect_b32 s45, s15, s43
	s_cselect_b32 s44, s71, s42
	s_cselect_b32 s43, s13, s74
	s_cselect_b32 s42, s72, s73
	s_add_i32 s79, 0, 0x14000
	s_add_i32 m0, s53, 0xc000
	s_nop 0
	global_load_lds_dwordx4 v138, s[20:21]
	ds_read_b128 v[158:161], v144
	ds_read_b128 v[162:165], v144 offset:1024
	ds_read_b128 v[166:169], v144 offset:2048
	ds_read_b128 v[170:173], v144 offset:3072
	ds_read_b128 v[174:177], v144 offset:16384
	ds_read_b128 v[178:181], v144 offset:17408
	ds_read_b128 v[182:185], v144 offset:18432
	ds_read_b128 v[186:189], v144 offset:19456
	s_add_i32 m0, s53, 0xe000
	s_nop 0
	global_load_lds_dwordx4 v140, s[20:21]
	ds_read_b128 v[190:193], v155
	ds_read_b128 v[206:209], v155 offset:1024
	ds_read_b128 v[210:213], v155 offset:2048
	ds_read_b128 v[214:217], v155 offset:3072
	ds_read_b128 v[226:229], v155 offset:4096
	ds_read_b128 v[234:237], v155 offset:5120
	ds_read_b128 v[238:241], v155 offset:6144
	ds_read_b128 v[242:245], v155 offset:7168
	s_waitcnt lgkmcnt(0)
	v_mfma_f32_16x16x32_bf16 v[126:129], v[158:161], v[190:193], 0
	v_mfma_f32_16x16x32_bf16 v[118:121], v[166:169], v[190:193], 0
	v_mfma_f32_16x16x32_bf16 v[110:113], v[158:161], v[210:213], 0
	v_mfma_f32_16x16x32_bf16 v[102:105], v[166:169], v[210:213], 0
	s_waitcnt vmcnt(8)
	s_barrier
	v_mfma_f32_16x16x32_bf16 v[94:97], v[158:161], v[226:229], 0
	v_mfma_f32_16x16x32_bf16 v[86:89], v[166:169], v[226:229], 0
	v_mfma_f32_16x16x32_bf16 v[78:81], v[158:161], v[238:241], 0
	v_mfma_f32_16x16x32_bf16 v[70:73], v[166:169], v[238:241], 0
	v_mfma_f32_16x16x32_bf16 v[126:129], v[162:165], v[206:209], v[126:129]
	v_mfma_f32_16x16x32_bf16 v[118:121], v[170:173], v[206:209], v[118:121]
	v_mfma_f32_16x16x32_bf16 v[110:113], v[162:165], v[214:217], v[110:113]
	v_mfma_f32_16x16x32_bf16 v[102:105], v[170:173], v[214:217], v[102:105]
	v_mfma_f32_16x16x32_bf16 v[94:97], v[162:165], v[234:237], v[94:97]
	v_mfma_f32_16x16x32_bf16 v[86:89], v[170:173], v[234:237], v[86:89]
	v_mfma_f32_16x16x32_bf16 v[78:81], v[162:165], v[242:245], v[78:81]
	v_mfma_f32_16x16x32_bf16 v[70:73], v[170:173], v[242:245], v[70:73]
	v_mfma_f32_16x16x32_bf16 v[122:125], v[174:177], v[190:193], 0
	v_mfma_f32_16x16x32_bf16 v[114:117], v[182:185], v[190:193], 0
	v_mfma_f32_16x16x32_bf16 v[106:109], v[174:177], v[210:213], 0
	v_mfma_f32_16x16x32_bf16 v[98:101], v[182:185], v[210:213], 0
	v_mfma_f32_16x16x32_bf16 v[90:93], v[174:177], v[226:229], 0
	v_mfma_f32_16x16x32_bf16 v[82:85], v[182:185], v[226:229], 0
	v_mfma_f32_16x16x32_bf16 v[74:77], v[174:177], v[238:241], 0
	v_mfma_f32_16x16x32_bf16 v[66:69], v[182:185], v[238:241], 0
	v_mfma_f32_16x16x32_bf16 v[122:125], v[178:181], v[206:209], v[122:125]
	v_mfma_f32_16x16x32_bf16 v[114:117], v[186:189], v[206:209], v[114:117]
	v_mfma_f32_16x16x32_bf16 v[106:109], v[178:181], v[214:217], v[106:109]
	v_mfma_f32_16x16x32_bf16 v[98:101], v[186:189], v[214:217], v[98:101]
	v_mfma_f32_16x16x32_bf16 v[90:93], v[178:181], v[234:237], v[90:93]
	v_mfma_f32_16x16x32_bf16 v[82:85], v[186:189], v[234:237], v[82:85]
	v_mfma_f32_16x16x32_bf16 v[74:77], v[178:181], v[242:245], v[74:77]
	v_mfma_f32_16x16x32_bf16 v[66:69], v[186:189], v[242:245], v[66:69]
	s_barrier
	s_add_i32 s76, s76, s41
	s_mov_b32 m0, s76
	s_nop 0
	global_load_lds_dwordx4 v132, s[42:43]
	ds_read_b128 v[190:193], v155 offset:16384
	ds_read_b128 v[206:209], v155 offset:17408
	s_add_i32 m0, s76, 0x2000
	s_add_u32 s76, s42, 0x80000
	s_addc_u32 s77, s43, 0
	s_add_i32 s79, s79, s41
	global_load_lds_dwordx4 v136, s[42:43]
	ds_read_b128 v[210:213], v155 offset:18432
	ds_read_b128 v[214:217], v155 offset:19456
	s_mov_b32 m0, s79
	s_nop 0
	global_load_lds_dwordx4 v132, s[76:77]
	ds_read_b128 v[226:229], v155 offset:20480
	ds_read_b128 v[234:237], v155 offset:21504
	s_add_i32 m0, s79, 0x2000
	s_nop 0
	global_load_lds_dwordx4 v136, s[76:77]
	ds_read_b128 v[238:241], v155 offset:22528
	ds_read_b128 v[242:245], v155 offset:23552
	s_mov_b32 m0, s53
	s_nop 0
	global_load_lds_dwordx4 v130, s[44:45]
	s_mov_b32 m0, s56
	s_nop 0
	global_load_lds_dwordx4 v134, s[44:45]
	s_waitcnt lgkmcnt(0)
	v_mfma_f32_16x16x32_bf16 v[62:65], v[158:161], v[190:193], 0
	v_mfma_f32_16x16x32_bf16 v[54:57], v[166:169], v[190:193], 0
	v_mfma_f32_16x16x32_bf16 v[46:49], v[158:161], v[210:213], 0
	v_mfma_f32_16x16x32_bf16 v[38:41], v[166:169], v[210:213], 0
	s_waitcnt vmcnt(8)
	s_barrier
; #define PG8_STAGE(bufoff, gbase, voff) do { _Pragma("unroll") for (int _i = 0; _i < 2; ++_i) \
;         __builtin_amdgcn_global_load_lds((const unsigned*)((const char*)(gbase) + (voff)[_i]), (PG8_LAS unsigned*)(lds + (bufoff) + ldsw + _i * 8192), 16, 0, 0); } while (0)
; #define PG8_LDA(dst, b, h) do { _Pragma("unroll") for (int m = 0; m < 4; ++m) _Pragma("unroll") for (int k = 0; k < 2; ++k) dst[m][k] = *(const PG8_LAS bf16x8*)(lds + PG8_SA(b, h) + aoff + m * 2048 + k * 1024); } while (0)
; #define PG8_LDB(dst, b, h) do { _Pragma("unroll") for (int n = 0; n < 2; ++n) _Pragma("unroll") for (int k = 0; k < 2; ++k) dst[n][k] = *(const PG8_LAS bf16x8*)(lds + PG8_SB(b, h) + boff + n * 2048 + k * 1024); } while (0)
; #define PG8_MMA(ai, bj, At, Bt) do { __builtin_amdgcn_s_setprio(1); _Pragma("unroll") for (int m = 0; m < 4; ++m) _Pragma("unroll") for (int n = 0; n < 2; ++n) _Pragma("unroll") for (int k = 0; k < 2; ++k) \
;         acc[ai][bj][m][n] = __builtin_amdgcn_mfma_f32_16x16x32_bf16(Bt[n][k], At[m][k], acc[ai][bj][m][n], 0, 0, 0); __builtin_amdgcn_s_setprio(0); } while (0)
; #define PG8_BAR __builtin_amdgcn_s_barrier()
; template <class Epi, class Sched, bool ALIGN_EPI = false, bool SP2 = false>
; __device__ __forceinline__ void gemm_phase(PG8_LAS unsigned char* lds, const Gemm g, const Sched& S, const Epi& E, const int wave_id) {
;     ...
;             PG8_LDB(B0, 0, 0); PG8_LDB(B1, 0, 1); PG8_SCHED; PG8_LDA(At, 0, 0); PG8_STAGE(PG8_SA(1, 1), a1 + hstep, voffA);
;             PG8_WAIT_V(8); PG8_WAIT_L(0); PG8_BAR; PG8_MMA(0, 0, At, B0); PG8_MMA(0, 1, At, B1); PG8_BAR; PG8_SCHED;
;             PG8_LDA(At, 0, 1); PG8_STAGE(PG8_SB(0, 0), b2, voffB); PG8_STAGE(PG8_SB(0, 1), b2 + hstep, voffB); PG8_STAGE(PG8_SA(0, 0), a2, voffA);
;             PG8_WAIT_V(8); PG8_WAIT_L(0); PG8_BAR; PG8_MMA(1, 0, At, B0); PG8_MMA(1, 1, At, B1); PG8_BAR; PG8_SCHED;
;             PG8_LDB(B0, 1, 0); PG8_LDB(B1, 1, 1); PG8_SCHED; PG8_LDA(At, 1, 0); PG8_STAGE(PG8_SA(0, 1), a2 + hstep, voffA);
;             PG8_WAIT_V(8); PG8_WAIT_L(0); PG8_BAR; PG8_MMA(0, 0, At, B0); PG8_MMA(0, 1, At, B1); PG8_BAR; PG8_SCHED;
;             PG8_LDA(At, 1, 1); PG8_STAGE(PG8_SB(1, 0), b3, voffB); PG8_STAGE(PG8_SB(1, 1), b3 + hstep, voffB); PG8_STAGE(PG8_SA(1, 0), a3, voffA);
;             PG8_WAIT_V(8); PG8_WAIT_L(0); PG8_BAR; PG8_MMA(1, 0, At, B0); PG8_MMA(1, 1, At, B1); PG8_BAR; PG8_SCHED;
	v_mfma_f32_16x16x32_bf16 v[30:33], v[158:161], v[226:229], 0
	v_mfma_f32_16x16x32_bf16 v[22:25], v[166:169], v[226:229], 0
	v_mfma_f32_16x16x32_bf16 v[14:17], v[158:161], v[238:241], 0
	v_mfma_f32_16x16x32_bf16 v[6:9], v[166:169], v[238:241], 0
	v_mfma_f32_16x16x32_bf16 v[62:65], v[162:165], v[206:209], v[62:65]
	v_mfma_f32_16x16x32_bf16 v[54:57], v[170:173], v[206:209], v[54:57]
	v_mfma_f32_16x16x32_bf16 v[46:49], v[162:165], v[214:217], v[46:49]
	v_mfma_f32_16x16x32_bf16 v[38:41], v[170:173], v[214:217], v[38:41]
	v_mfma_f32_16x16x32_bf16 v[30:33], v[162:165], v[234:237], v[30:33]
	v_mfma_f32_16x16x32_bf16 v[22:25], v[170:173], v[234:237], v[22:25]
	v_mfma_f32_16x16x32_bf16 v[14:17], v[162:165], v[242:245], v[14:17]
	v_mfma_f32_16x16x32_bf16 v[6:9], v[170:173], v[242:245], v[6:9]
	v_mfma_f32_16x16x32_bf16 v[58:61], v[174:177], v[190:193], 0
	v_mfma_f32_16x16x32_bf16 v[50:53], v[182:185], v[190:193], 0
	v_mfma_f32_16x16x32_bf16 v[42:45], v[174:177], v[210:213], 0
	v_mfma_f32_16x16x32_bf16 v[34:37], v[182:185], v[210:213], 0
	v_mfma_f32_16x16x32_bf16 v[26:29], v[174:177], v[226:229], 0
	v_mfma_f32_16x16x32_bf16 v[18:21], v[182:185], v[226:229], 0
	v_mfma_f32_16x16x32_bf16 v[10:13], v[174:177], v[238:241], 0
	v_mfma_f32_16x16x32_bf16 v[2:5], v[182:185], v[238:241], 0
	v_mfma_f32_16x16x32_bf16 v[58:61], v[178:181], v[206:209], v[58:61]
	v_mfma_f32_16x16x32_bf16 v[50:53], v[186:189], v[206:209], v[50:53]
	v_mfma_f32_16x16x32_bf16 v[42:45], v[178:181], v[214:217], v[42:45]
	v_mfma_f32_16x16x32_bf16 v[34:37], v[186:189], v[214:217], v[34:37]
	v_mfma_f32_16x16x32_bf16 v[26:29], v[178:181], v[234:237], v[26:29]
	v_mfma_f32_16x16x32_bf16 v[18:21], v[186:189], v[234:237], v[18:21]
	v_mfma_f32_16x16x32_bf16 v[10:13], v[178:181], v[242:245], v[10:13]
	v_mfma_f32_16x16x32_bf16 v[2:5], v[186:189], v[242:245], v[2:5]
	s_barrier
	s_add_i32 s76, 0, 0x18000
	s_add_i32 s77, 0, 0x1c000
	s_add_u32 s44, s44, 0x80000
	s_addc_u32 s45, s45, 0
	s_mov_b32 m0, s57
	s_nop 0
	global_load_lds_dwordx4 v130, s[44:45]
	ds_read_b128 v[158:161], v144 offset:32768
	ds_read_b128 v[162:165], v144 offset:33792
	ds_read_b128 v[166:169], v144 offset:34816
	ds_read_b128 v[170:173], v144 offset:35840
	ds_read_b128 v[174:177], v144 offset:49152
	ds_read_b128 v[178:181], v144 offset:50176
	ds_read_b128 v[182:185], v144 offset:51200
	ds_read_b128 v[186:189], v144 offset:52224
	s_mov_b32 m0, s64
	s_nop 0
	global_load_lds_dwordx4 v134, s[44:45]
	ds_read_b128 v[190:193], v155 offset:32768
	ds_read_b128 v[206:209], v155 offset:33792
	ds_read_b128 v[210:213], v155 offset:34816
	ds_read_b128 v[214:217], v155 offset:35840
	ds_read_b128 v[226:229], v155 offset:36864
	ds_read_b128 v[234:237], v155 offset:37888
	ds_read_b128 v[238:241], v155 offset:38912
	ds_read_b128 v[242:245], v155 offset:39936
	s_waitcnt lgkmcnt(0)
	v_mfma_f32_16x16x32_bf16 v[126:129], v[158:161], v[190:193], v[126:129]
	v_mfma_f32_16x16x32_bf16 v[118:121], v[166:169], v[190:193], v[118:121]
	v_mfma_f32_16x16x32_bf16 v[110:113], v[158:161], v[210:213], v[110:113]
	v_mfma_f32_16x16x32_bf16 v[102:105], v[166:169], v[210:213], v[102:105]
	s_waitcnt vmcnt(8)
	s_barrier
	v_mfma_f32_16x16x32_bf16 v[94:97], v[158:161], v[226:229], v[94:97]
	v_mfma_f32_16x16x32_bf16 v[86:89], v[166:169], v[226:229], v[86:89]
	v_mfma_f32_16x16x32_bf16 v[78:81], v[158:161], v[238:241], v[78:81]
	v_mfma_f32_16x16x32_bf16 v[70:73], v[166:169], v[238:241], v[70:73]
	v_mfma_f32_16x16x32_bf16 v[126:129], v[162:165], v[206:209], v[126:129]
	v_mfma_f32_16x16x32_bf16 v[118:121], v[170:173], v[206:209], v[118:121]
	v_mfma_f32_16x16x32_bf16 v[110:113], v[162:165], v[214:217], v[110:113]
	v_mfma_f32_16x16x32_bf16 v[102:105], v[170:173], v[214:217], v[102:105]
	v_mfma_f32_16x16x32_bf16 v[94:97], v[162:165], v[234:237], v[94:97]
	v_mfma_f32_16x16x32_bf16 v[86:89], v[170:173], v[234:237], v[86:89]
	v_mfma_f32_16x16x32_bf16 v[78:81], v[162:165], v[242:245], v[78:81]
	v_mfma_f32_16x16x32_bf16 v[70:73], v[170:173], v[242:245], v[70:73]
	v_mfma_f32_16x16x32_bf16 v[122:125], v[174:177], v[190:193], v[122:125]
	v_mfma_f32_16x16x32_bf16 v[114:117], v[182:185], v[190:193], v[114:117]
	v_mfma_f32_16x16x32_bf16 v[106:109], v[174:177], v[210:213], v[106:109]
	v_mfma_f32_16x16x32_bf16 v[98:101], v[182:185], v[210:213], v[98:101]
	v_mfma_f32_16x16x32_bf16 v[90:93], v[174:177], v[226:229], v[90:93]
	v_mfma_f32_16x16x32_bf16 v[82:85], v[182:185], v[226:229], v[82:85]
	v_mfma_f32_16x16x32_bf16 v[74:77], v[174:177], v[238:241], v[74:77]
	v_mfma_f32_16x16x32_bf16 v[66:69], v[182:185], v[238:241], v[66:69]
	v_mfma_f32_16x16x32_bf16 v[122:125], v[178:181], v[206:209], v[122:125]
	v_mfma_f32_16x16x32_bf16 v[114:117], v[186:189], v[206:209], v[114:117]
	v_mfma_f32_16x16x32_bf16 v[106:109], v[178:181], v[214:217], v[106:109]
	v_mfma_f32_16x16x32_bf16 v[98:101], v[186:189], v[214:217], v[98:101]
	v_mfma_f32_16x16x32_bf16 v[90:93], v[178:181], v[234:237], v[90:93]
	v_mfma_f32_16x16x32_bf16 v[82:85], v[186:189], v[234:237], v[82:85]
	v_mfma_f32_16x16x32_bf16 v[74:77], v[178:181], v[242:245], v[74:77]
	v_mfma_f32_16x16x32_bf16 v[66:69], v[186:189], v[242:245], v[66:69]
	s_barrier
; #define PG8_STAGE(bufoff, gbase, voff) do { _Pragma("unroll") for (int _i = 0; _i < 2; ++_i) \
;         __builtin_amdgcn_global_load_lds((const unsigned*)((const char*)(gbase) + (voff)[_i]), (PG8_LAS unsigned*)(lds + (bufoff) + ldsw + _i * 8192), 16, 0, 0); } while (0)
; #define PG8_LDA(dst, b, h) do { _Pragma("unroll") for (int m = 0; m < 4; ++m) _Pragma("unroll") for (int k = 0; k < 2; ++k) dst[m][k] = *(const PG8_LAS bf16x8*)(lds + PG8_SA(b, h) + aoff + m * 2048 + k * 1024); } while (0)
; #define PG8_WAIT_V(n) asm volatile("s_waitcnt vmcnt(" #n ")" ::: "memory")
; #define PG8_WAIT_L(n) asm volatile("s_waitcnt lgkmcnt(" #n ")" ::: "memory")
; #define PG8_BAR __builtin_amdgcn_s_barrier()
; template <class Epi, class Sched, bool ALIGN_EPI = false, bool SP2 = false>
; __device__ __forceinline__ void gemm_phase(PG8_LAS unsigned char* lds, const Gemm g, const Sched& S, const Epi& E, const int wave_id) {
;     ...
;         for (int t = 0; t < nt; t += 2) {
;             const bool last = (t == nt - 2);
;             const char* a1 = cA + (size_t)(t + 1) * kstep;
;             const char* a2 = last ? nA : cA + (size_t)(t + 2) * kstep; const char* b2 = last ? nB : cB + (size_t)(t + 2) * kstep;
;             const char* a3 = a2 + kstep; const char* b3 = b2 + kstep;
;             if (last && has_next) S.a_ready(nxt);
;             if constexpr (SP2) {
;             PG8_LDB(B0, 0, 0); PG8_LDB(B1, 0, 1); PG8_SCHED; PG8_LDA(At, 0, 0); PG8_STAGE(PG8_SA(1, 1), a1 + hstep, voffA);
;             PG8_WAIT_V(8); PG8_WAIT_L(0); PG8_BAR; PG8_MMA(0, 0, At, B0); PG8_MMA(0, 1, At, B1); PG8_BAR; PG8_SCHED;
;             PG8_LDA(At, 0, 1); PG8_STAGE(PG8_SB(0, 0), b2, voffB); PG8_STAGE(PG8_SB(0, 1), b2 + hstep, voffB); PG8_STAGE(PG8_SA(0, 0), a2, voffA);
;             PG8_WAIT_V(8); PG8_WAIT_L(0); PG8_BAR; PG8_MMA(1, 0, At, B0); PG8_MMA(1, 1, At, B1); PG8_BAR; PG8_SCHED;
;             PG8_LDB(B0, 1, 0); PG8_LDB(B1, 1, 1); PG8_SCHED; PG8_LDA(At, 1, 0); PG8_STAGE(PG8_SA(0, 1), a2 + hstep, voffA);
;             PG8_WAIT_V(8); PG8_WAIT_L(0); PG8_BAR; PG8_MMA(0, 0, At, B0); PG8_MMA(0, 1, At, B1); PG8_BAR; PG8_SCHED;
;             PG8_LDA(At, 1, 1); PG8_STAGE(PG8_SB(1, 0), b3, voffB); PG8_STAGE(PG8_SB(1, 1), b3 + hstep, voffB); PG8_STAGE(PG8_SA(1, 0), a3, voffA);
;             PG8_WAIT_V(8); PG8_WAIT_L(0); PG8_BAR; PG8_MMA(1, 0, At, B0); PG8_MMA(1, 1, At, B1); PG8_BAR; PG8_SCHED;
	s_add_u32 vcc_lo, s44, 0xfff80080
	s_addc_u32 vcc_hi, s45, -1
	s_mov_b32 m0, s65
	s_nop 0
	global_load_lds_dwordx4 v130, vcc
	ds_read_b128 v[190:193], v155 offset:49152
	ds_read_b128 v[206:209], v155 offset:50176
	s_mov_b32 m0, s68
	s_add_i32 s44, s76, s41
	global_load_lds_dwordx4 v134, vcc
	ds_read_b128 v[210:213], v155 offset:51200
	ds_read_b128 v[214:217], v155 offset:52224
	s_add_u32 vcc_lo, s42, 0x80
	s_addc_u32 vcc_hi, s43, 0
	s_mov_b32 m0, s44
	s_nop 0
	global_load_lds_dwordx4 v132, vcc
	ds_read_b128 v[226:229], v155 offset:53248
	ds_read_b128 v[234:237], v155 offset:54272
	s_add_i32 m0, s44, 0x2000
	s_add_u32 s42, s42, 0x80080
	s_addc_u32 s43, s43, 0
	global_load_lds_dwordx4 v136, vcc
	ds_read_b128 v[238:241], v155 offset:55296
	ds_read_b128 v[242:245], v155 offset:56320
	s_add_i32 s44, s77, s41
	s_mov_b32 m0, s44
	s_nop 0
	global_load_lds_dwordx4 v132, s[42:43]
	s_add_i32 m0, s44, 0x2000
	s_nop 0
	global_load_lds_dwordx4 v136, s[42:43]
	s_waitcnt lgkmcnt(0)
	v_mfma_f32_16x16x32_bf16 v[62:65], v[158:161], v[190:193], v[62:65]
	v_mfma_f32_16x16x32_bf16 v[54:57], v[166:169], v[190:193], v[54:57]
	v_mfma_f32_16x16x32_bf16 v[46:49], v[158:161], v[210:213], v[46:49]
	v_mfma_f32_16x16x32_bf16 v[38:41], v[166:169], v[210:213], v[38:41]
	s_waitcnt vmcnt(8)
	s_barrier
	v_mfma_f32_16x16x32_bf16 v[30:33], v[158:161], v[226:229], v[30:33]
	v_mfma_f32_16x16x32_bf16 v[22:25], v[166:169], v[226:229], v[22:25]
	v_mfma_f32_16x16x32_bf16 v[14:17], v[158:161], v[238:241], v[14:17]
	v_mfma_f32_16x16x32_bf16 v[6:9], v[166:169], v[238:241], v[6:9]
	v_mfma_f32_16x16x32_bf16 v[62:65], v[162:165], v[206:209], v[62:65]
	v_mfma_f32_16x16x32_bf16 v[54:57], v[170:173], v[206:209], v[54:57]
	v_mfma_f32_16x16x32_bf16 v[46:49], v[162:165], v[214:217], v[46:49]
	v_mfma_f32_16x16x32_bf16 v[38:41], v[170:173], v[214:217], v[38:41]
	v_mfma_f32_16x16x32_bf16 v[30:33], v[162:165], v[234:237], v[30:33]
	v_mfma_f32_16x16x32_bf16 v[22:25], v[170:173], v[234:237], v[22:25]
	v_mfma_f32_16x16x32_bf16 v[14:17], v[162:165], v[242:245], v[14:17]
	v_mfma_f32_16x16x32_bf16 v[6:9], v[170:173], v[242:245], v[6:9]
	v_mfma_f32_16x16x32_bf16 v[58:61], v[174:177], v[190:193], v[58:61]
	v_mfma_f32_16x16x32_bf16 v[50:53], v[182:185], v[190:193], v[50:53]
	v_mfma_f32_16x16x32_bf16 v[42:45], v[174:177], v[210:213], v[42:45]
	v_mfma_f32_16x16x32_bf16 v[34:37], v[182:185], v[210:213], v[34:37]
	v_mfma_f32_16x16x32_bf16 v[26:29], v[174:177], v[226:229], v[26:29]
	v_mfma_f32_16x16x32_bf16 v[18:21], v[182:185], v[226:229], v[18:21]
	v_mfma_f32_16x16x32_bf16 v[10:13], v[174:177], v[238:241], v[10:13]
	v_mfma_f32_16x16x32_bf16 v[2:5], v[182:185], v[238:241], v[2:5]
	v_mfma_f32_16x16x32_bf16 v[58:61], v[178:181], v[206:209], v[58:61]
	v_mfma_f32_16x16x32_bf16 v[50:53], v[186:189], v[206:209], v[50:53]
	v_mfma_f32_16x16x32_bf16 v[42:45], v[178:181], v[214:217], v[42:45]
	v_mfma_f32_16x16x32_bf16 v[34:37], v[186:189], v[214:217], v[34:37]
	v_mfma_f32_16x16x32_bf16 v[26:29], v[178:181], v[234:237], v[26:29]
	v_mfma_f32_16x16x32_bf16 v[18:21], v[186:189], v[234:237], v[18:21]
	v_mfma_f32_16x16x32_bf16 v[10:13], v[178:181], v[242:245], v[10:13]
	v_mfma_f32_16x16x32_bf16 v[2:5], v[186:189], v[242:245], v[2:5]
	s_barrier
	s_add_i32 s75, s75, 2
	s_add_u32 s20, s20, 0x100
	s_addc_u32 s21, s21, 0
	s_add_u32 s73, s73, 0x100
	s_addc_u32 s74, s74, 0
	s_cmp_gt_u32 s75, 29
	s_cbranch_scc1 .Lpeel_exit_g3
.LBB0_641:
	s_add_u32 s42, s20, 0xfff80080
	s_addc_u32 s43, s21, -1
	s_add_i32 s76, 0, 0x10000
	s_cmp_eq_u32 s75, 28
	s_cselect_b32 s45, s15, s43
	s_cselect_b32 s44, s71, s42
	s_cselect_b32 s43, s13, s74
	s_cselect_b32 s42, s72, s73
	s_add_i32 s79, 0, 0x14000
	s_add_i32 m0, s53, 0xc000
	s_nop 0
	global_load_lds_dwordx4 v138, s[20:21]
	ds_read_b128 v[158:161], v144
	ds_read_b128 v[162:165], v144 offset:1024
	ds_read_b128 v[166:169], v144 offset:2048
	ds_read_b128 v[170:173], v144 offset:3072
	ds_read_b128 v[174:177], v144 offset:16384
	ds_read_b128 v[178:181], v144 offset:17408
	ds_read_b128 v[182:185], v144 offset:18432
	ds_read_b128 v[186:189], v144 offset:19456
	s_add_i32 m0, s53, 0xe000
	s_nop 0
	global_load_lds_dwordx4 v140, s[20:21]
	ds_read_b128 v[190:193], v155
	ds_read_b128 v[206:209], v155 offset:1024
	ds_read_b128 v[210:213], v155 offset:2048
	ds_read_b128 v[214:217], v155 offset:3072
	ds_read_b128 v[226:229], v155 offset:4096
	ds_read_b128 v[234:237], v155 offset:5120
	ds_read_b128 v[238:241], v155 offset:6144
	ds_read_b128 v[242:245], v155 offset:7168
	s_waitcnt lgkmcnt(0)
	v_mfma_f32_16x16x32_bf16 v[126:129], v[158:161], v[190:193], v[126:129]
	v_mfma_f32_16x16x32_bf16 v[118:121], v[166:169], v[190:193], v[118:121]
	v_mfma_f32_16x16x32_bf16 v[110:113], v[158:161], v[210:213], v[110:113]
	v_mfma_f32_16x16x32_bf16 v[102:105], v[166:169], v[210:213], v[102:105]
	s_waitcnt vmcnt(8)
	s_barrier
; #define PG8_STAGE(bufoff, gbase, voff) do { _Pragma("unroll") for (int _i = 0; _i < 2; ++_i) \
;         __builtin_amdgcn_global_load_lds((const unsigned*)((const char*)(gbase) + (voff)[_i]), (PG8_LAS unsigned*)(lds + (bufoff) + ldsw + _i * 8192), 16, 0, 0); } while (0)
; #define PG8_LDA(dst, b, h) do { _Pragma("unroll") for (int m = 0; m < 4; ++m) _Pragma("unroll") for (int k = 0; k < 2; ++k) dst[m][k] = *(const PG8_LAS bf16x8*)(lds + PG8_SA(b, h) + aoff + m * 2048 + k * 1024); } while (0)
; #define PG8_LDB(dst, b, h) do { _Pragma("unroll") for (int n = 0; n < 2; ++n) _Pragma("unroll") for (int k = 0; k < 2; ++k) dst[n][k] = *(const PG8_LAS bf16x8*)(lds + PG8_SB(b, h) + boff + n * 2048 + k * 1024); } while (0)
; #define PG8_MMA(ai, bj, At, Bt) do { __builtin_amdgcn_s_setprio(1); _Pragma("unroll") for (int m = 0; m < 4; ++m) _Pragma("unroll") for (int n = 0; n < 2; ++n) _Pragma("unroll") for (int k = 0; k < 2; ++k) \
;         acc[ai][bj][m][n] = __builtin_amdgcn_mfma_f32_16x16x32_bf16(Bt[n][k], At[m][k], acc[ai][bj][m][n], 0, 0, 0); __builtin_amdgcn_s_setprio(0); } while (0)
; #define PG8_BAR __builtin_amdgcn_s_barrier()
; template <class Epi, class Sched, bool ALIGN_EPI = false, bool SP2 = false>
; __device__ __forceinline__ void gemm_phase(PG8_LAS unsigned char* lds, const Gemm g, const Sched& S, const Epi& E, const int wave_id) {
;     ...
;             PG8_LDB(B0, 0, 0); PG8_LDB(B1, 0, 1); PG8_SCHED; PG8_LDA(At, 0, 0); PG8_STAGE(PG8_SA(1, 1), a1 + hstep, voffA);
;             PG8_WAIT_V(8); PG8_WAIT_L(0); PG8_BAR; PG8_MMA(0, 0, At, B0); PG8_MMA(0, 1, At, B1); PG8_BAR; PG8_SCHED;
;             PG8_LDA(At, 0, 1); PG8_STAGE(PG8_SB(0, 0), b2, voffB); PG8_STAGE(PG8_SB(0, 1), b2 + hstep, voffB); PG8_STAGE(PG8_SA(0, 0), a2, voffA);
;             PG8_WAIT_V(8); PG8_WAIT_L(0); PG8_BAR; PG8_MMA(1, 0, At, B0); PG8_MMA(1, 1, At, B1); PG8_BAR; PG8_SCHED;
;             PG8_LDB(B0, 1, 0); PG8_LDB(B1, 1, 1); PG8_SCHED; PG8_LDA(At, 1, 0); PG8_STAGE(PG8_SA(0, 1), a2 + hstep, voffA);
;             PG8_WAIT_V(8); PG8_WAIT_L(0); PG8_BAR; PG8_MMA(0, 0, At, B0); PG8_MMA(0, 1, At, B1); PG8_BAR; PG8_SCHED;
;             PG8_LDA(At, 1, 1); PG8_STAGE(PG8_SB(1, 0), b3, voffB); PG8_STAGE(PG8_SB(1, 1), b3 + hstep, voffB); PG8_STAGE(PG8_SA(1, 0), a3, voffA);
;             PG8_WAIT_V(8); PG8_WAIT_L(0); PG8_BAR; PG8_MMA(1, 0, At, B0); PG8_MMA(1, 1, At, B1); PG8_BAR; PG8_SCHED;
	v_mfma_f32_16x16x32_bf16 v[94:97], v[158:161], v[226:229], v[94:97]
	v_mfma_f32_16x16x32_bf16 v[86:89], v[166:169], v[226:229], v[86:89]
	v_mfma_f32_16x16x32_bf16 v[78:81], v[158:161], v[238:241], v[78:81]
	v_mfma_f32_16x16x32_bf16 v[70:73], v[166:169], v[238:241], v[70:73]
	v_mfma_f32_16x16x32_bf16 v[126:129], v[162:165], v[206:209], v[126:129]
	v_mfma_f32_16x16x32_bf16 v[118:121], v[170:173], v[206:209], v[118:121]
	v_mfma_f32_16x16x32_bf16 v[110:113], v[162:165], v[214:217], v[110:113]
	v_mfma_f32_16x16x32_bf16 v[102:105], v[170:173], v[214:217], v[102:105]
	v_mfma_f32_16x16x32_bf16 v[94:97], v[162:165], v[234:237], v[94:97]
	v_mfma_f32_16x16x32_bf16 v[86:89], v[170:173], v[234:237], v[86:89]
	v_mfma_f32_16x16x32_bf16 v[78:81], v[162:165], v[242:245], v[78:81]
	v_mfma_f32_16x16x32_bf16 v[70:73], v[170:173], v[242:245], v[70:73]
	v_mfma_f32_16x16x32_bf16 v[122:125], v[174:177], v[190:193], v[122:125]
	v_mfma_f32_16x16x32_bf16 v[114:117], v[182:185], v[190:193], v[114:117]
	v_mfma_f32_16x16x32_bf16 v[106:109], v[174:177], v[210:213], v[106:109]
	v_mfma_f32_16x16x32_bf16 v[98:101], v[182:185], v[210:213], v[98:101]
	v_mfma_f32_16x16x32_bf16 v[90:93], v[174:177], v[226:229], v[90:93]
	v_mfma_f32_16x16x32_bf16 v[82:85], v[182:185], v[226:229], v[82:85]
	v_mfma_f32_16x16x32_bf16 v[74:77], v[174:177], v[238:241], v[74:77]
	v_mfma_f32_16x16x32_bf16 v[66:69], v[182:185], v[238:241], v[66:69]
	v_mfma_f32_16x16x32_bf16 v[122:125], v[178:181], v[206:209], v[122:125]
	v_mfma_f32_16x16x32_bf16 v[114:117], v[186:189], v[206:209], v[114:117]
	v_mfma_f32_16x16x32_bf16 v[106:109], v[178:181], v[214:217], v[106:109]
	v_mfma_f32_16x16x32_bf16 v[98:101], v[186:189], v[214:217], v[98:101]
	v_mfma_f32_16x16x32_bf16 v[90:93], v[178:181], v[234:237], v[90:93]
	v_mfma_f32_16x16x32_bf16 v[82:85], v[186:189], v[234:237], v[82:85]
	v_mfma_f32_16x16x32_bf16 v[74:77], v[178:181], v[242:245], v[74:77]
	v_mfma_f32_16x16x32_bf16 v[66:69], v[186:189], v[242:245], v[66:69]
	s_barrier
	s_add_i32 s76, s76, s41
	s_mov_b32 m0, s76
	s_nop 0
	global_load_lds_dwordx4 v132, s[42:43]
	ds_read_b128 v[190:193], v155 offset:16384
	ds_read_b128 v[206:209], v155 offset:17408
	s_add_i32 m0, s76, 0x2000
	s_add_u32 s76, s42, 0x80000
	s_addc_u32 s77, s43, 0
	s_add_i32 s79, s79, s41
	global_load_lds_dwordx4 v136, s[42:43]
	ds_read_b128 v[210:213], v155 offset:18432
	ds_read_b128 v[214:217], v155 offset:19456
	s_mov_b32 m0, s79
	s_nop 0
	global_load_lds_dwordx4 v132, s[76:77]
	ds_read_b128 v[226:229], v155 offset:20480
	ds_read_b128 v[234:237], v155 offset:21504
	s_add_i32 m0, s79, 0x2000
	s_nop 0
	global_load_lds_dwordx4 v136, s[76:77]
	ds_read_b128 v[238:241], v155 offset:22528
	ds_read_b128 v[242:245], v155 offset:23552
	s_mov_b32 m0, s53
	s_nop 0
	global_load_lds_dwordx4 v130, s[44:45]
	s_mov_b32 m0, s56
	s_nop 0
	global_load_lds_dwordx4 v134, s[44:45]
	s_waitcnt lgkmcnt(0)
	v_mfma_f32_16x16x32_bf16 v[62:65], v[158:161], v[190:193], v[62:65]
	v_mfma_f32_16x16x32_bf16 v[54:57], v[166:169], v[190:193], v[54:57]
	v_mfma_f32_16x16x32_bf16 v[46:49], v[158:161], v[210:213], v[46:49]
	v_mfma_f32_16x16x32_bf16 v[38:41], v[166:169], v[210:213], v[38:41]
	s_waitcnt vmcnt(8)
	s_barrier
	v_mfma_f32_16x16x32_bf16 v[30:33], v[158:161], v[226:229], v[30:33]
	v_mfma_f32_16x16x32_bf16 v[22:25], v[166:169], v[226:229], v[22:25]
	v_mfma_f32_16x16x32_bf16 v[14:17], v[158:161], v[238:241], v[14:17]
	v_mfma_f32_16x16x32_bf16 v[6:9], v[166:169], v[238:241], v[6:9]
	v_mfma_f32_16x16x32_bf16 v[62:65], v[162:165], v[206:209], v[62:65]
	v_mfma_f32_16x16x32_bf16 v[54:57], v[170:173], v[206:209], v[54:57]
	v_mfma_f32_16x16x32_bf16 v[46:49], v[162:165], v[214:217], v[46:49]
	v_mfma_f32_16x16x32_bf16 v[38:41], v[170:173], v[214:217], v[38:41]
	v_mfma_f32_16x16x32_bf16 v[30:33], v[162:165], v[234:237], v[30:33]
	v_mfma_f32_16x16x32_bf16 v[22:25], v[170:173], v[234:237], v[22:25]
	v_mfma_f32_16x16x32_bf16 v[14:17], v[162:165], v[242:245], v[14:17]
	v_mfma_f32_16x16x32_bf16 v[6:9], v[170:173], v[242:245], v[6:9]
	v_mfma_f32_16x16x32_bf16 v[58:61], v[174:177], v[190:193], v[58:61]
	v_mfma_f32_16x16x32_bf16 v[50:53], v[182:185], v[190:193], v[50:53]
	v_mfma_f32_16x16x32_bf16 v[42:45], v[174:177], v[210:213], v[42:45]
	v_mfma_f32_16x16x32_bf16 v[34:37], v[182:185], v[210:213], v[34:37]
	v_mfma_f32_16x16x32_bf16 v[26:29], v[174:177], v[226:229], v[26:29]
	v_mfma_f32_16x16x32_bf16 v[18:21], v[182:185], v[226:229], v[18:21]
	v_mfma_f32_16x16x32_bf16 v[10:13], v[174:177], v[238:241], v[10:13]
	v_mfma_f32_16x16x32_bf16 v[2:5], v[182:185], v[238:241], v[2:5]
	v_mfma_f32_16x16x32_bf16 v[58:61], v[178:181], v[206:209], v[58:61]
	v_mfma_f32_16x16x32_bf16 v[50:53], v[186:189], v[206:209], v[50:53]
	v_mfma_f32_16x16x32_bf16 v[42:45], v[178:181], v[214:217], v[42:45]
	v_mfma_f32_16x16x32_bf16 v[34:37], v[186:189], v[214:217], v[34:37]
	v_mfma_f32_16x16x32_bf16 v[26:29], v[178:181], v[234:237], v[26:29]
	v_mfma_f32_16x16x32_bf16 v[18:21], v[186:189], v[234:237], v[18:21]
	v_mfma_f32_16x16x32_bf16 v[10:13], v[178:181], v[242:245], v[10:13]
	v_mfma_f32_16x16x32_bf16 v[2:5], v[186:189], v[242:245], v[2:5]
	s_barrier
; #define PG8_STAGE(bufoff, gbase, voff) do { _Pragma("unroll") for (int _i = 0; _i < 2; ++_i) \
;         __builtin_amdgcn_global_load_lds((const unsigned*)((const char*)(gbase) + (voff)[_i]), (PG8_LAS unsigned*)(lds + (bufoff) + ldsw + _i * 8192), 16, 0, 0); } while (0)
; #define PG8_LDA(dst, b, h) do { _Pragma("unroll") for (int m = 0; m < 4; ++m) _Pragma("unroll") for (int k = 0; k < 2; ++k) dst[m][k] = *(const PG8_LAS bf16x8*)(lds + PG8_SA(b, h) + aoff + m * 2048 + k * 1024); } while (0)
; #define PG8_LDB(dst, b, h) do { _Pragma("unroll") for (int n = 0; n < 2; ++n) _Pragma("unroll") for (int k = 0; k < 2; ++k) dst[n][k] = *(const PG8_LAS bf16x8*)(lds + PG8_SB(b, h) + boff + n * 2048 + k * 1024); } while (0)
; #define PG8_MMA(ai, bj, At, Bt) do { __builtin_amdgcn_s_setprio(1); _Pragma("unroll") for (int m = 0; m < 4; ++m) _Pragma("unroll") for (int n = 0; n < 2; ++n) _Pragma("unroll") for (int k = 0; k < 2; ++k) \
;         acc[ai][bj][m][n] = __builtin_amdgcn_mfma_f32_16x16x32_bf16(Bt[n][k], At[m][k], acc[ai][bj][m][n], 0, 0, 0); __builtin_amdgcn_s_setprio(0); } while (0)
; #define PG8_BAR __builtin_amdgcn_s_barrier()
; template <class Epi, class Sched, bool ALIGN_EPI = false, bool SP2 = false>
; __device__ __forceinline__ void gemm_phase(PG8_LAS unsigned char* lds, const Gemm g, const Sched& S, const Epi& E, const int wave_id) {
;     ...
;             PG8_LDB(B0, 0, 0); PG8_LDB(B1, 0, 1); PG8_SCHED; PG8_LDA(At, 0, 0); PG8_STAGE(PG8_SA(1, 1), a1 + hstep, voffA);
;             PG8_WAIT_V(8); PG8_WAIT_L(0); PG8_BAR; PG8_MMA(0, 0, At, B0); PG8_MMA(0, 1, At, B1); PG8_BAR; PG8_SCHED;
;             PG8_LDA(At, 0, 1); PG8_STAGE(PG8_SB(0, 0), b2, voffB); PG8_STAGE(PG8_SB(0, 1), b2 + hstep, voffB); PG8_STAGE(PG8_SA(0, 0), a2, voffA);
;             PG8_WAIT_V(8); PG8_WAIT_L(0); PG8_BAR; PG8_MMA(1, 0, At, B0); PG8_MMA(1, 1, At, B1); PG8_BAR; PG8_SCHED;
;             PG8_LDB(B0, 1, 0); PG8_LDB(B1, 1, 1); PG8_SCHED; PG8_LDA(At, 1, 0); PG8_STAGE(PG8_SA(0, 1), a2 + hstep, voffA);
;             PG8_WAIT_V(8); PG8_WAIT_L(0); PG8_BAR; PG8_MMA(0, 0, At, B0); PG8_MMA(0, 1, At, B1); PG8_BAR; PG8_SCHED;
;             PG8_LDA(At, 1, 1); PG8_STAGE(PG8_SB(1, 0), b3, voffB); PG8_STAGE(PG8_SB(1, 1), b3 + hstep, voffB); PG8_STAGE(PG8_SA(1, 0), a3, voffA);
;             PG8_WAIT_V(8); PG8_WAIT_L(0); PG8_BAR; PG8_MMA(1, 0, At, B0); PG8_MMA(1, 1, At, B1); PG8_BAR; PG8_SCHED;
	s_add_i32 s76, 0, 0x18000
	s_add_i32 s77, 0, 0x1c000
	s_add_u32 s44, s44, 0x80000
	s_addc_u32 s45, s45, 0
	s_mov_b32 m0, s57
	s_nop 0
	global_load_lds_dwordx4 v130, s[44:45]
	ds_read_b128 v[158:161], v144 offset:32768
	ds_read_b128 v[162:165], v144 offset:33792
	ds_read_b128 v[166:169], v144 offset:34816
	ds_read_b128 v[170:173], v144 offset:35840
	ds_read_b128 v[174:177], v144 offset:49152
	ds_read_b128 v[178:181], v144 offset:50176
	ds_read_b128 v[182:185], v144 offset:51200
	ds_read_b128 v[186:189], v144 offset:52224
	s_mov_b32 m0, s64
	s_nop 0
	global_load_lds_dwordx4 v134, s[44:45]
	ds_read_b128 v[190:193], v155 offset:32768
	ds_read_b128 v[206:209], v155 offset:33792
	ds_read_b128 v[210:213], v155 offset:34816
	ds_read_b128 v[214:217], v155 offset:35840
	ds_read_b128 v[226:229], v155 offset:36864
	ds_read_b128 v[234:237], v155 offset:37888
	ds_read_b128 v[238:241], v155 offset:38912
	ds_read_b128 v[242:245], v155 offset:39936
	s_waitcnt lgkmcnt(0)
	v_mfma_f32_16x16x32_bf16 v[126:129], v[158:161], v[190:193], v[126:129]
	v_mfma_f32_16x16x32_bf16 v[118:121], v[166:169], v[190:193], v[118:121]
	v_mfma_f32_16x16x32_bf16 v[110:113], v[158:161], v[210:213], v[110:113]
	v_mfma_f32_16x16x32_bf16 v[102:105], v[166:169], v[210:213], v[102:105]
	s_waitcnt vmcnt(8)
	s_barrier
	v_mfma_f32_16x16x32_bf16 v[94:97], v[158:161], v[226:229], v[94:97]
	v_mfma_f32_16x16x32_bf16 v[86:89], v[166:169], v[226:229], v[86:89]
	v_mfma_f32_16x16x32_bf16 v[78:81], v[158:161], v[238:241], v[78:81]
	v_mfma_f32_16x16x32_bf16 v[70:73], v[166:169], v[238:241], v[70:73]
	v_mfma_f32_16x16x32_bf16 v[126:129], v[162:165], v[206:209], v[126:129]
	v_mfma_f32_16x16x32_bf16 v[118:121], v[170:173], v[206:209], v[118:121]
	v_mfma_f32_16x16x32_bf16 v[110:113], v[162:165], v[214:217], v[110:113]
	v_mfma_f32_16x16x32_bf16 v[102:105], v[170:173], v[214:217], v[102:105]
	v_mfma_f32_16x16x32_bf16 v[94:97], v[162:165], v[234:237], v[94:97]
	v_mfma_f32_16x16x32_bf16 v[86:89], v[170:173], v[234:237], v[86:89]
	v_mfma_f32_16x16x32_bf16 v[78:81], v[162:165], v[242:245], v[78:81]
	v_mfma_f32_16x16x32_bf16 v[70:73], v[170:173], v[242:245], v[70:73]
	v_mfma_f32_16x16x32_bf16 v[122:125], v[174:177], v[190:193], v[122:125]
	v_mfma_f32_16x16x32_bf16 v[114:117], v[182:185], v[190:193], v[114:117]
	v_mfma_f32_16x16x32_bf16 v[106:109], v[174:177], v[210:213], v[106:109]
	v_mfma_f32_16x16x32_bf16 v[98:101], v[182:185], v[210:213], v[98:101]
	v_mfma_f32_16x16x32_bf16 v[90:93], v[174:177], v[226:229], v[90:93]
	v_mfma_f32_16x16x32_bf16 v[82:85], v[182:185], v[226:229], v[82:85]
	v_mfma_f32_16x16x32_bf16 v[74:77], v[174:177], v[238:241], v[74:77]
	v_mfma_f32_16x16x32_bf16 v[66:69], v[182:185], v[238:241], v[66:69]
	v_mfma_f32_16x16x32_bf16 v[122:125], v[178:181], v[206:209], v[122:125]
	v_mfma_f32_16x16x32_bf16 v[114:117], v[186:189], v[206:209], v[114:117]
	v_mfma_f32_16x16x32_bf16 v[106:109], v[178:181], v[214:217], v[106:109]
	v_mfma_f32_16x16x32_bf16 v[98:101], v[186:189], v[214:217], v[98:101]
	v_mfma_f32_16x16x32_bf16 v[90:93], v[178:181], v[234:237], v[90:93]
	v_mfma_f32_16x16x32_bf16 v[82:85], v[186:189], v[234:237], v[82:85]
	v_mfma_f32_16x16x32_bf16 v[74:77], v[178:181], v[242:245], v[74:77]
	v_mfma_f32_16x16x32_bf16 v[66:69], v[186:189], v[242:245], v[66:69]
	s_barrier
	s_add_u32 vcc_lo, s44, 0xfff80080
	s_addc_u32 vcc_hi, s45, -1
	s_mov_b32 m0, s65
	s_nop 0
	global_load_lds_dwordx4 v130, vcc
	ds_read_b128 v[190:193], v155 offset:49152
	ds_read_b128 v[206:209], v155 offset:50176
	s_mov_b32 m0, s68
	s_add_i32 s44, s76, s41
	global_load_lds_dwordx4 v134, vcc
	ds_read_b128 v[210:213], v155 offset:51200
	ds_read_b128 v[214:217], v155 offset:52224
	s_add_u32 vcc_lo, s42, 0x80
	s_addc_u32 vcc_hi, s43, 0
	s_mov_b32 m0, s44
	s_nop 0
	global_load_lds_dwordx4 v132, vcc
	ds_read_b128 v[226:229], v155 offset:53248
	ds_read_b128 v[234:237], v155 offset:54272
	s_add_i32 m0, s44, 0x2000
	s_add_u32 s42, s42, 0x80080
	s_addc_u32 s43, s43, 0
	global_load_lds_dwordx4 v136, vcc
	ds_read_b128 v[238:241], v155 offset:55296
	ds_read_b128 v[242:245], v155 offset:56320
	s_add_i32 s44, s77, s41
	s_mov_b32 m0, s44
	s_nop 0
	global_load_lds_dwordx4 v132, s[42:43]
	s_add_i32 m0, s44, 0x2000
	s_nop 0
	global_load_lds_dwordx4 v136, s[42:43]
	s_waitcnt lgkmcnt(0)
	v_mfma_f32_16x16x32_bf16 v[62:65], v[158:161], v[190:193], v[62:65]
	v_mfma_f32_16x16x32_bf16 v[54:57], v[166:169], v[190:193], v[54:57]
	v_mfma_f32_16x16x32_bf16 v[46:49], v[158:161], v[210:213], v[46:49]
	v_mfma_f32_16x16x32_bf16 v[38:41], v[166:169], v[210:213], v[38:41]
	s_waitcnt vmcnt(8)
	s_barrier
	v_mfma_f32_16x16x32_bf16 v[30:33], v[158:161], v[226:229], v[30:33]
	v_mfma_f32_16x16x32_bf16 v[22:25], v[166:169], v[226:229], v[22:25]
	v_mfma_f32_16x16x32_bf16 v[14:17], v[158:161], v[238:241], v[14:17]
	v_mfma_f32_16x16x32_bf16 v[6:9], v[166:169], v[238:241], v[6:9]
	v_mfma_f32_16x16x32_bf16 v[62:65], v[162:165], v[206:209], v[62:65]
	v_mfma_f32_16x16x32_bf16 v[54:57], v[170:173], v[206:209], v[54:57]
	v_mfma_f32_16x16x32_bf16 v[46:49], v[162:165], v[214:217], v[46:49]
	v_mfma_f32_16x16x32_bf16 v[38:41], v[170:173], v[214:217], v[38:41]
	v_mfma_f32_16x16x32_bf16 v[30:33], v[162:165], v[234:237], v[30:33]
	v_mfma_f32_16x16x32_bf16 v[22:25], v[170:173], v[234:237], v[22:25]
	v_mfma_f32_16x16x32_bf16 v[14:17], v[162:165], v[242:245], v[14:17]
	v_mfma_f32_16x16x32_bf16 v[6:9], v[170:173], v[242:245], v[6:9]
	v_mfma_f32_16x16x32_bf16 v[58:61], v[174:177], v[190:193], v[58:61]
	v_mfma_f32_16x16x32_bf16 v[50:53], v[182:185], v[190:193], v[50:53]
	v_mfma_f32_16x16x32_bf16 v[42:45], v[174:177], v[210:213], v[42:45]
	v_mfma_f32_16x16x32_bf16 v[34:37], v[182:185], v[210:213], v[34:37]
	v_mfma_f32_16x16x32_bf16 v[26:29], v[174:177], v[226:229], v[26:29]
	v_mfma_f32_16x16x32_bf16 v[18:21], v[182:185], v[226:229], v[18:21]
	v_mfma_f32_16x16x32_bf16 v[10:13], v[174:177], v[238:241], v[10:13]
	v_mfma_f32_16x16x32_bf16 v[2:5], v[182:185], v[238:241], v[2:5]
	v_mfma_f32_16x16x32_bf16 v[58:61], v[178:181], v[206:209], v[58:61]
	v_mfma_f32_16x16x32_bf16 v[50:53], v[186:189], v[206:209], v[50:53]
	v_mfma_f32_16x16x32_bf16 v[42:45], v[178:181], v[214:217], v[42:45]
	v_mfma_f32_16x16x32_bf16 v[34:37], v[186:189], v[214:217], v[34:37]
	v_mfma_f32_16x16x32_bf16 v[26:29], v[178:181], v[234:237], v[26:29]
	v_mfma_f32_16x16x32_bf16 v[18:21], v[186:189], v[234:237], v[18:21]
	v_mfma_f32_16x16x32_bf16 v[10:13], v[178:181], v[242:245], v[10:13]
	v_mfma_f32_16x16x32_bf16 v[2:5], v[186:189], v[242:245], v[2:5]
	s_barrier
	s_add_i32 s75, s75, 2
	s_add_u32 s20, s20, 0x100
	s_addc_u32 s21, s21, 0
	s_add_u32 s73, s73, 0x100
	s_addc_u32 s74, s74, 0
	s_cmp_gt_u32 s75, 29
	s_cbranch_scc0 .LBB0_641

;     __host__ __device__ bool next(int i, Unit& u) const { const bool ok = StaticOrder::next(i, u); u.lm = 0; u.ln = 0; return ok; }
; #define PG8_STAGE(bufoff, gbase, voff) do { _Pragma("unroll") for (int _i = 0; _i < 2; ++_i) \
;         __builtin_amdgcn_global_load_lds((const unsigned*)((const char*)(gbase) + (voff)[_i]), (PG8_LAS unsigned*)(lds + (bufoff) + ldsw + _i * 8192), 16, 0, 0); } while (0)
; #define PG8_BAR __builtin_amdgcn_s_barrier()
; template <class Epi, class Sched, bool ALIGN_EPI = false, bool SP2 = false>
; __device__ __forceinline__ void gemm_phase(PG8_LAS unsigned char* lds, const Gemm g, const Sched& S, const Epi& E, const int wave_id) {
;     ...
;         const bool has_next = S.next(ui + 1, nxt);
;         const char* nA = has_next ? (const char*)g.A + (size_t)nxt.lm * tstep : cA; const char* nB = has_next ? (const char*)g.Bt + (size_t)nxt.ln * tstep : cB;
; #pragma unroll 1
;         for (int t = 0; t < nt; t += 2) {
;             const bool last = (t == nt - 2);
;             const char* a1 = cA + (size_t)(t + 1) * kstep;
;             const char* a2 = last ? nA : cA + (size_t)(t + 2) * kstep; const char* b2 = last ? nB : cB + (size_t)(t + 2) * kstep;
;             const char* a3 = a2 + kstep; const char* b3 = b2 + kstep;
;             if (last && has_next) S.a_ready(nxt);
;             if constexpr (SP2) {
;             PG8_LDB(B0, 0, 0); PG8_LDB(B1, 0, 1); PG8_SCHED; PG8_LDA(At, 0, 0); PG8_STAGE(PG8_SA(1, 1), a1 + hstep, voffA);
;             PG8_WAIT_V(8); PG8_WAIT_L(0); PG8_BAR; PG8_MMA(0, 0, At, B0); PG8_MMA(0, 1, At, B1); PG8_BAR; PG8_SCHED;
;             PG8_LDA(At, 0, 1); PG8_STAGE(PG8_SB(0, 0), b2, voffB); PG8_STAGE(PG8_SB(0, 1), b2 + hstep, voffB); PG8_STAGE(PG8_SA(0, 0), a2, voffA);
;             PG8_WAIT_V(8); PG8_WAIT_L(0); PG8_BAR; PG8_MMA(1, 0, At, B0); PG8_MMA(1, 1, At, B1); PG8_BAR; PG8_SCHED;
;             PG8_LDB(B0, 1, 0); PG8_LDB(B1, 1, 1); PG8_SCHED; PG8_LDA(At, 1, 0); PG8_STAGE(PG8_SA(0, 1), a2 + hstep, voffA);
;             PG8_WAIT_V(8); PG8_WAIT_L(0); PG8_BAR; PG8_MMA(0, 0, At, B0); PG8_MMA(0, 1, At, B1); PG8_BAR; PG8_SCHED;
;             PG8_LDA(At, 1, 1); PG8_STAGE(PG8_SB(1, 0), b3, voffB); PG8_STAGE(PG8_SB(1, 1), b3 + hstep, voffB); PG8_STAGE(PG8_SA(1, 0), a3, voffA);
;             PG8_WAIT_V(8); PG8_WAIT_L(0); PG8_BAR; PG8_MMA(1, 0, At, B0); PG8_MMA(1, 1, At, B1); PG8_BAR; PG8_SCHED;
.LBB0_758:
	s_add_u32 s74, s20, 0x100
	s_addc_u32 s75, s21, 0
	s_mov_b32 s76, -2
	v_add_u32_e32 v226, 0x10000, v218
	s_cmp_eq_u64 s[10:11], 0
	s_cbranch_scc0 .Lprio_g4
	s_setprio 1
.Lprio_g4:
	s_add_u32 s20, s18, 0x100
	s_addc_u32 s21, s19, 0
	s_add_i32 s77, 0, 0x10000
	s_cmpk_eq_i32 s76, 0x54
	s_cselect_b32 s43, s15, s21
	s_cselect_b32 s42, s14, s20
	s_cselect_b32 s41, s17, s75
	s_cselect_b32 s40, s16, s74
	s_add_i32 s79, 0, 0x14000
	s_add_i32 m0, s52, 0xc000
	s_nop 0
	global_load_lds_dwordx4 v210, s[18:19]
	ds_read_b128 v[118:121], v226
	ds_read_b128 v[122:125], v226 offset:1024
	ds_read_b128 v[130:133], v226 offset:2048
	ds_read_b128 v[134:137], v226 offset:3072
	ds_read_b128 v[146:149], v226 offset:16384
	ds_read_b128 v[150:153], v226 offset:17408
	ds_read_b128 v[154:157], v226 offset:18432
	ds_read_b128 v[158:161], v226 offset:19456
	s_add_i32 m0, s52, 0xe000
	s_nop 0
	global_load_lds_dwordx4 v212, s[18:19]
	ds_read_b128 v[162:165], v222
	ds_read_b128 v[166:169], v222 offset:1024
	ds_read_b128 v[170:173], v222 offset:2048
	ds_read_b128 v[174:177], v222 offset:3072
	ds_read_b128 v[178:181], v222 offset:4096
	ds_read_b128 v[182:185], v222 offset:5120
	ds_read_b128 v[186:189], v222 offset:6144
	ds_read_b128 v[214:217], v222 offset:7168
	s_waitcnt lgkmcnt(0)
	v_mfma_f32_16x16x32_bf16 v[142:145], v[118:121], v[162:165], 0
	v_mfma_f32_16x16x32_bf16 v[138:141], v[130:133], v[162:165], 0
	v_mfma_f32_16x16x32_bf16 v[110:113], v[118:121], v[170:173], 0
	v_mfma_f32_16x16x32_bf16 v[106:109], v[130:133], v[170:173], 0
	s_waitcnt vmcnt(8)
	s_barrier
	v_mfma_f32_16x16x32_bf16 v[94:97], v[118:121], v[178:181], 0
	v_mfma_f32_16x16x32_bf16 v[90:93], v[130:133], v[178:181], 0
	v_mfma_f32_16x16x32_bf16 v[78:81], v[118:121], v[186:189], 0
	v_mfma_f32_16x16x32_bf16 v[74:77], v[130:133], v[186:189], 0
	v_mfma_f32_16x16x32_bf16 v[142:145], v[122:125], v[166:169], v[142:145]
	v_mfma_f32_16x16x32_bf16 v[138:141], v[134:137], v[166:169], v[138:141]
	v_mfma_f32_16x16x32_bf16 v[110:113], v[122:125], v[174:177], v[110:113]
	v_mfma_f32_16x16x32_bf16 v[106:109], v[134:137], v[174:177], v[106:109]
	v_mfma_f32_16x16x32_bf16 v[94:97], v[122:125], v[182:185], v[94:97]
	v_mfma_f32_16x16x32_bf16 v[90:93], v[134:137], v[182:185], v[90:93]
	v_mfma_f32_16x16x32_bf16 v[78:81], v[122:125], v[214:217], v[78:81]
	v_mfma_f32_16x16x32_bf16 v[74:77], v[134:137], v[214:217], v[74:77]
	v_mfma_f32_16x16x32_bf16 v[126:129], v[146:149], v[162:165], 0
	v_mfma_f32_16x16x32_bf16 v[114:117], v[154:157], v[162:165], 0
	v_mfma_f32_16x16x32_bf16 v[102:105], v[146:149], v[170:173], 0
	v_mfma_f32_16x16x32_bf16 v[98:101], v[154:157], v[170:173], 0
	v_mfma_f32_16x16x32_bf16 v[86:89], v[146:149], v[178:181], 0
	v_mfma_f32_16x16x32_bf16 v[82:85], v[154:157], v[178:181], 0
	v_mfma_f32_16x16x32_bf16 v[70:73], v[146:149], v[186:189], 0
	v_mfma_f32_16x16x32_bf16 v[66:69], v[154:157], v[186:189], 0
	v_mfma_f32_16x16x32_bf16 v[126:129], v[150:153], v[166:169], v[126:129]
	v_mfma_f32_16x16x32_bf16 v[114:117], v[158:161], v[166:169], v[114:117]
	v_mfma_f32_16x16x32_bf16 v[102:105], v[150:153], v[174:177], v[102:105]
	v_mfma_f32_16x16x32_bf16 v[98:101], v[158:161], v[174:177], v[98:101]
	v_mfma_f32_16x16x32_bf16 v[86:89], v[150:153], v[182:185], v[86:89]
	v_mfma_f32_16x16x32_bf16 v[82:85], v[158:161], v[182:185], v[82:85]
	v_mfma_f32_16x16x32_bf16 v[70:73], v[150:153], v[214:217], v[70:73]
	v_mfma_f32_16x16x32_bf16 v[66:69], v[158:161], v[214:217], v[66:69]
	s_barrier
	s_add_i32 s18, s77, s49
	s_mov_b32 m0, s18
	s_nop 0
	global_load_lds_dwordx4 v192, s[40:41]
	ds_read_b128 v[162:165], v222 offset:16384
	ds_read_b128 v[166:169], v222 offset:17408
	s_add_i32 m0, s18, 0x2000
	s_add_u32 s18, s40, 0x160000
	s_addc_u32 s19, s41, 0
	s_add_i32 s77, s79, s49
	global_load_lds_dwordx4 v208, s[40:41]
	ds_read_b128 v[170:173], v222 offset:18432
	ds_read_b128 v[174:177], v222 offset:19456
	s_mov_b32 m0, s77
	s_nop 0
	global_load_lds_dwordx4 v192, s[18:19]
	ds_read_b128 v[178:181], v222 offset:20480
	ds_read_b128 v[182:185], v222 offset:21504
	s_add_i32 m0, s77, 0x2000
	s_nop 0
	global_load_lds_dwordx4 v208, s[18:19]
	ds_read_b128 v[186:189], v222 offset:22528
	ds_read_b128 v[214:217], v222 offset:23552
	s_mov_b32 m0, s52
	s_nop 0
	global_load_lds_dwordx4 v190, s[42:43]
	s_mov_b32 m0, s53
	s_nop 0
	global_load_lds_dwordx4 v206, s[42:43]
	s_waitcnt lgkmcnt(0)
	v_mfma_f32_16x16x32_bf16 v[62:65], v[118:121], v[162:165], 0
	v_mfma_f32_16x16x32_bf16 v[58:61], v[130:133], v[162:165], 0
	v_mfma_f32_16x16x32_bf16 v[46:49], v[118:121], v[170:173], 0
	v_mfma_f32_16x16x32_bf16 v[42:45], v[130:133], v[170:173], 0
	s_waitcnt vmcnt(8)
	s_barrier
	v_mfma_f32_16x16x32_bf16 v[30:33], v[118:121], v[178:181], 0
	v_mfma_f32_16x16x32_bf16 v[26:29], v[130:133], v[178:181], 0
	v_mfma_f32_16x16x32_bf16 v[14:17], v[118:121], v[186:189], 0
	v_mfma_f32_16x16x32_bf16 v[10:13], v[130:133], v[186:189], 0
	v_mfma_f32_16x16x32_bf16 v[62:65], v[122:125], v[166:169], v[62:65]
	v_mfma_f32_16x16x32_bf16 v[58:61], v[134:137], v[166:169], v[58:61]
	v_mfma_f32_16x16x32_bf16 v[46:49], v[122:125], v[174:177], v[46:49]
	v_mfma_f32_16x16x32_bf16 v[42:45], v[134:137], v[174:177], v[42:45]
	v_mfma_f32_16x16x32_bf16 v[30:33], v[122:125], v[182:185], v[30:33]
	v_mfma_f32_16x16x32_bf16 v[26:29], v[134:137], v[182:185], v[26:29]
	v_mfma_f32_16x16x32_bf16 v[14:17], v[122:125], v[214:217], v[14:17]
	v_mfma_f32_16x16x32_bf16 v[10:13], v[134:137], v[214:217], v[10:13]
	v_mfma_f32_16x16x32_bf16 v[54:57], v[146:149], v[162:165], 0
	v_mfma_f32_16x16x32_bf16 v[50:53], v[154:157], v[162:165], 0
	v_mfma_f32_16x16x32_bf16 v[38:41], v[146:149], v[170:173], 0
	v_mfma_f32_16x16x32_bf16 v[34:37], v[154:157], v[170:173], 0
	v_mfma_f32_16x16x32_bf16 v[22:25], v[146:149], v[178:181], 0
	v_mfma_f32_16x16x32_bf16 v[18:21], v[154:157], v[178:181], 0
	v_mfma_f32_16x16x32_bf16 v[6:9], v[146:149], v[186:189], 0
	v_mfma_f32_16x16x32_bf16 v[2:5], v[154:157], v[186:189], 0
	v_mfma_f32_16x16x32_bf16 v[54:57], v[150:153], v[166:169], v[54:57]
	v_mfma_f32_16x16x32_bf16 v[50:53], v[158:161], v[166:169], v[50:53]
	v_mfma_f32_16x16x32_bf16 v[38:41], v[150:153], v[174:177], v[38:41]
	v_mfma_f32_16x16x32_bf16 v[34:37], v[158:161], v[174:177], v[34:37]
	v_mfma_f32_16x16x32_bf16 v[22:25], v[150:153], v[182:185], v[22:25]
	v_mfma_f32_16x16x32_bf16 v[18:21], v[158:161], v[182:185], v[18:21]
	v_mfma_f32_16x16x32_bf16 v[6:9], v[150:153], v[214:217], v[6:9]
	v_mfma_f32_16x16x32_bf16 v[2:5], v[158:161], v[214:217], v[2:5]
	s_barrier
; #define PG8_STAGE(bufoff, gbase, voff) do { _Pragma("unroll") for (int _i = 0; _i < 2; ++_i) \
;         __builtin_amdgcn_global_load_lds((const unsigned*)((const char*)(gbase) + (voff)[_i]), (PG8_LAS unsigned*)(lds + (bufoff) + ldsw + _i * 8192), 16, 0, 0); } while (0)
; #define PG8_LDA(dst, b, h) do { _Pragma("unroll") for (int m = 0; m < 4; ++m) _Pragma("unroll") for (int k = 0; k < 2; ++k) dst[m][k] = *(const PG8_LAS bf16x8*)(lds + PG8_SA(b, h) + aoff + m * 2048 + k * 1024); } while (0)
; #define PG8_WAIT_V(n) asm volatile("s_waitcnt vmcnt(" #n ")" ::: "memory")
; #define PG8_WAIT_L(n) asm volatile("s_waitcnt lgkmcnt(" #n ")" ::: "memory")
; #define PG8_BAR __builtin_amdgcn_s_barrier()
; template <class Epi, class Sched, bool ALIGN_EPI = false, bool SP2 = false>
; __device__ __forceinline__ void gemm_phase(PG8_LAS unsigned char* lds, const Gemm g, const Sched& S, const Epi& E, const int wave_id) {
;     ...
;         for (int t = 0; t < nt; t += 2) {
;             const bool last = (t == nt - 2);
;             const char* a1 = cA + (size_t)(t + 1) * kstep;
;             const char* a2 = last ? nA : cA + (size_t)(t + 2) * kstep; const char* b2 = last ? nB : cB + (size_t)(t + 2) * kstep;
;             const char* a3 = a2 + kstep; const char* b3 = b2 + kstep;
;             if (last && has_next) S.a_ready(nxt);
;             if constexpr (SP2) {
;             PG8_LDB(B0, 0, 0); PG8_LDB(B1, 0, 1); PG8_SCHED; PG8_LDA(At, 0, 0); PG8_STAGE(PG8_SA(1, 1), a1 + hstep, voffA);
;             PG8_WAIT_V(8); PG8_WAIT_L(0); PG8_BAR; PG8_MMA(0, 0, At, B0); PG8_MMA(0, 1, At, B1); PG8_BAR; PG8_SCHED;
;             PG8_LDA(At, 0, 1); PG8_STAGE(PG8_SB(0, 0), b2, voffB); PG8_STAGE(PG8_SB(0, 1), b2 + hstep, voffB); PG8_STAGE(PG8_SA(0, 0), a2, voffA);
;             PG8_WAIT_V(8); PG8_WAIT_L(0); PG8_BAR; PG8_MMA(1, 0, At, B0); PG8_MMA(1, 1, At, B1); PG8_BAR; PG8_SCHED;
;             PG8_LDB(B0, 1, 0); PG8_LDB(B1, 1, 1); PG8_SCHED; PG8_LDA(At, 1, 0); PG8_STAGE(PG8_SA(0, 1), a2 + hstep, voffA);
;             PG8_WAIT_V(8); PG8_WAIT_L(0); PG8_BAR; PG8_MMA(0, 0, At, B0); PG8_MMA(0, 1, At, B1); PG8_BAR; PG8_SCHED;
;             PG8_LDA(At, 1, 1); PG8_STAGE(PG8_SB(1, 0), b3, voffB); PG8_STAGE(PG8_SB(1, 1), b3 + hstep, voffB); PG8_STAGE(PG8_SA(1, 0), a3, voffA);
;             PG8_WAIT_V(8); PG8_WAIT_L(0); PG8_BAR; PG8_MMA(1, 0, At, B0); PG8_MMA(1, 1, At, B1); PG8_BAR; PG8_SCHED;
	s_add_i32 s77, 0, 0x18000
	s_add_i32 s79, 0, 0x1c000
	s_add_u32 s18, s42, 0x160000
	s_addc_u32 s19, s43, 0
	s_mov_b32 m0, s56
	s_nop 0
	global_load_lds_dwordx4 v190, s[18:19]
	ds_read_b128 v[118:121], v226 offset:32768
	ds_read_b128 v[122:125], v226 offset:33792
	ds_read_b128 v[130:133], v226 offset:34816
	ds_read_b128 v[134:137], v226 offset:35840
	ds_read_b128 v[146:149], v226 offset:49152
	ds_read_b128 v[150:153], v226 offset:50176
	ds_read_b128 v[154:157], v226 offset:51200
	ds_read_b128 v[158:161], v226 offset:52224
	s_mov_b32 m0, s57
	s_nop 0
	global_load_lds_dwordx4 v206, s[18:19]
	ds_read_b128 v[162:165], v222 offset:32768
	ds_read_b128 v[166:169], v222 offset:33792
	ds_read_b128 v[170:173], v222 offset:34816
	ds_read_b128 v[174:177], v222 offset:35840
	ds_read_b128 v[178:181], v222 offset:36864
	ds_read_b128 v[182:185], v222 offset:37888
	ds_read_b128 v[186:189], v222 offset:38912
	ds_read_b128 v[214:217], v222 offset:39936
	s_waitcnt lgkmcnt(0)
	v_mfma_f32_16x16x32_bf16 v[142:145], v[118:121], v[162:165], v[142:145]
	v_mfma_f32_16x16x32_bf16 v[138:141], v[130:133], v[162:165], v[138:141]
	v_mfma_f32_16x16x32_bf16 v[110:113], v[118:121], v[170:173], v[110:113]
	v_mfma_f32_16x16x32_bf16 v[106:109], v[130:133], v[170:173], v[106:109]
	s_waitcnt vmcnt(8)
	s_barrier
	v_mfma_f32_16x16x32_bf16 v[94:97], v[118:121], v[178:181], v[94:97]
	v_mfma_f32_16x16x32_bf16 v[90:93], v[130:133], v[178:181], v[90:93]
	v_mfma_f32_16x16x32_bf16 v[78:81], v[118:121], v[186:189], v[78:81]
	v_mfma_f32_16x16x32_bf16 v[74:77], v[130:133], v[186:189], v[74:77]
	v_mfma_f32_16x16x32_bf16 v[142:145], v[122:125], v[166:169], v[142:145]
	v_mfma_f32_16x16x32_bf16 v[138:141], v[134:137], v[166:169], v[138:141]
	v_mfma_f32_16x16x32_bf16 v[110:113], v[122:125], v[174:177], v[110:113]
	v_mfma_f32_16x16x32_bf16 v[106:109], v[134:137], v[174:177], v[106:109]
	v_mfma_f32_16x16x32_bf16 v[94:97], v[122:125], v[182:185], v[94:97]
	v_mfma_f32_16x16x32_bf16 v[90:93], v[134:137], v[182:185], v[90:93]
	v_mfma_f32_16x16x32_bf16 v[78:81], v[122:125], v[214:217], v[78:81]
	v_mfma_f32_16x16x32_bf16 v[74:77], v[134:137], v[214:217], v[74:77]
	v_mfma_f32_16x16x32_bf16 v[126:129], v[146:149], v[162:165], v[126:129]
	v_mfma_f32_16x16x32_bf16 v[114:117], v[154:157], v[162:165], v[114:117]
	v_mfma_f32_16x16x32_bf16 v[102:105], v[146:149], v[170:173], v[102:105]
	v_mfma_f32_16x16x32_bf16 v[98:101], v[154:157], v[170:173], v[98:101]
	v_mfma_f32_16x16x32_bf16 v[86:89], v[146:149], v[178:181], v[86:89]
	v_mfma_f32_16x16x32_bf16 v[82:85], v[154:157], v[178:181], v[82:85]
	v_mfma_f32_16x16x32_bf16 v[70:73], v[146:149], v[186:189], v[70:73]
	v_mfma_f32_16x16x32_bf16 v[66:69], v[154:157], v[186:189], v[66:69]
	v_mfma_f32_16x16x32_bf16 v[126:129], v[150:153], v[166:169], v[126:129]
	v_mfma_f32_16x16x32_bf16 v[114:117], v[158:161], v[166:169], v[114:117]
	v_mfma_f32_16x16x32_bf16 v[102:105], v[150:153], v[174:177], v[102:105]
	v_mfma_f32_16x16x32_bf16 v[98:101], v[158:161], v[174:177], v[98:101]
	v_mfma_f32_16x16x32_bf16 v[86:89], v[150:153], v[182:185], v[86:89]
	v_mfma_f32_16x16x32_bf16 v[82:85], v[158:161], v[182:185], v[82:85]
	v_mfma_f32_16x16x32_bf16 v[70:73], v[150:153], v[214:217], v[70:73]
	v_mfma_f32_16x16x32_bf16 v[66:69], v[158:161], v[214:217], v[66:69]
	s_barrier
	s_add_u32 vcc_lo, s42, 0x80
	s_addc_u32 vcc_hi, s43, 0
	s_mov_b32 m0, s68
	s_nop 0
	global_load_lds_dwordx4 v190, vcc
	ds_read_b128 v[162:165], v222 offset:49152
	ds_read_b128 v[166:169], v222 offset:50176
	s_mov_b32 m0, s69
	s_add_i32 s18, s77, s49
	global_load_lds_dwordx4 v206, vcc
	ds_read_b128 v[170:173], v222 offset:51200
	ds_read_b128 v[174:177], v222 offset:52224
	s_add_u32 vcc_lo, s40, 0x80
	s_addc_u32 vcc_hi, s41, 0
	s_mov_b32 m0, s18
	s_nop 0
	global_load_lds_dwordx4 v192, vcc
	ds_read_b128 v[178:181], v222 offset:53248
	ds_read_b128 v[182:185], v222 offset:54272
	s_add_i32 m0, s18, 0x2000
	s_add_u32 s18, s40, 0x160080
	s_addc_u32 s19, s41, 0
	global_load_lds_dwordx4 v208, vcc
	ds_read_b128 v[186:189], v222 offset:55296
	ds_read_b128 v[214:217], v222 offset:56320
	s_add_i32 s40, s79, s49
	s_mov_b32 m0, s40
	s_nop 0
	global_load_lds_dwordx4 v192, s[18:19]
	s_add_i32 m0, s40, 0x2000
	s_nop 0
	global_load_lds_dwordx4 v208, s[18:19]
	s_waitcnt lgkmcnt(0)
	v_mfma_f32_16x16x32_bf16 v[62:65], v[118:121], v[162:165], v[62:65]
	v_mfma_f32_16x16x32_bf16 v[58:61], v[130:133], v[162:165], v[58:61]
	v_mfma_f32_16x16x32_bf16 v[46:49], v[118:121], v[170:173], v[46:49]
	v_mfma_f32_16x16x32_bf16 v[42:45], v[130:133], v[170:173], v[42:45]
	s_waitcnt vmcnt(8)
	s_barrier
	v_mfma_f32_16x16x32_bf16 v[30:33], v[118:121], v[178:181], v[30:33]
	v_mfma_f32_16x16x32_bf16 v[26:29], v[130:133], v[178:181], v[26:29]
	v_mfma_f32_16x16x32_bf16 v[14:17], v[118:121], v[186:189], v[14:17]
	v_mfma_f32_16x16x32_bf16 v[10:13], v[130:133], v[186:189], v[10:13]
	v_mfma_f32_16x16x32_bf16 v[62:65], v[122:125], v[166:169], v[62:65]
	v_mfma_f32_16x16x32_bf16 v[58:61], v[134:137], v[166:169], v[58:61]
	v_mfma_f32_16x16x32_bf16 v[46:49], v[122:125], v[174:177], v[46:49]
	v_mfma_f32_16x16x32_bf16 v[42:45], v[134:137], v[174:177], v[42:45]
	v_mfma_f32_16x16x32_bf16 v[30:33], v[122:125], v[182:185], v[30:33]
	v_mfma_f32_16x16x32_bf16 v[26:29], v[134:137], v[182:185], v[26:29]
	v_mfma_f32_16x16x32_bf16 v[14:17], v[122:125], v[214:217], v[14:17]
	v_mfma_f32_16x16x32_bf16 v[10:13], v[134:137], v[214:217], v[10:13]
	v_mfma_f32_16x16x32_bf16 v[54:57], v[146:149], v[162:165], v[54:57]
	v_mfma_f32_16x16x32_bf16 v[50:53], v[154:157], v[162:165], v[50:53]
	v_mfma_f32_16x16x32_bf16 v[38:41], v[146:149], v[170:173], v[38:41]
	v_mfma_f32_16x16x32_bf16 v[34:37], v[154:157], v[170:173], v[34:37]
	v_mfma_f32_16x16x32_bf16 v[22:25], v[146:149], v[178:181], v[22:25]
	v_mfma_f32_16x16x32_bf16 v[18:21], v[154:157], v[178:181], v[18:21]
	v_mfma_f32_16x16x32_bf16 v[6:9], v[146:149], v[186:189], v[6:9]
	v_mfma_f32_16x16x32_bf16 v[2:5], v[154:157], v[186:189], v[2:5]
	v_mfma_f32_16x16x32_bf16 v[54:57], v[150:153], v[166:169], v[54:57]
	v_mfma_f32_16x16x32_bf16 v[50:53], v[158:161], v[166:169], v[50:53]
	v_mfma_f32_16x16x32_bf16 v[38:41], v[150:153], v[174:177], v[38:41]
	v_mfma_f32_16x16x32_bf16 v[34:37], v[158:161], v[174:177], v[34:37]
	v_mfma_f32_16x16x32_bf16 v[22:25], v[150:153], v[182:185], v[22:25]
	v_mfma_f32_16x16x32_bf16 v[18:21], v[158:161], v[182:185], v[18:21]
	v_mfma_f32_16x16x32_bf16 v[6:9], v[150:153], v[214:217], v[6:9]
	v_mfma_f32_16x16x32_bf16 v[2:5], v[158:161], v[214:217], v[2:5]
	s_barrier
	s_add_i32 s76, s76, 2
	s_add_u32 s74, s74, 0x100
	s_addc_u32 s75, s75, 0
	s_cmpk_gt_u32 s76, 0x55
	s_mov_b64 s[18:19], s[20:21]
	s_cbranch_scc1 .Lpeel_exit_g4
; #define PG8_STAGE(bufoff, gbase, voff) do { _Pragma("unroll") for (int _i = 0; _i < 2; ++_i) \
;         __builtin_amdgcn_global_load_lds((const unsigned*)((const char*)(gbase) + (voff)[_i]), (PG8_LAS unsigned*)(lds + (bufoff) + ldsw + _i * 8192), 16, 0, 0); } while (0)
; #define PG8_LDA(dst, b, h) do { _Pragma("unroll") for (int m = 0; m < 4; ++m) _Pragma("unroll") for (int k = 0; k < 2; ++k) dst[m][k] = *(const PG8_LAS bf16x8*)(lds + PG8_SA(b, h) + aoff + m * 2048 + k * 1024); } while (0)
; #define PG8_WAIT_V(n) asm volatile("s_waitcnt vmcnt(" #n ")" ::: "memory")
; #define PG8_WAIT_L(n) asm volatile("s_waitcnt lgkmcnt(" #n ")" ::: "memory")
; #define PG8_BAR __builtin_amdgcn_s_barrier()
; template <class Epi, class Sched, bool ALIGN_EPI = false, bool SP2 = false>
; __device__ __forceinline__ void gemm_phase(PG8_LAS unsigned char* lds, const Gemm g, const Sched& S, const Epi& E, const int wave_id) {
;     ...
;         for (int t = 0; t < nt; t += 2) {
;             const bool last = (t == nt - 2);
;             const char* a1 = cA + (size_t)(t + 1) * kstep;
;             const char* a2 = last ? nA : cA + (size_t)(t + 2) * kstep; const char* b2 = last ? nB : cB + (size_t)(t + 2) * kstep;
;             const char* a3 = a2 + kstep; const char* b3 = b2 + kstep;
;             if (last && has_next) S.a_ready(nxt);
;             if constexpr (SP2) {
;             PG8_LDB(B0, 0, 0); PG8_LDB(B1, 0, 1); PG8_SCHED; PG8_LDA(At, 0, 0); PG8_STAGE(PG8_SA(1, 1), a1 + hstep, voffA);
;             PG8_WAIT_V(8); PG8_WAIT_L(0); PG8_BAR; PG8_MMA(0, 0, At, B0); PG8_MMA(0, 1, At, B1); PG8_BAR; PG8_SCHED;
;             PG8_LDA(At, 0, 1); PG8_STAGE(PG8_SB(0, 0), b2, voffB); PG8_STAGE(PG8_SB(0, 1), b2 + hstep, voffB); PG8_STAGE(PG8_SA(0, 0), a2, voffA);
;             PG8_WAIT_V(8); PG8_WAIT_L(0); PG8_BAR; PG8_MMA(1, 0, At, B0); PG8_MMA(1, 1, At, B1); PG8_BAR; PG8_SCHED;
;             PG8_LDB(B0, 1, 0); PG8_LDB(B1, 1, 1); PG8_SCHED; PG8_LDA(At, 1, 0); PG8_STAGE(PG8_SA(0, 1), a2 + hstep, voffA);
;             PG8_WAIT_V(8); PG8_WAIT_L(0); PG8_BAR; PG8_MMA(0, 0, At, B0); PG8_MMA(0, 1, At, B1); PG8_BAR; PG8_SCHED;
;             PG8_LDA(At, 1, 1); PG8_STAGE(PG8_SB(1, 0), b3, voffB); PG8_STAGE(PG8_SB(1, 1), b3 + hstep, voffB); PG8_STAGE(PG8_SA(1, 0), a3, voffA);
;             PG8_WAIT_V(8); PG8_WAIT_L(0); PG8_BAR; PG8_MMA(1, 0, At, B0); PG8_MMA(1, 1, At, B1); PG8_BAR; PG8_SCHED;
.LBB0_759:
	s_add_u32 s20, s18, 0x100
	s_addc_u32 s21, s19, 0
	s_add_i32 s77, 0, 0x10000
	s_cmpk_eq_i32 s76, 0x54
	s_cselect_b32 s43, s15, s21
	s_cselect_b32 s42, s14, s20
	s_cselect_b32 s41, s17, s75
	s_cselect_b32 s40, s16, s74
	s_add_i32 s79, 0, 0x14000
	s_add_i32 m0, s52, 0xc000
	s_nop 0
	global_load_lds_dwordx4 v210, s[18:19]
	ds_read_b128 v[118:121], v226
	ds_read_b128 v[122:125], v226 offset:1024
	ds_read_b128 v[130:133], v226 offset:2048
	ds_read_b128 v[134:137], v226 offset:3072
	ds_read_b128 v[146:149], v226 offset:16384
	ds_read_b128 v[150:153], v226 offset:17408
	ds_read_b128 v[154:157], v226 offset:18432
	ds_read_b128 v[158:161], v226 offset:19456
	s_add_i32 m0, s52, 0xe000
	s_nop 0
	global_load_lds_dwordx4 v212, s[18:19]
	ds_read_b128 v[162:165], v222
	ds_read_b128 v[166:169], v222 offset:1024
	ds_read_b128 v[170:173], v222 offset:2048
	ds_read_b128 v[174:177], v222 offset:3072
	ds_read_b128 v[178:181], v222 offset:4096
	ds_read_b128 v[182:185], v222 offset:5120
	ds_read_b128 v[186:189], v222 offset:6144
	ds_read_b128 v[214:217], v222 offset:7168
	s_waitcnt lgkmcnt(0)
	v_mfma_f32_16x16x32_bf16 v[142:145], v[118:121], v[162:165], v[142:145]
	v_mfma_f32_16x16x32_bf16 v[138:141], v[130:133], v[162:165], v[138:141]
	v_mfma_f32_16x16x32_bf16 v[110:113], v[118:121], v[170:173], v[110:113]
	v_mfma_f32_16x16x32_bf16 v[106:109], v[130:133], v[170:173], v[106:109]
	s_waitcnt vmcnt(8)
	s_barrier
	v_mfma_f32_16x16x32_bf16 v[94:97], v[118:121], v[178:181], v[94:97]
	v_mfma_f32_16x16x32_bf16 v[90:93], v[130:133], v[178:181], v[90:93]
	v_mfma_f32_16x16x32_bf16 v[78:81], v[118:121], v[186:189], v[78:81]
	v_mfma_f32_16x16x32_bf16 v[74:77], v[130:133], v[186:189], v[74:77]
	v_mfma_f32_16x16x32_bf16 v[142:145], v[122:125], v[166:169], v[142:145]
	v_mfma_f32_16x16x32_bf16 v[138:141], v[134:137], v[166:169], v[138:141]
	v_mfma_f32_16x16x32_bf16 v[110:113], v[122:125], v[174:177], v[110:113]
	v_mfma_f32_16x16x32_bf16 v[106:109], v[134:137], v[174:177], v[106:109]
	v_mfma_f32_16x16x32_bf16 v[94:97], v[122:125], v[182:185], v[94:97]
	v_mfma_f32_16x16x32_bf16 v[90:93], v[134:137], v[182:185], v[90:93]
	v_mfma_f32_16x16x32_bf16 v[78:81], v[122:125], v[214:217], v[78:81]
	v_mfma_f32_16x16x32_bf16 v[74:77], v[134:137], v[214:217], v[74:77]
	v_mfma_f32_16x16x32_bf16 v[126:129], v[146:149], v[162:165], v[126:129]
	v_mfma_f32_16x16x32_bf16 v[114:117], v[154:157], v[162:165], v[114:117]
	v_mfma_f32_16x16x32_bf16 v[102:105], v[146:149], v[170:173], v[102:105]
	v_mfma_f32_16x16x32_bf16 v[98:101], v[154:157], v[170:173], v[98:101]
	v_mfma_f32_16x16x32_bf16 v[86:89], v[146:149], v[178:181], v[86:89]
	v_mfma_f32_16x16x32_bf16 v[82:85], v[154:157], v[178:181], v[82:85]
	v_mfma_f32_16x16x32_bf16 v[70:73], v[146:149], v[186:189], v[70:73]
	v_mfma_f32_16x16x32_bf16 v[66:69], v[154:157], v[186:189], v[66:69]
	v_mfma_f32_16x16x32_bf16 v[126:129], v[150:153], v[166:169], v[126:129]
	v_mfma_f32_16x16x32_bf16 v[114:117], v[158:161], v[166:169], v[114:117]
	v_mfma_f32_16x16x32_bf16 v[102:105], v[150:153], v[174:177], v[102:105]
	v_mfma_f32_16x16x32_bf16 v[98:101], v[158:161], v[174:177], v[98:101]
	v_mfma_f32_16x16x32_bf16 v[86:89], v[150:153], v[182:185], v[86:89]
	v_mfma_f32_16x16x32_bf16 v[82:85], v[158:161], v[182:185], v[82:85]
	v_mfma_f32_16x16x32_bf16 v[70:73], v[150:153], v[214:217], v[70:73]
	v_mfma_f32_16x16x32_bf16 v[66:69], v[158:161], v[214:217], v[66:69]
	s_barrier
	s_add_i32 s18, s77, s49
	s_mov_b32 m0, s18
	s_nop 0
	global_load_lds_dwordx4 v192, s[40:41]
	ds_read_b128 v[162:165], v222 offset:16384
	ds_read_b128 v[166:169], v222 offset:17408
	s_add_i32 m0, s18, 0x2000
	s_add_u32 s18, s40, 0x160000
	s_addc_u32 s19, s41, 0
	s_add_i32 s77, s79, s49
	global_load_lds_dwordx4 v208, s[40:41]
	ds_read_b128 v[170:173], v222 offset:18432
	ds_read_b128 v[174:177], v222 offset:19456
	s_mov_b32 m0, s77
	s_nop 0
	global_load_lds_dwordx4 v192, s[18:19]
	ds_read_b128 v[178:181], v222 offset:20480
	ds_read_b128 v[182:185], v222 offset:21504
	s_add_i32 m0, s77, 0x2000
	s_nop 0
	global_load_lds_dwordx4 v208, s[18:19]
	ds_read_b128 v[186:189], v222 offset:22528
	ds_read_b128 v[214:217], v222 offset:23552
	s_mov_b32 m0, s52
	s_nop 0
	global_load_lds_dwordx4 v190, s[42:43]
	s_mov_b32 m0, s53
	s_nop 0
	global_load_lds_dwordx4 v206, s[42:43]
	s_waitcnt lgkmcnt(0)
	v_mfma_f32_16x16x32_bf16 v[62:65], v[118:121], v[162:165], v[62:65]
	v_mfma_f32_16x16x32_bf16 v[58:61], v[130:133], v[162:165], v[58:61]
	v_mfma_f32_16x16x32_bf16 v[46:49], v[118:121], v[170:173], v[46:49]
	v_mfma_f32_16x16x32_bf16 v[42:45], v[130:133], v[170:173], v[42:45]
	s_waitcnt vmcnt(8)
	s_barrier
	v_mfma_f32_16x16x32_bf16 v[30:33], v[118:121], v[178:181], v[30:33]
	v_mfma_f32_16x16x32_bf16 v[26:29], v[130:133], v[178:181], v[26:29]
	v_mfma_f32_16x16x32_bf16 v[14:17], v[118:121], v[186:189], v[14:17]
	v_mfma_f32_16x16x32_bf16 v[10:13], v[130:133], v[186:189], v[10:13]
	v_mfma_f32_16x16x32_bf16 v[62:65], v[122:125], v[166:169], v[62:65]
	v_mfma_f32_16x16x32_bf16 v[58:61], v[134:137], v[166:169], v[58:61]
	v_mfma_f32_16x16x32_bf16 v[46:49], v[122:125], v[174:177], v[46:49]
	v_mfma_f32_16x16x32_bf16 v[42:45], v[134:137], v[174:177], v[42:45]
	v_mfma_f32_16x16x32_bf16 v[30:33], v[122:125], v[182:185], v[30:33]
	v_mfma_f32_16x16x32_bf16 v[26:29], v[134:137], v[182:185], v[26:29]
	v_mfma_f32_16x16x32_bf16 v[14:17], v[122:125], v[214:217], v[14:17]
	v_mfma_f32_16x16x32_bf16 v[10:13], v[134:137], v[214:217], v[10:13]
	v_mfma_f32_16x16x32_bf16 v[54:57], v[146:149], v[162:165], v[54:57]
	v_mfma_f32_16x16x32_bf16 v[50:53], v[154:157], v[162:165], v[50:53]
	v_mfma_f32_16x16x32_bf16 v[38:41], v[146:149], v[170:173], v[38:41]
	v_mfma_f32_16x16x32_bf16 v[34:37], v[154:157], v[170:173], v[34:37]
	v_mfma_f32_16x16x32_bf16 v[22:25], v[146:149], v[178:181], v[22:25]
	v_mfma_f32_16x16x32_bf16 v[18:21], v[154:157], v[178:181], v[18:21]
	v_mfma_f32_16x16x32_bf16 v[6:9], v[146:149], v[186:189], v[6:9]
	v_mfma_f32_16x16x32_bf16 v[2:5], v[154:157], v[186:189], v[2:5]
	v_mfma_f32_16x16x32_bf16 v[54:57], v[150:153], v[166:169], v[54:57]
	v_mfma_f32_16x16x32_bf16 v[50:53], v[158:161], v[166:169], v[50:53]
	v_mfma_f32_16x16x32_bf16 v[38:41], v[150:153], v[174:177], v[38:41]
	v_mfma_f32_16x16x32_bf16 v[34:37], v[158:161], v[174:177], v[34:37]
	v_mfma_f32_16x16x32_bf16 v[22:25], v[150:153], v[182:185], v[22:25]
	v_mfma_f32_16x16x32_bf16 v[18:21], v[158:161], v[182:185], v[18:21]
	v_mfma_f32_16x16x32_bf16 v[6:9], v[150:153], v[214:217], v[6:9]
	v_mfma_f32_16x16x32_bf16 v[2:5], v[158:161], v[214:217], v[2:5]
	s_barrier
; #define PG8_STAGE(bufoff, gbase, voff) do { _Pragma("unroll") for (int _i = 0; _i < 2; ++_i) \
;         __builtin_amdgcn_global_load_lds((const unsigned*)((const char*)(gbase) + (voff)[_i]), (PG8_LAS unsigned*)(lds + (bufoff) + ldsw + _i * 8192), 16, 0, 0); } while (0)
; #define PG8_LDA(dst, b, h) do { _Pragma("unroll") for (int m = 0; m < 4; ++m) _Pragma("unroll") for (int k = 0; k < 2; ++k) dst[m][k] = *(const PG8_LAS bf16x8*)(lds + PG8_SA(b, h) + aoff + m * 2048 + k * 1024); } while (0)
; #define PG8_LDB(dst, b, h) do { _Pragma("unroll") for (int n = 0; n < 2; ++n) _Pragma("unroll") for (int k = 0; k < 2; ++k) dst[n][k] = *(const PG8_LAS bf16x8*)(lds + PG8_SB(b, h) + boff + n * 2048 + k * 1024); } while (0)
; #define PG8_MMA(ai, bj, At, Bt) do { __builtin_amdgcn_s_setprio(1); _Pragma("unroll") for (int m = 0; m < 4; ++m) _Pragma("unroll") for (int n = 0; n < 2; ++n) _Pragma("unroll") for (int k = 0; k < 2; ++k) \
;         acc[ai][bj][m][n] = __builtin_amdgcn_mfma_f32_16x16x32_bf16(Bt[n][k], At[m][k], acc[ai][bj][m][n], 0, 0, 0); __builtin_amdgcn_s_setprio(0); } while (0)
; #define PG8_BAR __builtin_amdgcn_s_barrier()
; template <class Epi, class Sched, bool ALIGN_EPI = false, bool SP2 = false>
; __device__ __forceinline__ void gemm_phase(PG8_LAS unsigned char* lds, const Gemm g, const Sched& S, const Epi& E, const int wave_id) {
;     ...
;             PG8_LDB(B0, 0, 0); PG8_LDB(B1, 0, 1); PG8_SCHED; PG8_LDA(At, 0, 0); PG8_STAGE(PG8_SA(1, 1), a1 + hstep, voffA);
;             PG8_WAIT_V(8); PG8_WAIT_L(0); PG8_BAR; PG8_MMA(0, 0, At, B0); PG8_MMA(0, 1, At, B1); PG8_BAR; PG8_SCHED;
;             PG8_LDA(At, 0, 1); PG8_STAGE(PG8_SB(0, 0), b2, voffB); PG8_STAGE(PG8_SB(0, 1), b2 + hstep, voffB); PG8_STAGE(PG8_SA(0, 0), a2, voffA);
;             PG8_WAIT_V(8); PG8_WAIT_L(0); PG8_BAR; PG8_MMA(1, 0, At, B0); PG8_MMA(1, 1, At, B1); PG8_BAR; PG8_SCHED;
;             PG8_LDB(B0, 1, 0); PG8_LDB(B1, 1, 1); PG8_SCHED; PG8_LDA(At, 1, 0); PG8_STAGE(PG8_SA(0, 1), a2 + hstep, voffA);
;             PG8_WAIT_V(8); PG8_WAIT_L(0); PG8_BAR; PG8_MMA(0, 0, At, B0); PG8_MMA(0, 1, At, B1); PG8_BAR; PG8_SCHED;
;             PG8_LDA(At, 1, 1); PG8_STAGE(PG8_SB(1, 0), b3, voffB); PG8_STAGE(PG8_SB(1, 1), b3 + hstep, voffB); PG8_STAGE(PG8_SA(1, 0), a3, voffA);
;             PG8_WAIT_V(8); PG8_WAIT_L(0); PG8_BAR; PG8_MMA(1, 0, At, B0); PG8_MMA(1, 1, At, B1); PG8_BAR; PG8_SCHED;
	s_add_i32 s77, 0, 0x18000
	s_add_i32 s79, 0, 0x1c000
	s_add_u32 s18, s42, 0x160000
	s_addc_u32 s19, s43, 0
	s_mov_b32 m0, s56
	s_nop 0
	global_load_lds_dwordx4 v190, s[18:19]
	ds_read_b128 v[118:121], v226 offset:32768
	ds_read_b128 v[122:125], v226 offset:33792
	ds_read_b128 v[130:133], v226 offset:34816
	ds_read_b128 v[134:137], v226 offset:35840
	ds_read_b128 v[146:149], v226 offset:49152
	ds_read_b128 v[150:153], v226 offset:50176
	ds_read_b128 v[154:157], v226 offset:51200
	ds_read_b128 v[158:161], v226 offset:52224
	s_mov_b32 m0, s57
	s_nop 0
	global_load_lds_dwordx4 v206, s[18:19]
	ds_read_b128 v[162:165], v222 offset:32768
	ds_read_b128 v[166:169], v222 offset:33792
	ds_read_b128 v[170:173], v222 offset:34816
	ds_read_b128 v[174:177], v222 offset:35840
	ds_read_b128 v[178:181], v222 offset:36864
	ds_read_b128 v[182:185], v222 offset:37888
	ds_read_b128 v[186:189], v222 offset:38912
	ds_read_b128 v[214:217], v222 offset:39936
	s_waitcnt lgkmcnt(0)
	v_mfma_f32_16x16x32_bf16 v[142:145], v[118:121], v[162:165], v[142:145]
	v_mfma_f32_16x16x32_bf16 v[138:141], v[130:133], v[162:165], v[138:141]
	v_mfma_f32_16x16x32_bf16 v[110:113], v[118:121], v[170:173], v[110:113]
	v_mfma_f32_16x16x32_bf16 v[106:109], v[130:133], v[170:173], v[106:109]
	s_waitcnt vmcnt(8)
	s_barrier
	v_mfma_f32_16x16x32_bf16 v[94:97], v[118:121], v[178:181], v[94:97]
	v_mfma_f32_16x16x32_bf16 v[90:93], v[130:133], v[178:181], v[90:93]
	v_mfma_f32_16x16x32_bf16 v[78:81], v[118:121], v[186:189], v[78:81]
	v_mfma_f32_16x16x32_bf16 v[74:77], v[130:133], v[186:189], v[74:77]
	v_mfma_f32_16x16x32_bf16 v[142:145], v[122:125], v[166:169], v[142:145]
	v_mfma_f32_16x16x32_bf16 v[138:141], v[134:137], v[166:169], v[138:141]
	v_mfma_f32_16x16x32_bf16 v[110:113], v[122:125], v[174:177], v[110:113]
	v_mfma_f32_16x16x32_bf16 v[106:109], v[134:137], v[174:177], v[106:109]
	v_mfma_f32_16x16x32_bf16 v[94:97], v[122:125], v[182:185], v[94:97]
	v_mfma_f32_16x16x32_bf16 v[90:93], v[134:137], v[182:185], v[90:93]
	v_mfma_f32_16x16x32_bf16 v[78:81], v[122:125], v[214:217], v[78:81]
	v_mfma_f32_16x16x32_bf16 v[74:77], v[134:137], v[214:217], v[74:77]
	v_mfma_f32_16x16x32_bf16 v[126:129], v[146:149], v[162:165], v[126:129]
	v_mfma_f32_16x16x32_bf16 v[114:117], v[154:157], v[162:165], v[114:117]
	v_mfma_f32_16x16x32_bf16 v[102:105], v[146:149], v[170:173], v[102:105]
	v_mfma_f32_16x16x32_bf16 v[98:101], v[154:157], v[170:173], v[98:101]
	v_mfma_f32_16x16x32_bf16 v[86:89], v[146:149], v[178:181], v[86:89]
	v_mfma_f32_16x16x32_bf16 v[82:85], v[154:157], v[178:181], v[82:85]
	v_mfma_f32_16x16x32_bf16 v[70:73], v[146:149], v[186:189], v[70:73]
	v_mfma_f32_16x16x32_bf16 v[66:69], v[154:157], v[186:189], v[66:69]
	v_mfma_f32_16x16x32_bf16 v[126:129], v[150:153], v[166:169], v[126:129]
	v_mfma_f32_16x16x32_bf16 v[114:117], v[158:161], v[166:169], v[114:117]
	v_mfma_f32_16x16x32_bf16 v[102:105], v[150:153], v[174:177], v[102:105]
	v_mfma_f32_16x16x32_bf16 v[98:101], v[158:161], v[174:177], v[98:101]
	v_mfma_f32_16x16x32_bf16 v[86:89], v[150:153], v[182:185], v[86:89]
	v_mfma_f32_16x16x32_bf16 v[82:85], v[158:161], v[182:185], v[82:85]
	v_mfma_f32_16x16x32_bf16 v[70:73], v[150:153], v[214:217], v[70:73]
	v_mfma_f32_16x16x32_bf16 v[66:69], v[158:161], v[214:217], v[66:69]
	s_barrier
	s_add_u32 vcc_lo, s42, 0x80
	s_addc_u32 vcc_hi, s43, 0
	s_mov_b32 m0, s68
	s_nop 0
	global_load_lds_dwordx4 v190, vcc
	ds_read_b128 v[162:165], v222 offset:49152
	ds_read_b128 v[166:169], v222 offset:50176
	s_mov_b32 m0, s69
	s_add_i32 s18, s77, s49
	global_load_lds_dwordx4 v206, vcc
	ds_read_b128 v[170:173], v222 offset:51200
	ds_read_b128 v[174:177], v222 offset:52224
	s_add_u32 vcc_lo, s40, 0x80
	s_addc_u32 vcc_hi, s41, 0
	s_mov_b32 m0, s18
	s_nop 0
	global_load_lds_dwordx4 v192, vcc
	ds_read_b128 v[178:181], v222 offset:53248
	ds_read_b128 v[182:185], v222 offset:54272
	s_add_i32 m0, s18, 0x2000
	s_add_u32 s18, s40, 0x160080
	s_addc_u32 s19, s41, 0
	global_load_lds_dwordx4 v208, vcc
	ds_read_b128 v[186:189], v222 offset:55296
	ds_read_b128 v[214:217], v222 offset:56320
	s_add_i32 s40, s79, s49
	s_mov_b32 m0, s40
	s_nop 0
	global_load_lds_dwordx4 v192, s[18:19]
	s_add_i32 m0, s40, 0x2000
	s_nop 0
	global_load_lds_dwordx4 v208, s[18:19]
	s_waitcnt lgkmcnt(0)
	v_mfma_f32_16x16x32_bf16 v[62:65], v[118:121], v[162:165], v[62:65]
	v_mfma_f32_16x16x32_bf16 v[58:61], v[130:133], v[162:165], v[58:61]
	v_mfma_f32_16x16x32_bf16 v[46:49], v[118:121], v[170:173], v[46:49]
	v_mfma_f32_16x16x32_bf16 v[42:45], v[130:133], v[170:173], v[42:45]
	s_waitcnt vmcnt(8)
	s_barrier
	v_mfma_f32_16x16x32_bf16 v[30:33], v[118:121], v[178:181], v[30:33]
	v_mfma_f32_16x16x32_bf16 v[26:29], v[130:133], v[178:181], v[26:29]
	v_mfma_f32_16x16x32_bf16 v[14:17], v[118:121], v[186:189], v[14:17]
	v_mfma_f32_16x16x32_bf16 v[10:13], v[130:133], v[186:189], v[10:13]
	v_mfma_f32_16x16x32_bf16 v[62:65], v[122:125], v[166:169], v[62:65]
	v_mfma_f32_16x16x32_bf16 v[58:61], v[134:137], v[166:169], v[58:61]
	v_mfma_f32_16x16x32_bf16 v[46:49], v[122:125], v[174:177], v[46:49]
	v_mfma_f32_16x16x32_bf16 v[42:45], v[134:137], v[174:177], v[42:45]
	v_mfma_f32_16x16x32_bf16 v[30:33], v[122:125], v[182:185], v[30:33]
	v_mfma_f32_16x16x32_bf16 v[26:29], v[134:137], v[182:185], v[26:29]
	v_mfma_f32_16x16x32_bf16 v[14:17], v[122:125], v[214:217], v[14:17]
	v_mfma_f32_16x16x32_bf16 v[10:13], v[134:137], v[214:217], v[10:13]
	v_mfma_f32_16x16x32_bf16 v[54:57], v[146:149], v[162:165], v[54:57]
	v_mfma_f32_16x16x32_bf16 v[50:53], v[154:157], v[162:165], v[50:53]
	v_mfma_f32_16x16x32_bf16 v[38:41], v[146:149], v[170:173], v[38:41]
	v_mfma_f32_16x16x32_bf16 v[34:37], v[154:157], v[170:173], v[34:37]
	v_mfma_f32_16x16x32_bf16 v[22:25], v[146:149], v[178:181], v[22:25]
	v_mfma_f32_16x16x32_bf16 v[18:21], v[154:157], v[178:181], v[18:21]
	v_mfma_f32_16x16x32_bf16 v[6:9], v[146:149], v[186:189], v[6:9]
	v_mfma_f32_16x16x32_bf16 v[2:5], v[154:157], v[186:189], v[2:5]
	v_mfma_f32_16x16x32_bf16 v[54:57], v[150:153], v[166:169], v[54:57]
	v_mfma_f32_16x16x32_bf16 v[50:53], v[158:161], v[166:169], v[50:53]
	v_mfma_f32_16x16x32_bf16 v[38:41], v[150:153], v[174:177], v[38:41]
	v_mfma_f32_16x16x32_bf16 v[34:37], v[158:161], v[174:177], v[34:37]
	v_mfma_f32_16x16x32_bf16 v[22:25], v[150:153], v[182:185], v[22:25]
	v_mfma_f32_16x16x32_bf16 v[18:21], v[158:161], v[182:185], v[18:21]
	v_mfma_f32_16x16x32_bf16 v[6:9], v[150:153], v[214:217], v[6:9]
	v_mfma_f32_16x16x32_bf16 v[2:5], v[158:161], v[214:217], v[2:5]
	s_barrier
	s_add_i32 s76, s76, 2
	s_add_u32 s74, s74, 0x100
	s_addc_u32 s75, s75, 0
	s_cmpk_gt_u32 s76, 0x55
	s_mov_b64 s[18:19], s[20:21]
	s_cbranch_scc0 .LBB0_759

;     __host__ __device__ bool next(int i, Unit& u) const { const bool ok = StaticOrder::next(i, u); u.lm = 0; u.ln = 0; return ok; }
; #define PG8_STAGE(bufoff, gbase, voff) do { _Pragma("unroll") for (int _i = 0; _i < 2; ++_i) \
;         __builtin_amdgcn_global_load_lds((const unsigned*)((const char*)(gbase) + (voff)[_i]), (PG8_LAS unsigned*)(lds + (bufoff) + ldsw + _i * 8192), 16, 0, 0); } while (0)
; #define PG8_BAR __builtin_amdgcn_s_barrier()
; template <class Epi, class Sched, bool ALIGN_EPI = false, bool SP2 = false>
; __device__ __forceinline__ void gemm_phase(PG8_LAS unsigned char* lds, const Gemm g, const Sched& S, const Epi& E, const int wave_id) {
;     ...
;         const bool has_next = S.next(ui + 1, nxt);
;         const char* nA = has_next ? (const char*)g.A + (size_t)nxt.lm * tstep : cA; const char* nB = has_next ? (const char*)g.Bt + (size_t)nxt.ln * tstep : cB;
; #pragma unroll 1
;         for (int t = 0; t < nt; t += 2) {
;             const bool last = (t == nt - 2);
;             const char* a1 = cA + (size_t)(t + 1) * kstep;
;             const char* a2 = last ? nA : cA + (size_t)(t + 2) * kstep; const char* b2 = last ? nB : cB + (size_t)(t + 2) * kstep;
;             const char* a3 = a2 + kstep; const char* b3 = b2 + kstep;
;             if (last && has_next) S.a_ready(nxt);
;             if constexpr (SP2) {
;             PG8_LDB(B0, 0, 0); PG8_LDB(B1, 0, 1); PG8_SCHED; PG8_LDA(At, 0, 0); PG8_STAGE(PG8_SA(1, 1), a1 + hstep, voffA);
;             PG8_WAIT_V(8); PG8_WAIT_L(0); PG8_BAR; PG8_MMA(0, 0, At, B0); PG8_MMA(0, 1, At, B1); PG8_BAR; PG8_SCHED;
;             PG8_LDA(At, 0, 1); PG8_STAGE(PG8_SB(0, 0), b2, voffB); PG8_STAGE(PG8_SB(0, 1), b2 + hstep, voffB); PG8_STAGE(PG8_SA(0, 0), a2, voffA);
;             PG8_WAIT_V(8); PG8_WAIT_L(0); PG8_BAR; PG8_MMA(1, 0, At, B0); PG8_MMA(1, 1, At, B1); PG8_BAR; PG8_SCHED;
;             PG8_LDB(B0, 1, 0); PG8_LDB(B1, 1, 1); PG8_SCHED; PG8_LDA(At, 1, 0); PG8_STAGE(PG8_SA(0, 1), a2 + hstep, voffA);
;             PG8_WAIT_V(8); PG8_WAIT_L(0); PG8_BAR; PG8_MMA(0, 0, At, B0); PG8_MMA(0, 1, At, B1); PG8_BAR; PG8_SCHED;
;             PG8_LDA(At, 1, 1); PG8_STAGE(PG8_SB(1, 0), b3, voffB); PG8_STAGE(PG8_SB(1, 1), b3 + hstep, voffB); PG8_STAGE(PG8_SA(1, 0), a3, voffA);
;             PG8_WAIT_V(8); PG8_WAIT_L(0); PG8_BAR; PG8_MMA(1, 0, At, B0); PG8_MMA(1, 1, At, B1); PG8_BAR; PG8_SCHED;
.LBB0_903:
	s_ashr_i32 s21, s20, 31
	s_lshl_b64 s[42:43], s[20:21], 20
	s_add_u32 s42, s8, s42
	s_addc_u32 s43, s9, s43
	s_and_b64 s[44:45], s[40:41], exec
	s_cselect_b32 s21, s43, s47
	s_cselect_b32 s49, s42, s46
	s_ashr_i32 s19, s18, 31
	s_lshl_b64 s[44:45], s[18:19], 20
	s_add_u32 s44, s65, s44
	s_addc_u32 s45, s68, s45
	s_and_b64 s[80:81], s[40:41], exec
	s_cselect_b32 s19, s45, s53
	s_cselect_b32 s79, s44, s52
	s_add_u32 s46, s46, 0x80080
	s_addc_u32 s47, s47, 0
	s_add_u32 s80, s52, 0x100
	s_addc_u32 s81, s53, 0
	s_mov_b32 s84, -2
	v_add_u32_e32 v226, 0x10000, v237
	s_cmp_eq_u64 s[16:17], 0
	s_cbranch_scc0 .Lprio_g5
	s_setprio 1
.Lprio_g5:
	s_add_u32 s52, s46, 0xfff80080
	s_addc_u32 s53, s47, -1
	s_add_i32 s85, 0, 0x10000
	s_cmp_eq_u32 s84, 28
	s_cselect_b32 s83, s21, s53
	s_cselect_b32 s82, s49, s52
	s_cselect_b32 s53, s19, s81
	s_cselect_b32 s52, s79, s80
	s_add_i32 s92, 0, 0x14000
	s_add_i32 m0, s70, 0xc000
	s_nop 0
	global_load_lds_dwordx4 v214, s[46:47]
	ds_read_b128 v[114:117], v226
	ds_read_b128 v[118:121], v226 offset:1024
	ds_read_b128 v[130:133], v226 offset:2048
	ds_read_b128 v[134:137], v226 offset:3072
	ds_read_b128 v[138:141], v226 offset:16384
	ds_read_b128 v[142:145], v226 offset:17408
	ds_read_b128 v[146:149], v226 offset:18432
	ds_read_b128 v[150:153], v226 offset:19456
	s_add_i32 m0, s70, 0xe000
	s_nop 0
	global_load_lds_dwordx4 v216, s[46:47]
	ds_read_b128 v[162:165], v244
	ds_read_b128 v[166:169], v244 offset:1024
	ds_read_b128 v[170:173], v244 offset:2048
	ds_read_b128 v[174:177], v244 offset:3072
	ds_read_b128 v[178:181], v244 offset:4096
	ds_read_b128 v[182:185], v244 offset:5120
	ds_read_b128 v[186:189], v244 offset:6144
	ds_read_b128 v[190:193], v244 offset:7168
	s_waitcnt lgkmcnt(0)
	v_mfma_f32_16x16x32_bf16 v[158:161], v[114:117], v[162:165], 0
	v_mfma_f32_16x16x32_bf16 v[154:157], v[130:133], v[162:165], 0
	v_mfma_f32_16x16x32_bf16 v[110:113], v[114:117], v[170:173], 0
	v_mfma_f32_16x16x32_bf16 v[106:109], v[130:133], v[170:173], 0
	s_waitcnt vmcnt(8)
	s_barrier
	v_mfma_f32_16x16x32_bf16 v[94:97], v[114:117], v[178:181], 0
	v_mfma_f32_16x16x32_bf16 v[90:93], v[130:133], v[178:181], 0
	v_mfma_f32_16x16x32_bf16 v[78:81], v[114:117], v[186:189], 0
	v_mfma_f32_16x16x32_bf16 v[74:77], v[130:133], v[186:189], 0
	v_mfma_f32_16x16x32_bf16 v[158:161], v[118:121], v[166:169], v[158:161]
	v_mfma_f32_16x16x32_bf16 v[154:157], v[134:137], v[166:169], v[154:157]
	v_mfma_f32_16x16x32_bf16 v[110:113], v[118:121], v[174:177], v[110:113]
	v_mfma_f32_16x16x32_bf16 v[106:109], v[134:137], v[174:177], v[106:109]
	v_mfma_f32_16x16x32_bf16 v[94:97], v[118:121], v[182:185], v[94:97]
	v_mfma_f32_16x16x32_bf16 v[90:93], v[134:137], v[182:185], v[90:93]
	v_mfma_f32_16x16x32_bf16 v[78:81], v[118:121], v[190:193], v[78:81]
	v_mfma_f32_16x16x32_bf16 v[74:77], v[134:137], v[190:193], v[74:77]
	v_mfma_f32_16x16x32_bf16 v[126:129], v[138:141], v[162:165], 0
	v_mfma_f32_16x16x32_bf16 v[122:125], v[146:149], v[162:165], 0
	v_mfma_f32_16x16x32_bf16 v[102:105], v[138:141], v[170:173], 0
	v_mfma_f32_16x16x32_bf16 v[98:101], v[146:149], v[170:173], 0
	v_mfma_f32_16x16x32_bf16 v[86:89], v[138:141], v[178:181], 0
	v_mfma_f32_16x16x32_bf16 v[82:85], v[146:149], v[178:181], 0
	v_mfma_f32_16x16x32_bf16 v[70:73], v[138:141], v[186:189], 0
	v_mfma_f32_16x16x32_bf16 v[66:69], v[146:149], v[186:189], 0
	v_mfma_f32_16x16x32_bf16 v[126:129], v[142:145], v[166:169], v[126:129]
	v_mfma_f32_16x16x32_bf16 v[122:125], v[150:153], v[166:169], v[122:125]
	v_mfma_f32_16x16x32_bf16 v[102:105], v[142:145], v[174:177], v[102:105]
	v_mfma_f32_16x16x32_bf16 v[98:101], v[150:153], v[174:177], v[98:101]
	v_mfma_f32_16x16x32_bf16 v[86:89], v[142:145], v[182:185], v[86:89]
	v_mfma_f32_16x16x32_bf16 v[82:85], v[150:153], v[182:185], v[82:85]
	v_mfma_f32_16x16x32_bf16 v[70:73], v[142:145], v[190:193], v[70:73]
	v_mfma_f32_16x16x32_bf16 v[66:69], v[150:153], v[190:193], v[66:69]
	s_barrier
	s_add_i32 s85, s85, s69
	s_mov_b32 m0, s85
	s_nop 0
	global_load_lds_dwordx4 v208, s[52:53]
	ds_read_b128 v[162:165], v244 offset:16384
	ds_read_b128 v[166:169], v244 offset:17408
	s_add_i32 m0, s85, 0x2000
	s_add_u32 s88, s52, 0x80000
	s_addc_u32 s89, s53, 0
	s_add_i32 s85, s92, s69
	global_load_lds_dwordx4 v212, s[52:53]
	ds_read_b128 v[170:173], v244 offset:18432
	ds_read_b128 v[174:177], v244 offset:19456
	s_mov_b32 m0, s85
	s_nop 0
	global_load_lds_dwordx4 v208, s[88:89]
	ds_read_b128 v[178:181], v244 offset:20480
	ds_read_b128 v[182:185], v244 offset:21504
	s_add_i32 m0, s85, 0x2000
	s_nop 0
	global_load_lds_dwordx4 v212, s[88:89]
	ds_read_b128 v[186:189], v244 offset:22528
	ds_read_b128 v[190:193], v244 offset:23552
	s_mov_b32 m0, s70
	s_nop 0
	global_load_lds_dwordx4 v206, s[82:83]
	s_mov_b32 m0, s71
	s_nop 0
	global_load_lds_dwordx4 v210, s[82:83]
	s_waitcnt lgkmcnt(0)
	v_mfma_f32_16x16x32_bf16 v[62:65], v[114:117], v[162:165], 0
	v_mfma_f32_16x16x32_bf16 v[58:61], v[130:133], v[162:165], 0
	v_mfma_f32_16x16x32_bf16 v[46:49], v[114:117], v[170:173], 0
	v_mfma_f32_16x16x32_bf16 v[42:45], v[130:133], v[170:173], 0
	s_waitcnt vmcnt(8)
	s_barrier
; #define PG8_STAGE(bufoff, gbase, voff) do { _Pragma("unroll") for (int _i = 0; _i < 2; ++_i) \
;         __builtin_amdgcn_global_load_lds((const unsigned*)((const char*)(gbase) + (voff)[_i]), (PG8_LAS unsigned*)(lds + (bufoff) + ldsw + _i * 8192), 16, 0, 0); } while (0)
; #define PG8_LDA(dst, b, h) do { _Pragma("unroll") for (int m = 0; m < 4; ++m) _Pragma("unroll") for (int k = 0; k < 2; ++k) dst[m][k] = *(const PG8_LAS bf16x8*)(lds + PG8_SA(b, h) + aoff + m * 2048 + k * 1024); } while (0)
; #define PG8_LDB(dst, b, h) do { _Pragma("unroll") for (int n = 0; n < 2; ++n) _Pragma("unroll") for (int k = 0; k < 2; ++k) dst[n][k] = *(const PG8_LAS bf16x8*)(lds + PG8_SB(b, h) + boff + n * 2048 + k * 1024); } while (0)
; #define PG8_MMA(ai, bj, At, Bt) do { __builtin_amdgcn_s_setprio(1); _Pragma("unroll") for (int m = 0; m < 4; ++m) _Pragma("unroll") for (int n = 0; n < 2; ++n) _Pragma("unroll") for (int k = 0; k < 2; ++k) \
;         acc[ai][bj][m][n] = __builtin_amdgcn_mfma_f32_16x16x32_bf16(Bt[n][k], At[m][k], acc[ai][bj][m][n], 0, 0, 0); __builtin_amdgcn_s_setprio(0); } while (0)
; #define PG8_BAR __builtin_amdgcn_s_barrier()
; template <class Epi, class Sched, bool ALIGN_EPI = false, bool SP2 = false>
; __device__ __forceinline__ void gemm_phase(PG8_LAS unsigned char* lds, const Gemm g, const Sched& S, const Epi& E, const int wave_id) {
;     ...
;             PG8_LDB(B0, 0, 0); PG8_LDB(B1, 0, 1); PG8_SCHED; PG8_LDA(At, 0, 0); PG8_STAGE(PG8_SA(1, 1), a1 + hstep, voffA);
;             PG8_WAIT_V(8); PG8_WAIT_L(0); PG8_BAR; PG8_MMA(0, 0, At, B0); PG8_MMA(0, 1, At, B1); PG8_BAR; PG8_SCHED;
;             PG8_LDA(At, 0, 1); PG8_STAGE(PG8_SB(0, 0), b2, voffB); PG8_STAGE(PG8_SB(0, 1), b2 + hstep, voffB); PG8_STAGE(PG8_SA(0, 0), a2, voffA);
;             PG8_WAIT_V(8); PG8_WAIT_L(0); PG8_BAR; PG8_MMA(1, 0, At, B0); PG8_MMA(1, 1, At, B1); PG8_BAR; PG8_SCHED;
;             PG8_LDB(B0, 1, 0); PG8_LDB(B1, 1, 1); PG8_SCHED; PG8_LDA(At, 1, 0); PG8_STAGE(PG8_SA(0, 1), a2 + hstep, voffA);
;             PG8_WAIT_V(8); PG8_WAIT_L(0); PG8_BAR; PG8_MMA(0, 0, At, B0); PG8_MMA(0, 1, At, B1); PG8_BAR; PG8_SCHED;
;             PG8_LDA(At, 1, 1); PG8_STAGE(PG8_SB(1, 0), b3, voffB); PG8_STAGE(PG8_SB(1, 1), b3 + hstep, voffB); PG8_STAGE(PG8_SA(1, 0), a3, voffA);
;             PG8_WAIT_V(8); PG8_WAIT_L(0); PG8_BAR; PG8_MMA(1, 0, At, B0); PG8_MMA(1, 1, At, B1); PG8_BAR; PG8_SCHED;
	v_mfma_f32_16x16x32_bf16 v[30:33], v[114:117], v[178:181], 0
	v_mfma_f32_16x16x32_bf16 v[26:29], v[130:133], v[178:181], 0
	v_mfma_f32_16x16x32_bf16 v[14:17], v[114:117], v[186:189], 0
	v_mfma_f32_16x16x32_bf16 v[10:13], v[130:133], v[186:189], 0
	v_mfma_f32_16x16x32_bf16 v[62:65], v[118:121], v[166:169], v[62:65]
	v_mfma_f32_16x16x32_bf16 v[58:61], v[134:137], v[166:169], v[58:61]
	v_mfma_f32_16x16x32_bf16 v[46:49], v[118:121], v[174:177], v[46:49]
	v_mfma_f32_16x16x32_bf16 v[42:45], v[134:137], v[174:177], v[42:45]
	v_mfma_f32_16x16x32_bf16 v[30:33], v[118:121], v[182:185], v[30:33]
	v_mfma_f32_16x16x32_bf16 v[26:29], v[134:137], v[182:185], v[26:29]
	v_mfma_f32_16x16x32_bf16 v[14:17], v[118:121], v[190:193], v[14:17]
	v_mfma_f32_16x16x32_bf16 v[10:13], v[134:137], v[190:193], v[10:13]
	v_mfma_f32_16x16x32_bf16 v[54:57], v[138:141], v[162:165], 0
	v_mfma_f32_16x16x32_bf16 v[50:53], v[146:149], v[162:165], 0
	v_mfma_f32_16x16x32_bf16 v[38:41], v[138:141], v[170:173], 0
	v_mfma_f32_16x16x32_bf16 v[34:37], v[146:149], v[170:173], 0
	v_mfma_f32_16x16x32_bf16 v[22:25], v[138:141], v[178:181], 0
	v_mfma_f32_16x16x32_bf16 v[18:21], v[146:149], v[178:181], 0
	v_mfma_f32_16x16x32_bf16 v[6:9], v[138:141], v[186:189], 0
	v_mfma_f32_16x16x32_bf16 v[2:5], v[146:149], v[186:189], 0
	v_mfma_f32_16x16x32_bf16 v[54:57], v[142:145], v[166:169], v[54:57]
	v_mfma_f32_16x16x32_bf16 v[50:53], v[150:153], v[166:169], v[50:53]
	v_mfma_f32_16x16x32_bf16 v[38:41], v[142:145], v[174:177], v[38:41]
	v_mfma_f32_16x16x32_bf16 v[34:37], v[150:153], v[174:177], v[34:37]
	v_mfma_f32_16x16x32_bf16 v[22:25], v[142:145], v[182:185], v[22:25]
	v_mfma_f32_16x16x32_bf16 v[18:21], v[150:153], v[182:185], v[18:21]
	v_mfma_f32_16x16x32_bf16 v[6:9], v[142:145], v[190:193], v[6:9]
	v_mfma_f32_16x16x32_bf16 v[2:5], v[150:153], v[190:193], v[2:5]
	s_barrier
	s_add_i32 s85, 0, 0x18000
	s_add_i32 s88, 0, 0x1c000
	s_add_u32 s82, s82, 0x80000
	s_addc_u32 s83, s83, 0
	s_mov_b32 m0, s72
	s_nop 0
	global_load_lds_dwordx4 v206, s[82:83]
	ds_read_b128 v[114:117], v226 offset:32768
	ds_read_b128 v[118:121], v226 offset:33792
	ds_read_b128 v[130:133], v226 offset:34816
	ds_read_b128 v[134:137], v226 offset:35840
	ds_read_b128 v[138:141], v226 offset:49152
	ds_read_b128 v[142:145], v226 offset:50176
	ds_read_b128 v[146:149], v226 offset:51200
	ds_read_b128 v[150:153], v226 offset:52224
	s_mov_b32 m0, s73
	s_nop 0
	global_load_lds_dwordx4 v210, s[82:83]
	ds_read_b128 v[162:165], v244 offset:32768
	ds_read_b128 v[166:169], v244 offset:33792
	ds_read_b128 v[170:173], v244 offset:34816
	ds_read_b128 v[174:177], v244 offset:35840
	ds_read_b128 v[178:181], v244 offset:36864
	ds_read_b128 v[182:185], v244 offset:37888
	ds_read_b128 v[186:189], v244 offset:38912
	ds_read_b128 v[190:193], v244 offset:39936
	s_waitcnt lgkmcnt(0)
	v_mfma_f32_16x16x32_bf16 v[158:161], v[114:117], v[162:165], v[158:161]
	v_mfma_f32_16x16x32_bf16 v[154:157], v[130:133], v[162:165], v[154:157]
	v_mfma_f32_16x16x32_bf16 v[110:113], v[114:117], v[170:173], v[110:113]
	v_mfma_f32_16x16x32_bf16 v[106:109], v[130:133], v[170:173], v[106:109]
	s_waitcnt vmcnt(8)
	s_barrier
	v_mfma_f32_16x16x32_bf16 v[94:97], v[114:117], v[178:181], v[94:97]
	v_mfma_f32_16x16x32_bf16 v[90:93], v[130:133], v[178:181], v[90:93]
	v_mfma_f32_16x16x32_bf16 v[78:81], v[114:117], v[186:189], v[78:81]
	v_mfma_f32_16x16x32_bf16 v[74:77], v[130:133], v[186:189], v[74:77]
	v_mfma_f32_16x16x32_bf16 v[158:161], v[118:121], v[166:169], v[158:161]
	v_mfma_f32_16x16x32_bf16 v[154:157], v[134:137], v[166:169], v[154:157]
	v_mfma_f32_16x16x32_bf16 v[110:113], v[118:121], v[174:177], v[110:113]
	v_mfma_f32_16x16x32_bf16 v[106:109], v[134:137], v[174:177], v[106:109]
	v_mfma_f32_16x16x32_bf16 v[94:97], v[118:121], v[182:185], v[94:97]
	v_mfma_f32_16x16x32_bf16 v[90:93], v[134:137], v[182:185], v[90:93]
	v_mfma_f32_16x16x32_bf16 v[78:81], v[118:121], v[190:193], v[78:81]
	v_mfma_f32_16x16x32_bf16 v[74:77], v[134:137], v[190:193], v[74:77]
	v_mfma_f32_16x16x32_bf16 v[126:129], v[138:141], v[162:165], v[126:129]
	v_mfma_f32_16x16x32_bf16 v[122:125], v[146:149], v[162:165], v[122:125]
	v_mfma_f32_16x16x32_bf16 v[102:105], v[138:141], v[170:173], v[102:105]
	v_mfma_f32_16x16x32_bf16 v[98:101], v[146:149], v[170:173], v[98:101]
	v_mfma_f32_16x16x32_bf16 v[86:89], v[138:141], v[178:181], v[86:89]
	v_mfma_f32_16x16x32_bf16 v[82:85], v[146:149], v[178:181], v[82:85]
	v_mfma_f32_16x16x32_bf16 v[70:73], v[138:141], v[186:189], v[70:73]
	v_mfma_f32_16x16x32_bf16 v[66:69], v[146:149], v[186:189], v[66:69]
	v_mfma_f32_16x16x32_bf16 v[126:129], v[142:145], v[166:169], v[126:129]
	v_mfma_f32_16x16x32_bf16 v[122:125], v[150:153], v[166:169], v[122:125]
	v_mfma_f32_16x16x32_bf16 v[102:105], v[142:145], v[174:177], v[102:105]
	v_mfma_f32_16x16x32_bf16 v[98:101], v[150:153], v[174:177], v[98:101]
	v_mfma_f32_16x16x32_bf16 v[86:89], v[142:145], v[182:185], v[86:89]
	v_mfma_f32_16x16x32_bf16 v[82:85], v[150:153], v[182:185], v[82:85]
	v_mfma_f32_16x16x32_bf16 v[70:73], v[142:145], v[190:193], v[70:73]
	v_mfma_f32_16x16x32_bf16 v[66:69], v[150:153], v[190:193], v[66:69]
	s_barrier
; #define PG8_STAGE(bufoff, gbase, voff) do { _Pragma("unroll") for (int _i = 0; _i < 2; ++_i) \
;         __builtin_amdgcn_global_load_lds((const unsigned*)((const char*)(gbase) + (voff)[_i]), (PG8_LAS unsigned*)(lds + (bufoff) + ldsw + _i * 8192), 16, 0, 0); } while (0)
; #define PG8_LDA(dst, b, h) do { _Pragma("unroll") for (int m = 0; m < 4; ++m) _Pragma("unroll") for (int k = 0; k < 2; ++k) dst[m][k] = *(const PG8_LAS bf16x8*)(lds + PG8_SA(b, h) + aoff + m * 2048 + k * 1024); } while (0)
; #define PG8_LDB(dst, b, h) do { _Pragma("unroll") for (int n = 0; n < 2; ++n) _Pragma("unroll") for (int k = 0; k < 2; ++k) dst[n][k] = *(const PG8_LAS bf16x8*)(lds + PG8_SB(b, h) + boff + n * 2048 + k * 1024); } while (0)
; #define PG8_MMA(ai, bj, At, Bt) do { __builtin_amdgcn_s_setprio(1); _Pragma("unroll") for (int m = 0; m < 4; ++m) _Pragma("unroll") for (int n = 0; n < 2; ++n) _Pragma("unroll") for (int k = 0; k < 2; ++k) \
;         acc[ai][bj][m][n] = __builtin_amdgcn_mfma_f32_16x16x32_bf16(Bt[n][k], At[m][k], acc[ai][bj][m][n], 0, 0, 0); __builtin_amdgcn_s_setprio(0); } while (0)
; #define PG8_BAR __builtin_amdgcn_s_barrier()
; template <class Epi, class Sched, bool ALIGN_EPI = false, bool SP2 = false>
; __device__ __forceinline__ void gemm_phase(PG8_LAS unsigned char* lds, const Gemm g, const Sched& S, const Epi& E, const int wave_id) {
;     ...
;             PG8_LDB(B0, 0, 0); PG8_LDB(B1, 0, 1); PG8_SCHED; PG8_LDA(At, 0, 0); PG8_STAGE(PG8_SA(1, 1), a1 + hstep, voffA);
;             PG8_WAIT_V(8); PG8_WAIT_L(0); PG8_BAR; PG8_MMA(0, 0, At, B0); PG8_MMA(0, 1, At, B1); PG8_BAR; PG8_SCHED;
;             PG8_LDA(At, 0, 1); PG8_STAGE(PG8_SB(0, 0), b2, voffB); PG8_STAGE(PG8_SB(0, 1), b2 + hstep, voffB); PG8_STAGE(PG8_SA(0, 0), a2, voffA);
;             PG8_WAIT_V(8); PG8_WAIT_L(0); PG8_BAR; PG8_MMA(1, 0, At, B0); PG8_MMA(1, 1, At, B1); PG8_BAR; PG8_SCHED;
;             PG8_LDB(B0, 1, 0); PG8_LDB(B1, 1, 1); PG8_SCHED; PG8_LDA(At, 1, 0); PG8_STAGE(PG8_SA(0, 1), a2 + hstep, voffA);
;             PG8_WAIT_V(8); PG8_WAIT_L(0); PG8_BAR; PG8_MMA(0, 0, At, B0); PG8_MMA(0, 1, At, B1); PG8_BAR; PG8_SCHED;
;             PG8_LDA(At, 1, 1); PG8_STAGE(PG8_SB(1, 0), b3, voffB); PG8_STAGE(PG8_SB(1, 1), b3 + hstep, voffB); PG8_STAGE(PG8_SA(1, 0), a3, voffA);
;             PG8_WAIT_V(8); PG8_WAIT_L(0); PG8_BAR; PG8_MMA(1, 0, At, B0); PG8_MMA(1, 1, At, B1); PG8_BAR; PG8_SCHED;
	s_add_u32 vcc_lo, s82, 0xfff80080
	s_addc_u32 vcc_hi, s83, -1
	s_mov_b32 m0, s76
	s_nop 0
	global_load_lds_dwordx4 v206, vcc
	ds_read_b128 v[162:165], v244 offset:49152
	ds_read_b128 v[166:169], v244 offset:50176
	s_mov_b32 m0, s77
	s_add_i32 s82, s85, s69
	global_load_lds_dwordx4 v210, vcc
	ds_read_b128 v[170:173], v244 offset:51200
	ds_read_b128 v[174:177], v244 offset:52224
	s_add_u32 vcc_lo, s52, 0x80
	s_addc_u32 vcc_hi, s53, 0
	s_mov_b32 m0, s82
	s_nop 0
	global_load_lds_dwordx4 v208, vcc
	ds_read_b128 v[178:181], v244 offset:53248
	ds_read_b128 v[182:185], v244 offset:54272
	s_add_i32 m0, s82, 0x2000
	s_add_u32 s52, s52, 0x80080
	s_addc_u32 s53, s53, 0
	global_load_lds_dwordx4 v212, vcc
	ds_read_b128 v[186:189], v244 offset:55296
	ds_read_b128 v[190:193], v244 offset:56320
	s_add_i32 s82, s88, s69
	s_mov_b32 m0, s82
	s_nop 0
	global_load_lds_dwordx4 v208, s[52:53]
	s_add_i32 m0, s82, 0x2000
	s_nop 0
	global_load_lds_dwordx4 v212, s[52:53]
	s_waitcnt lgkmcnt(0)
	v_mfma_f32_16x16x32_bf16 v[62:65], v[114:117], v[162:165], v[62:65]
	v_mfma_f32_16x16x32_bf16 v[58:61], v[130:133], v[162:165], v[58:61]
	v_mfma_f32_16x16x32_bf16 v[46:49], v[114:117], v[170:173], v[46:49]
	v_mfma_f32_16x16x32_bf16 v[42:45], v[130:133], v[170:173], v[42:45]
	s_waitcnt vmcnt(8)
	s_barrier
	v_mfma_f32_16x16x32_bf16 v[30:33], v[114:117], v[178:181], v[30:33]
	v_mfma_f32_16x16x32_bf16 v[26:29], v[130:133], v[178:181], v[26:29]
	v_mfma_f32_16x16x32_bf16 v[14:17], v[114:117], v[186:189], v[14:17]
	v_mfma_f32_16x16x32_bf16 v[10:13], v[130:133], v[186:189], v[10:13]
	v_mfma_f32_16x16x32_bf16 v[62:65], v[118:121], v[166:169], v[62:65]
	v_mfma_f32_16x16x32_bf16 v[58:61], v[134:137], v[166:169], v[58:61]
	v_mfma_f32_16x16x32_bf16 v[46:49], v[118:121], v[174:177], v[46:49]
	v_mfma_f32_16x16x32_bf16 v[42:45], v[134:137], v[174:177], v[42:45]
	v_mfma_f32_16x16x32_bf16 v[30:33], v[118:121], v[182:185], v[30:33]
	v_mfma_f32_16x16x32_bf16 v[26:29], v[134:137], v[182:185], v[26:29]
	v_mfma_f32_16x16x32_bf16 v[14:17], v[118:121], v[190:193], v[14:17]
	v_mfma_f32_16x16x32_bf16 v[10:13], v[134:137], v[190:193], v[10:13]
	v_mfma_f32_16x16x32_bf16 v[54:57], v[138:141], v[162:165], v[54:57]
	v_mfma_f32_16x16x32_bf16 v[50:53], v[146:149], v[162:165], v[50:53]
	v_mfma_f32_16x16x32_bf16 v[38:41], v[138:141], v[170:173], v[38:41]
	v_mfma_f32_16x16x32_bf16 v[34:37], v[146:149], v[170:173], v[34:37]
	v_mfma_f32_16x16x32_bf16 v[22:25], v[138:141], v[178:181], v[22:25]
	v_mfma_f32_16x16x32_bf16 v[18:21], v[146:149], v[178:181], v[18:21]
	v_mfma_f32_16x16x32_bf16 v[6:9], v[138:141], v[186:189], v[6:9]
	v_mfma_f32_16x16x32_bf16 v[2:5], v[146:149], v[186:189], v[2:5]
	v_mfma_f32_16x16x32_bf16 v[54:57], v[142:145], v[166:169], v[54:57]
	v_mfma_f32_16x16x32_bf16 v[50:53], v[150:153], v[166:169], v[50:53]
	v_mfma_f32_16x16x32_bf16 v[38:41], v[142:145], v[174:177], v[38:41]
	v_mfma_f32_16x16x32_bf16 v[34:37], v[150:153], v[174:177], v[34:37]
	v_mfma_f32_16x16x32_bf16 v[22:25], v[142:145], v[182:185], v[22:25]
	v_mfma_f32_16x16x32_bf16 v[18:21], v[150:153], v[182:185], v[18:21]
	v_mfma_f32_16x16x32_bf16 v[6:9], v[142:145], v[190:193], v[6:9]
	v_mfma_f32_16x16x32_bf16 v[2:5], v[150:153], v[190:193], v[2:5]
	s_barrier
	s_add_i32 s84, s84, 2
	s_add_u32 s46, s46, 0x100
	s_addc_u32 s47, s47, 0
	s_add_u32 s80, s80, 0x100
	s_addc_u32 s81, s81, 0
	s_cmp_gt_u32 s84, 29
	s_cbranch_scc1 .Lpeel_exit_g5
.LBB0_904:
	s_add_u32 s52, s46, 0xfff80080
	s_addc_u32 s53, s47, -1
	s_add_i32 s85, 0, 0x10000
	s_cmp_eq_u32 s84, 28
	s_cselect_b32 s83, s21, s53
	s_cselect_b32 s82, s49, s52
	s_cselect_b32 s53, s19, s81
	s_cselect_b32 s52, s79, s80
	s_add_i32 s92, 0, 0x14000
	s_add_i32 m0, s70, 0xc000
	s_nop 0
	global_load_lds_dwordx4 v214, s[46:47]
	ds_read_b128 v[114:117], v226
	ds_read_b128 v[118:121], v226 offset:1024
	ds_read_b128 v[130:133], v226 offset:2048
	ds_read_b128 v[134:137], v226 offset:3072
	ds_read_b128 v[138:141], v226 offset:16384
	ds_read_b128 v[142:145], v226 offset:17408
	ds_read_b128 v[146:149], v226 offset:18432
	ds_read_b128 v[150:153], v226 offset:19456
	s_add_i32 m0, s70, 0xe000
	s_nop 0
	global_load_lds_dwordx4 v216, s[46:47]
	ds_read_b128 v[162:165], v244
	ds_read_b128 v[166:169], v244 offset:1024
	ds_read_b128 v[170:173], v244 offset:2048
	ds_read_b128 v[174:177], v244 offset:3072
	ds_read_b128 v[178:181], v244 offset:4096
	ds_read_b128 v[182:185], v244 offset:5120
	ds_read_b128 v[186:189], v244 offset:6144
	ds_read_b128 v[190:193], v244 offset:7168
	s_waitcnt lgkmcnt(0)
	v_mfma_f32_16x16x32_bf16 v[158:161], v[114:117], v[162:165], v[158:161]
	v_mfma_f32_16x16x32_bf16 v[154:157], v[130:133], v[162:165], v[154:157]
	v_mfma_f32_16x16x32_bf16 v[110:113], v[114:117], v[170:173], v[110:113]
	v_mfma_f32_16x16x32_bf16 v[106:109], v[130:133], v[170:173], v[106:109]
	s_waitcnt vmcnt(8)
	s_barrier
; #define PG8_STAGE(bufoff, gbase, voff) do { _Pragma("unroll") for (int _i = 0; _i < 2; ++_i) \
;         __builtin_amdgcn_global_load_lds((const unsigned*)((const char*)(gbase) + (voff)[_i]), (PG8_LAS unsigned*)(lds + (bufoff) + ldsw + _i * 8192), 16, 0, 0); } while (0)
; #define PG8_LDA(dst, b, h) do { _Pragma("unroll") for (int m = 0; m < 4; ++m) _Pragma("unroll") for (int k = 0; k < 2; ++k) dst[m][k] = *(const PG8_LAS bf16x8*)(lds + PG8_SA(b, h) + aoff + m * 2048 + k * 1024); } while (0)
; #define PG8_LDB(dst, b, h) do { _Pragma("unroll") for (int n = 0; n < 2; ++n) _Pragma("unroll") for (int k = 0; k < 2; ++k) dst[n][k] = *(const PG8_LAS bf16x8*)(lds + PG8_SB(b, h) + boff + n * 2048 + k * 1024); } while (0)
; #define PG8_MMA(ai, bj, At, Bt) do { __builtin_amdgcn_s_setprio(1); _Pragma("unroll") for (int m = 0; m < 4; ++m) _Pragma("unroll") for (int n = 0; n < 2; ++n) _Pragma("unroll") for (int k = 0; k < 2; ++k) \
;         acc[ai][bj][m][n] = __builtin_amdgcn_mfma_f32_16x16x32_bf16(Bt[n][k], At[m][k], acc[ai][bj][m][n], 0, 0, 0); __builtin_amdgcn_s_setprio(0); } while (0)
; #define PG8_BAR __builtin_amdgcn_s_barrier()
; template <class Epi, class Sched, bool ALIGN_EPI = false, bool SP2 = false>
; __device__ __forceinline__ void gemm_phase(PG8_LAS unsigned char* lds, const Gemm g, const Sched& S, const Epi& E, const int wave_id) {
;     ...
;             PG8_LDB(B0, 0, 0); PG8_LDB(B1, 0, 1); PG8_SCHED; PG8_LDA(At, 0, 0); PG8_STAGE(PG8_SA(1, 1), a1 + hstep, voffA);
;             PG8_WAIT_V(8); PG8_WAIT_L(0); PG8_BAR; PG8_MMA(0, 0, At, B0); PG8_MMA(0, 1, At, B1); PG8_BAR; PG8_SCHED;
;             PG8_LDA(At, 0, 1); PG8_STAGE(PG8_SB(0, 0), b2, voffB); PG8_STAGE(PG8_SB(0, 1), b2 + hstep, voffB); PG8_STAGE(PG8_SA(0, 0), a2, voffA);
;             PG8_WAIT_V(8); PG8_WAIT_L(0); PG8_BAR; PG8_MMA(1, 0, At, B0); PG8_MMA(1, 1, At, B1); PG8_BAR; PG8_SCHED;
;             PG8_LDB(B0, 1, 0); PG8_LDB(B1, 1, 1); PG8_SCHED; PG8_LDA(At, 1, 0); PG8_STAGE(PG8_SA(0, 1), a2 + hstep, voffA);
;             PG8_WAIT_V(8); PG8_WAIT_L(0); PG8_BAR; PG8_MMA(0, 0, At, B0); PG8_MMA(0, 1, At, B1); PG8_BAR; PG8_SCHED;
;             PG8_LDA(At, 1, 1); PG8_STAGE(PG8_SB(1, 0), b3, voffB); PG8_STAGE(PG8_SB(1, 1), b3 + hstep, voffB); PG8_STAGE(PG8_SA(1, 0), a3, voffA);
;             PG8_WAIT_V(8); PG8_WAIT_L(0); PG8_BAR; PG8_MMA(1, 0, At, B0); PG8_MMA(1, 1, At, B1); PG8_BAR; PG8_SCHED;
	v_mfma_f32_16x16x32_bf16 v[94:97], v[114:117], v[178:181], v[94:97]
	v_mfma_f32_16x16x32_bf16 v[90:93], v[130:133], v[178:181], v[90:93]
	v_mfma_f32_16x16x32_bf16 v[78:81], v[114:117], v[186:189], v[78:81]
	v_mfma_f32_16x16x32_bf16 v[74:77], v[130:133], v[186:189], v[74:77]
	v_mfma_f32_16x16x32_bf16 v[158:161], v[118:121], v[166:169], v[158:161]
	v_mfma_f32_16x16x32_bf16 v[154:157], v[134:137], v[166:169], v[154:157]
	v_mfma_f32_16x16x32_bf16 v[110:113], v[118:121], v[174:177], v[110:113]
	v_mfma_f32_16x16x32_bf16 v[106:109], v[134:137], v[174:177], v[106:109]
	v_mfma_f32_16x16x32_bf16 v[94:97], v[118:121], v[182:185], v[94:97]
	v_mfma_f32_16x16x32_bf16 v[90:93], v[134:137], v[182:185], v[90:93]
	v_mfma_f32_16x16x32_bf16 v[78:81], v[118:121], v[190:193], v[78:81]
	v_mfma_f32_16x16x32_bf16 v[74:77], v[134:137], v[190:193], v[74:77]
	v_mfma_f32_16x16x32_bf16 v[126:129], v[138:141], v[162:165], v[126:129]
	v_mfma_f32_16x16x32_bf16 v[122:125], v[146:149], v[162:165], v[122:125]
	v_mfma_f32_16x16x32_bf16 v[102:105], v[138:141], v[170:173], v[102:105]
	v_mfma_f32_16x16x32_bf16 v[98:101], v[146:149], v[170:173], v[98:101]
	v_mfma_f32_16x16x32_bf16 v[86:89], v[138:141], v[178:181], v[86:89]
	v_mfma_f32_16x16x32_bf16 v[82:85], v[146:149], v[178:181], v[82:85]
	v_mfma_f32_16x16x32_bf16 v[70:73], v[138:141], v[186:189], v[70:73]
	v_mfma_f32_16x16x32_bf16 v[66:69], v[146:149], v[186:189], v[66:69]
	v_mfma_f32_16x16x32_bf16 v[126:129], v[142:145], v[166:169], v[126:129]
	v_mfma_f32_16x16x32_bf16 v[122:125], v[150:153], v[166:169], v[122:125]
	v_mfma_f32_16x16x32_bf16 v[102:105], v[142:145], v[174:177], v[102:105]
	v_mfma_f32_16x16x32_bf16 v[98:101], v[150:153], v[174:177], v[98:101]
	v_mfma_f32_16x16x32_bf16 v[86:89], v[142:145], v[182:185], v[86:89]
	v_mfma_f32_16x16x32_bf16 v[82:85], v[150:153], v[182:185], v[82:85]
	v_mfma_f32_16x16x32_bf16 v[70:73], v[142:145], v[190:193], v[70:73]
	v_mfma_f32_16x16x32_bf16 v[66:69], v[150:153], v[190:193], v[66:69]
	s_barrier
	s_add_i32 s85, s85, s69
	s_mov_b32 m0, s85
	s_nop 0
	global_load_lds_dwordx4 v208, s[52:53]
	ds_read_b128 v[162:165], v244 offset:16384
	ds_read_b128 v[166:169], v244 offset:17408
	s_add_i32 m0, s85, 0x2000
	s_add_u32 s88, s52, 0x80000
	s_addc_u32 s89, s53, 0
	s_add_i32 s85, s92, s69
	global_load_lds_dwordx4 v212, s[52:53]
	ds_read_b128 v[170:173], v244 offset:18432
	ds_read_b128 v[174:177], v244 offset:19456
	s_mov_b32 m0, s85
	s_nop 0
	global_load_lds_dwordx4 v208, s[88:89]
	ds_read_b128 v[178:181], v244 offset:20480
	ds_read_b128 v[182:185], v244 offset:21504
	s_add_i32 m0, s85, 0x2000
	s_nop 0
	global_load_lds_dwordx4 v212, s[88:89]
	ds_read_b128 v[186:189], v244 offset:22528
	ds_read_b128 v[190:193], v244 offset:23552
	s_mov_b32 m0, s70
	s_nop 0
	global_load_lds_dwordx4 v206, s[82:83]
	s_mov_b32 m0, s71
	s_nop 0
	global_load_lds_dwordx4 v210, s[82:83]
	s_waitcnt lgkmcnt(0)
	v_mfma_f32_16x16x32_bf16 v[62:65], v[114:117], v[162:165], v[62:65]
	v_mfma_f32_16x16x32_bf16 v[58:61], v[130:133], v[162:165], v[58:61]
	v_mfma_f32_16x16x32_bf16 v[46:49], v[114:117], v[170:173], v[46:49]
	v_mfma_f32_16x16x32_bf16 v[42:45], v[130:133], v[170:173], v[42:45]
	s_waitcnt vmcnt(8)
	s_barrier
	v_mfma_f32_16x16x32_bf16 v[30:33], v[114:117], v[178:181], v[30:33]
	v_mfma_f32_16x16x32_bf16 v[26:29], v[130:133], v[178:181], v[26:29]
	v_mfma_f32_16x16x32_bf16 v[14:17], v[114:117], v[186:189], v[14:17]
	v_mfma_f32_16x16x32_bf16 v[10:13], v[130:133], v[186:189], v[10:13]
	v_mfma_f32_16x16x32_bf16 v[62:65], v[118:121], v[166:169], v[62:65]
	v_mfma_f32_16x16x32_bf16 v[58:61], v[134:137], v[166:169], v[58:61]
	v_mfma_f32_16x16x32_bf16 v[46:49], v[118:121], v[174:177], v[46:49]
	v_mfma_f32_16x16x32_bf16 v[42:45], v[134:137], v[174:177], v[42:45]
	v_mfma_f32_16x16x32_bf16 v[30:33], v[118:121], v[182:185], v[30:33]
	v_mfma_f32_16x16x32_bf16 v[26:29], v[134:137], v[182:185], v[26:29]
	v_mfma_f32_16x16x32_bf16 v[14:17], v[118:121], v[190:193], v[14:17]
	v_mfma_f32_16x16x32_bf16 v[10:13], v[134:137], v[190:193], v[10:13]
	v_mfma_f32_16x16x32_bf16 v[54:57], v[138:141], v[162:165], v[54:57]
	v_mfma_f32_16x16x32_bf16 v[50:53], v[146:149], v[162:165], v[50:53]
	v_mfma_f32_16x16x32_bf16 v[38:41], v[138:141], v[170:173], v[38:41]
	v_mfma_f32_16x16x32_bf16 v[34:37], v[146:149], v[170:173], v[34:37]
	v_mfma_f32_16x16x32_bf16 v[22:25], v[138:141], v[178:181], v[22:25]
	v_mfma_f32_16x16x32_bf16 v[18:21], v[146:149], v[178:181], v[18:21]
	v_mfma_f32_16x16x32_bf16 v[6:9], v[138:141], v[186:189], v[6:9]
	v_mfma_f32_16x16x32_bf16 v[2:5], v[146:149], v[186:189], v[2:5]
	v_mfma_f32_16x16x32_bf16 v[54:57], v[142:145], v[166:169], v[54:57]
	v_mfma_f32_16x16x32_bf16 v[50:53], v[150:153], v[166:169], v[50:53]
	v_mfma_f32_16x16x32_bf16 v[38:41], v[142:145], v[174:177], v[38:41]
	v_mfma_f32_16x16x32_bf16 v[34:37], v[150:153], v[174:177], v[34:37]
	v_mfma_f32_16x16x32_bf16 v[22:25], v[142:145], v[182:185], v[22:25]
	v_mfma_f32_16x16x32_bf16 v[18:21], v[150:153], v[182:185], v[18:21]
	v_mfma_f32_16x16x32_bf16 v[6:9], v[142:145], v[190:193], v[6:9]
	v_mfma_f32_16x16x32_bf16 v[2:5], v[150:153], v[190:193], v[2:5]
	s_barrier
; #define PG8_STAGE(bufoff, gbase, voff) do { _Pragma("unroll") for (int _i = 0; _i < 2; ++_i) \
;         __builtin_amdgcn_global_load_lds((const unsigned*)((const char*)(gbase) + (voff)[_i]), (PG8_LAS unsigned*)(lds + (bufoff) + ldsw + _i * 8192), 16, 0, 0); } while (0)
; #define PG8_LDA(dst, b, h) do { _Pragma("unroll") for (int m = 0; m < 4; ++m) _Pragma("unroll") for (int k = 0; k < 2; ++k) dst[m][k] = *(const PG8_LAS bf16x8*)(lds + PG8_SA(b, h) + aoff + m * 2048 + k * 1024); } while (0)
; #define PG8_WAIT_V(n) asm volatile("s_waitcnt vmcnt(" #n ")" ::: "memory")
; #define PG8_WAIT_L(n) asm volatile("s_waitcnt lgkmcnt(" #n ")" ::: "memory")
; #define PG8_BAR __builtin_amdgcn_s_barrier()
; template <class Epi, class Sched, bool ALIGN_EPI = false, bool SP2 = false>
; __device__ __forceinline__ void gemm_phase(PG8_LAS unsigned char* lds, const Gemm g, const Sched& S, const Epi& E, const int wave_id) {
;     ...
;         for (int t = 0; t < nt; t += 2) {
;             const bool last = (t == nt - 2);
;             const char* a1 = cA + (size_t)(t + 1) * kstep;
;             const char* a2 = last ? nA : cA + (size_t)(t + 2) * kstep; const char* b2 = last ? nB : cB + (size_t)(t + 2) * kstep;
;             const char* a3 = a2 + kstep; const char* b3 = b2 + kstep;
;             if (last && has_next) S.a_ready(nxt);
;             if constexpr (SP2) {
;             PG8_LDB(B0, 0, 0); PG8_LDB(B1, 0, 1); PG8_SCHED; PG8_LDA(At, 0, 0); PG8_STAGE(PG8_SA(1, 1), a1 + hstep, voffA);
;             PG8_WAIT_V(8); PG8_WAIT_L(0); PG8_BAR; PG8_MMA(0, 0, At, B0); PG8_MMA(0, 1, At, B1); PG8_BAR; PG8_SCHED;
;             PG8_LDA(At, 0, 1); PG8_STAGE(PG8_SB(0, 0), b2, voffB); PG8_STAGE(PG8_SB(0, 1), b2 + hstep, voffB); PG8_STAGE(PG8_SA(0, 0), a2, voffA);
;             PG8_WAIT_V(8); PG8_WAIT_L(0); PG8_BAR; PG8_MMA(1, 0, At, B0); PG8_MMA(1, 1, At, B1); PG8_BAR; PG8_SCHED;
;             PG8_LDB(B0, 1, 0); PG8_LDB(B1, 1, 1); PG8_SCHED; PG8_LDA(At, 1, 0); PG8_STAGE(PG8_SA(0, 1), a2 + hstep, voffA);
;             PG8_WAIT_V(8); PG8_WAIT_L(0); PG8_BAR; PG8_MMA(0, 0, At, B0); PG8_MMA(0, 1, At, B1); PG8_BAR; PG8_SCHED;
;             PG8_LDA(At, 1, 1); PG8_STAGE(PG8_SB(1, 0), b3, voffB); PG8_STAGE(PG8_SB(1, 1), b3 + hstep, voffB); PG8_STAGE(PG8_SA(1, 0), a3, voffA);
;             PG8_WAIT_V(8); PG8_WAIT_L(0); PG8_BAR; PG8_MMA(1, 0, At, B0); PG8_MMA(1, 1, At, B1); PG8_BAR; PG8_SCHED;
	s_add_i32 s85, 0, 0x18000
	s_add_i32 s88, 0, 0x1c000
	s_add_u32 s82, s82, 0x80000
	s_addc_u32 s83, s83, 0
	s_mov_b32 m0, s72
	s_nop 0
	global_load_lds_dwordx4 v206, s[82:83]
	ds_read_b128 v[114:117], v226 offset:32768
	ds_read_b128 v[118:121], v226 offset:33792
	ds_read_b128 v[130:133], v226 offset:34816
	ds_read_b128 v[134:137], v226 offset:35840
	ds_read_b128 v[138:141], v226 offset:49152
	ds_read_b128 v[142:145], v226 offset:50176
	ds_read_b128 v[146:149], v226 offset:51200
	ds_read_b128 v[150:153], v226 offset:52224
	s_mov_b32 m0, s73
	s_nop 0
	global_load_lds_dwordx4 v210, s[82:83]
	ds_read_b128 v[162:165], v244 offset:32768
	ds_read_b128 v[166:169], v244 offset:33792
	ds_read_b128 v[170:173], v244 offset:34816
	ds_read_b128 v[174:177], v244 offset:35840
	ds_read_b128 v[178:181], v244 offset:36864
	ds_read_b128 v[182:185], v244 offset:37888
	ds_read_b128 v[186:189], v244 offset:38912
	ds_read_b128 v[190:193], v244 offset:39936
	s_waitcnt lgkmcnt(0)
	v_mfma_f32_16x16x32_bf16 v[158:161], v[114:117], v[162:165], v[158:161]
	v_mfma_f32_16x16x32_bf16 v[154:157], v[130:133], v[162:165], v[154:157]
	v_mfma_f32_16x16x32_bf16 v[110:113], v[114:117], v[170:173], v[110:113]
	v_mfma_f32_16x16x32_bf16 v[106:109], v[130:133], v[170:173], v[106:109]
	s_waitcnt vmcnt(8)
	s_barrier
	v_mfma_f32_16x16x32_bf16 v[94:97], v[114:117], v[178:181], v[94:97]
	v_mfma_f32_16x16x32_bf16 v[90:93], v[130:133], v[178:181], v[90:93]
	v_mfma_f32_16x16x32_bf16 v[78:81], v[114:117], v[186:189], v[78:81]
	v_mfma_f32_16x16x32_bf16 v[74:77], v[130:133], v[186:189], v[74:77]
	v_mfma_f32_16x16x32_bf16 v[158:161], v[118:121], v[166:169], v[158:161]
	v_mfma_f32_16x16x32_bf16 v[154:157], v[134:137], v[166:169], v[154:157]
	v_mfma_f32_16x16x32_bf16 v[110:113], v[118:121], v[174:177], v[110:113]
	v_mfma_f32_16x16x32_bf16 v[106:109], v[134:137], v[174:177], v[106:109]
	v_mfma_f32_16x16x32_bf16 v[94:97], v[118:121], v[182:185], v[94:97]
	v_mfma_f32_16x16x32_bf16 v[90:93], v[134:137], v[182:185], v[90:93]
	v_mfma_f32_16x16x32_bf16 v[78:81], v[118:121], v[190:193], v[78:81]
	v_mfma_f32_16x16x32_bf16 v[74:77], v[134:137], v[190:193], v[74:77]
	v_mfma_f32_16x16x32_bf16 v[126:129], v[138:141], v[162:165], v[126:129]
	v_mfma_f32_16x16x32_bf16 v[122:125], v[146:149], v[162:165], v[122:125]
	v_mfma_f32_16x16x32_bf16 v[102:105], v[138:141], v[170:173], v[102:105]
	v_mfma_f32_16x16x32_bf16 v[98:101], v[146:149], v[170:173], v[98:101]
	v_mfma_f32_16x16x32_bf16 v[86:89], v[138:141], v[178:181], v[86:89]
	v_mfma_f32_16x16x32_bf16 v[82:85], v[146:149], v[178:181], v[82:85]
	v_mfma_f32_16x16x32_bf16 v[70:73], v[138:141], v[186:189], v[70:73]
	v_mfma_f32_16x16x32_bf16 v[66:69], v[146:149], v[186:189], v[66:69]
	v_mfma_f32_16x16x32_bf16 v[126:129], v[142:145], v[166:169], v[126:129]
	v_mfma_f32_16x16x32_bf16 v[122:125], v[150:153], v[166:169], v[122:125]
	v_mfma_f32_16x16x32_bf16 v[102:105], v[142:145], v[174:177], v[102:105]
	v_mfma_f32_16x16x32_bf16 v[98:101], v[150:153], v[174:177], v[98:101]
	v_mfma_f32_16x16x32_bf16 v[86:89], v[142:145], v[182:185], v[86:89]
	v_mfma_f32_16x16x32_bf16 v[82:85], v[150:153], v[182:185], v[82:85]
	v_mfma_f32_16x16x32_bf16 v[70:73], v[142:145], v[190:193], v[70:73]
	v_mfma_f32_16x16x32_bf16 v[66:69], v[150:153], v[190:193], v[66:69]
	s_barrier
	s_add_u32 vcc_lo, s82, 0xfff80080
	s_addc_u32 vcc_hi, s83, -1
	s_mov_b32 m0, s76
	s_nop 0
	global_load_lds_dwordx4 v206, vcc
	ds_read_b128 v[162:165], v244 offset:49152
	ds_read_b128 v[166:169], v244 offset:50176
	s_mov_b32 m0, s77
	s_add_i32 s82, s85, s69
	global_load_lds_dwordx4 v210, vcc
	ds_read_b128 v[170:173], v244 offset:51200
	ds_read_b128 v[174:177], v244 offset:52224
	s_add_u32 vcc_lo, s52, 0x80
	s_addc_u32 vcc_hi, s53, 0
	s_mov_b32 m0, s82
	s_nop 0
	global_load_lds_dwordx4 v208, vcc
	ds_read_b128 v[178:181], v244 offset:53248
	ds_read_b128 v[182:185], v244 offset:54272
	s_add_i32 m0, s82, 0x2000
	s_add_u32 s52, s52, 0x80080
	s_addc_u32 s53, s53, 0
	global_load_lds_dwordx4 v212, vcc
	ds_read_b128 v[186:189], v244 offset:55296
	ds_read_b128 v[190:193], v244 offset:56320
	s_add_i32 s82, s88, s69
	s_mov_b32 m0, s82
	s_nop 0
	global_load_lds_dwordx4 v208, s[52:53]
	s_add_i32 m0, s82, 0x2000
	s_nop 0
	global_load_lds_dwordx4 v212, s[52:53]
	s_waitcnt lgkmcnt(0)
	v_mfma_f32_16x16x32_bf16 v[62:65], v[114:117], v[162:165], v[62:65]
	v_mfma_f32_16x16x32_bf16 v[58:61], v[130:133], v[162:165], v[58:61]
	v_mfma_f32_16x16x32_bf16 v[46:49], v[114:117], v[170:173], v[46:49]
	v_mfma_f32_16x16x32_bf16 v[42:45], v[130:133], v[170:173], v[42:45]
	s_waitcnt vmcnt(8)
	s_barrier
	v_mfma_f32_16x16x32_bf16 v[30:33], v[114:117], v[178:181], v[30:33]
	v_mfma_f32_16x16x32_bf16 v[26:29], v[130:133], v[178:181], v[26:29]
	v_mfma_f32_16x16x32_bf16 v[14:17], v[114:117], v[186:189], v[14:17]
	v_mfma_f32_16x16x32_bf16 v[10:13], v[130:133], v[186:189], v[10:13]
	v_mfma_f32_16x16x32_bf16 v[62:65], v[118:121], v[166:169], v[62:65]
	v_mfma_f32_16x16x32_bf16 v[58:61], v[134:137], v[166:169], v[58:61]
	v_mfma_f32_16x16x32_bf16 v[46:49], v[118:121], v[174:177], v[46:49]
	v_mfma_f32_16x16x32_bf16 v[42:45], v[134:137], v[174:177], v[42:45]
	v_mfma_f32_16x16x32_bf16 v[30:33], v[118:121], v[182:185], v[30:33]
	v_mfma_f32_16x16x32_bf16 v[26:29], v[134:137], v[182:185], v[26:29]
	v_mfma_f32_16x16x32_bf16 v[14:17], v[118:121], v[190:193], v[14:17]
	v_mfma_f32_16x16x32_bf16 v[10:13], v[134:137], v[190:193], v[10:13]
	v_mfma_f32_16x16x32_bf16 v[54:57], v[138:141], v[162:165], v[54:57]
	v_mfma_f32_16x16x32_bf16 v[50:53], v[146:149], v[162:165], v[50:53]
	v_mfma_f32_16x16x32_bf16 v[38:41], v[138:141], v[170:173], v[38:41]
	v_mfma_f32_16x16x32_bf16 v[34:37], v[146:149], v[170:173], v[34:37]
	v_mfma_f32_16x16x32_bf16 v[22:25], v[138:141], v[178:181], v[22:25]
	v_mfma_f32_16x16x32_bf16 v[18:21], v[146:149], v[178:181], v[18:21]
	v_mfma_f32_16x16x32_bf16 v[6:9], v[138:141], v[186:189], v[6:9]
	v_mfma_f32_16x16x32_bf16 v[2:5], v[146:149], v[186:189], v[2:5]
	v_mfma_f32_16x16x32_bf16 v[54:57], v[142:145], v[166:169], v[54:57]
	v_mfma_f32_16x16x32_bf16 v[50:53], v[150:153], v[166:169], v[50:53]
	v_mfma_f32_16x16x32_bf16 v[38:41], v[142:145], v[174:177], v[38:41]
	v_mfma_f32_16x16x32_bf16 v[34:37], v[150:153], v[174:177], v[34:37]
	v_mfma_f32_16x16x32_bf16 v[22:25], v[142:145], v[182:185], v[22:25]
	v_mfma_f32_16x16x32_bf16 v[18:21], v[150:153], v[182:185], v[18:21]
	v_mfma_f32_16x16x32_bf16 v[6:9], v[142:145], v[190:193], v[6:9]
	v_mfma_f32_16x16x32_bf16 v[2:5], v[150:153], v[190:193], v[2:5]
	s_barrier
	s_add_i32 s84, s84, 2
	s_add_u32 s46, s46, 0x100
	s_addc_u32 s47, s47, 0
	s_add_u32 s80, s80, 0x100
	s_addc_u32 s81, s81, 0
	s_cmp_gt_u32 s84, 29
	s_cbranch_scc0 .LBB0_904
.Lpeel_exit_g5:
	s_setprio 0
	s_and_b64 vcc, exec, s[16:17]
	s_mov_b32 s50, 0x90000
	s_mov_b32 s51, 0xa0000
	s_mov_b32 s82, 0xb0000
	s_cbranch_vccz .LBB0_907
	s_barrier
